# FFN1 epilogue sigmoid: 1+2^g via one v_pk_add_f32 per register pair (24 of 32 pairs), exps write the reciprocal pair directly
# speedup vs baseline: 1.0075x; 1.0034x over previous
; #define LAS __attribute__((address_space(3)))
; __device__ __forceinline__ float sigmoidf_(float x) { return __builtin_amdgcn_rcpf(1.0f + __expf(-x)); }
;     __device__ __forceinline__ void operator()(AccRef acc, const Unit& u, int wr, int wc, int fr, int fq) const {
;     ...
;                 f32x4 h2v = (f32x4){0.f, 0.f, 0.f, 0.f}, h3v = h2v, h2g = h2v, h3g = h2v;
;                 const int pb = ai * 2 + wr - 1;
;                 if (pb >= 0 && fr == 0) { const LAS float* xp = xch + (pb * 2) * 256 + clb + 4 * n;
;                     h2v = *(const LAS f32x4*)(xp); h3v = *(const LAS f32x4*)(xp + 256); h2g = *(const LAS f32x4*)(xp + 128); h3g = *(const LAS f32x4*)(xp + 256 + 128); }
;                 float o[4][4];
; #pragma unroll
;                 for (int j = 0; j < 4; ++j) {
;                     const float v0 = acc[ai][0][0][n][j], v1 = acc[ai][0][1][n][j], v2 = acc[ai][0][2][n][j], v3 = acc[ai][0][3][n][j];
;                     const float g0 = acc[ai][1][0][n][j], g1 = acc[ai][1][1][n][j], g2 = acc[ai][1][2][n][j], g3 = acc[ai][1][3][n][j];
;                     const float pv3 = dpp_upd<0x111>(h3v[j], v3), pv2 = dpp_upd<0x111>(h2v[j], v2), pg3 = dpp_upd<0x111>(h3g[j], g3), pg2 = dpp_upd<0x111>(h2g[j], g2);
;                     const float hv0 = bvv[j] + w2v[j] * v0 + w1v[j] * pv3 + w0v[j] * pv2, hv1 = bvv[j] + w2v[j] * v1 + w1v[j] * v0 + w0v[j] * pv3;
;                     const float hv2 = bvv[j] + w2v[j] * v2 + w1v[j] * v1 + w0v[j] * v0, hv3 = bvv[j] + w2v[j] * v3 + w1v[j] * v2 + w0v[j] * v1;
;                     const float hg0 = bvg[j] + w2g[j] * g0 + w1g[j] * pg3 + w0g[j] * pg2, hg1 = bvg[j] + w2g[j] * g1 + w1g[j] * g0 + w0g[j] * pg3;
;                     const float hg2 = bvg[j] + w2g[j] * g2 + w1g[j] * g1 + w0g[j] * g0, hg3 = bvg[j] + w2g[j] * g3 + w1g[j] * g2 + w0g[j] * g1;
;                     o[0][j] = hg0 * sigmoidf_(hg0) * hv0; o[1][j] = hg1 * sigmoidf_(hg1) * hv1; o[2][j] = hg2 * sigmoidf_(hg2) * hv2; o[3][j] = hg3 * sigmoidf_(hg3) * hv3; }
; #pragma unroll
;                 for (int m = 0; m < 4; ++m) { u32x2 w; w.x = cvt_pk_bf16(o[m][0], o[m][1]); w.y = cvt_pk_bf16(o[m][2], o[m][3]);
;                     *(u32x2*)(Aout + (size_t)(row0 + ai * 128 + m) * FH + hc0 + 4 * n) = w; } } }
.LBB0_305:
	s_or_b64 exec, exec, s[34:35]
	s_waitcnt lgkmcnt(0)
	v_mov_b32_dpp v64, v8 row_shr:1 row_mask:0xf bank_mask:0xf
	v_mov_b32_dpp v65, v9 row_shr:1 row_mask:0xf bank_mask:0xf
	v_pk_fma_f32 v[44:45], v[24:25], v[120:121], v[124:125]
	v_mov_b32_dpp v40, v0 row_shr:1 row_mask:0xf bank_mask:0xf
	v_mov_b32_dpp v41, v1 row_shr:1 row_mask:0xf bank_mask:0xf
	v_pk_fma_f32 v[44:45], v[116:117], v[64:65], v[44:45]
	v_mov_b32_dpp v32, v20 row_shr:1 row_mask:0xf bank_mask:0xf
	v_pk_fma_f32 v[40:41], v[112:113], v[40:41], v[44:45]
	v_mov_b32_dpp v33, v21 row_shr:1 row_mask:0xf bank_mask:0xf
	v_exp_f32_e32 v44, v40
	v_exp_f32_e32 v45, v41
	v_pk_fma_f32 v[46:47], v[28:29], v[104:105], v[108:109]
	v_mov_b32_dpp v36, v12 row_shr:1 row_mask:0xf bank_mask:0xf
	v_pk_add_f32 v[44:45], v[44:45], 1.0 op_sel_hi:[1,0]
	v_rcp_f32_e32 v44, v44
	v_rcp_f32_e32 v45, v45
	v_mov_b32_dpp v37, v13 row_shr:1 row_mask:0xf bank_mask:0xf
	v_pk_fma_f32 v[46:47], v[100:101], v[32:33], v[46:47]
	v_mov_b32_dpp v66, v10 row_shr:1 row_mask:0xf bank_mask:0xf
	v_pk_fma_f32 v[36:37], v[96:97], v[36:37], v[46:47]
	v_pk_mul_f32 v[40:41], v[40:41], v[44:45]
	v_mov_b32_dpp v67, v11 row_shr:1 row_mask:0xf bank_mask:0xf
	v_pk_mul_f32 v[36:37], v[36:37], v[40:41]
	v_pk_fma_f32 v[40:41], v[26:27], v[122:123], v[126:127]
	v_mov_b32_dpp v42, v2 row_shr:1 row_mask:0xf bank_mask:0xf
	v_mov_b32_dpp v43, v3 row_shr:1 row_mask:0xf bank_mask:0xf
	v_pk_fma_f32 v[40:41], v[118:119], v[66:67], v[40:41]
	v_cvt_pk_bf16_f32 v36, v36, v37
	v_pk_fma_f32 v[40:41], v[114:115], v[42:43], v[40:41]
	v_mov_b32_dpp v34, v22 row_shr:1 row_mask:0xf bank_mask:0xf
	v_exp_f32_e32 v42, v40
	v_exp_f32_e32 v43, v41
	v_mov_b32_dpp v35, v23 row_shr:1 row_mask:0xf bank_mask:0xf
	v_pk_add_f32 v[42:43], v[42:43], 1.0 op_sel_hi:[1,0]
	v_rcp_f32_e32 v42, v42
	v_rcp_f32_e32 v43, v43
	v_pk_fma_f32 v[44:45], v[30:31], v[106:107], v[110:111]
	v_mov_b32_dpp v38, v14 row_shr:1 row_mask:0xf bank_mask:0xf
	v_mov_b32_dpp v39, v15 row_shr:1 row_mask:0xf bank_mask:0xf
	v_pk_fma_f32 v[44:45], v[102:103], v[34:35], v[44:45]
	v_pk_mul_f32 v[40:41], v[40:41], v[42:43]
	v_pk_fma_f32 v[38:39], v[98:99], v[38:39], v[44:45]
	v_pk_fma_f32 v[8:9], v[8:9], v[120:121], v[124:125]
	v_pk_mul_f32 v[38:39], v[38:39], v[40:41]
	v_pk_fma_f32 v[20:21], v[20:21], v[104:105], v[108:109]
	v_cvt_pk_bf16_f32 v37, v38, v39
	v_pk_fma_f32 v[38:39], v[4:5], v[120:121], v[124:125]
	v_mov_b32_e32 v146, v36
	v_mov_b32_e32 v147, v37
	global_store_dwordx4 v[132:133], v[144:147], off
	v_pk_fma_f32 v[38:39], v[24:25], v[116:117], v[38:39]
	s_and_b64 vcc, exec, s[12:13]
	v_pk_fma_f32 v[38:39], v[112:113], v[64:65], v[38:39]
	s_mov_b32 s35, s24
	v_exp_f32_e32 v36, v38
	v_exp_f32_e32 v37, v39
	s_mov_b32 s34, s26
	s_mov_b64 s[38:39], s[30:31]
	v_pk_add_f32 v[36:37], v[36:37], 1.0 op_sel_hi:[1,0]
	v_rcp_f32_e32 v36, v36
	v_rcp_f32_e32 v37, v37
	v_pk_fma_f32 v[40:41], v[16:17], v[104:105], v[108:109]
	s_mov_b64 s[36:37], s[28:29]
	v_pk_fma_f32 v[40:41], v[28:29], v[100:101], v[40:41]
	v_pk_mul_f32 v[36:37], v[38:39], v[36:37]
	v_pk_fma_f32 v[32:33], v[96:97], v[32:33], v[40:41]
	v_pk_fma_f32 v[40:41], v[18:19], v[106:107], v[110:111]
	v_pk_mul_f32 v[32:33], v[32:33], v[36:37]
	v_pk_fma_f32 v[36:37], v[6:7], v[122:123], v[126:127]
	v_cvt_pk_bf16_f32 v32, v32, v33
	v_pk_fma_f32 v[36:37], v[26:27], v[118:119], v[36:37]
	v_pk_fma_f32 v[40:41], v[30:31], v[102:103], v[40:41]
	v_pk_fma_f32 v[36:37], v[114:115], v[66:67], v[36:37]
	v_pk_fma_f32 v[34:35], v[98:99], v[34:35], v[40:41]
	v_exp_f32_e32 v38, v36
	v_exp_f32_e32 v39, v37
	s_nop 0
	v_pk_add_f32 v[38:39], v[38:39], 1.0 op_sel_hi:[1,0]
	v_rcp_f32_e32 v38, v38
	v_rcp_f32_e32 v39, v39
	s_nop 0
	v_pk_mul_f32 v[36:37], v[36:37], v[38:39]
	s_nop 0
	v_pk_mul_f32 v[34:35], v[34:35], v[36:37]
	s_nop 0
	v_cvt_pk_bf16_f32 v33, v34, v35
	v_pk_fma_f32 v[34:35], v[0:1], v[120:121], v[124:125]
	v_mov_b32_e32 v156, v32
	v_mov_b32_e32 v157, v33
	global_store_dwordx4 v[128:129], v[154:157], off
	v_pk_fma_f32 v[34:35], v[4:5], v[116:117], v[34:35]
	v_pk_fma_f32 v[0:1], v[0:1], v[116:117], v[8:9]
	v_pk_fma_f32 v[24:25], v[24:25], v[112:113], v[34:35]
	v_pk_fma_f32 v[0:1], v[4:5], v[112:113], v[0:1]
	v_exp_f32_e32 v32, v24
	v_exp_f32_e32 v33, v25
	v_exp_f32_e32 v8, v0
	v_pk_add_f32 v[32:33], v[32:33], 1.0 op_sel_hi:[1,0]
	v_rcp_f32_e32 v32, v32
	v_rcp_f32_e32 v33, v33
	v_pk_fma_f32 v[34:35], v[12:13], v[104:105], v[108:109]
	v_pk_fma_f32 v[4:5], v[10:11], v[122:123], v[126:127]
	v_pk_fma_f32 v[34:35], v[16:17], v[100:101], v[34:35]
	v_pk_mul_f32 v[24:25], v[24:25], v[32:33]
	v_pk_fma_f32 v[28:29], v[28:29], v[96:97], v[34:35]
	v_pk_mul_f32 v[24:25], v[28:29], v[24:25]
	v_pk_fma_f32 v[28:29], v[2:3], v[122:123], v[126:127]
	v_pk_fma_f32 v[2:3], v[2:3], v[118:119], v[4:5]
	v_pk_fma_f32 v[28:29], v[6:7], v[118:119], v[28:29]
	v_pk_fma_f32 v[2:3], v[6:7], v[114:115], v[2:3]
	v_pk_fma_f32 v[26:27], v[26:27], v[114:115], v[28:29]
	v_exp_f32_e32 v28, v26
	v_exp_f32_e32 v29, v27
	v_exp_f32_e32 v9, v1
	v_exp_f32_e32 v4, v2
	v_exp_f32_e32 v5, v3
	v_cvt_pk_bf16_f32 v24, v24, v25
	v_pk_add_f32 v[28:29], v[28:29], 1.0 op_sel_hi:[1,0]
	v_pk_add_f32 v[8:9], v[8:9], 1.0 op_sel_hi:[1,0]
	v_pk_add_f32 v[4:5], v[4:5], 1.0 op_sel_hi:[1,0]
	v_rcp_f32_e32 v28, v28
	v_rcp_f32_e32 v29, v29
	v_rcp_f32_e32 v8, v8
	v_rcp_f32_e32 v9, v9
	v_rcp_f32_e32 v4, v4
	v_rcp_f32_e32 v5, v5
	v_pk_fma_f32 v[32:33], v[14:15], v[106:107], v[110:111]
	v_pk_fma_f32 v[10:11], v[22:23], v[106:107], v[110:111]
	v_pk_fma_f32 v[32:33], v[18:19], v[102:103], v[32:33]
	v_pk_fma_f32 v[12:13], v[12:13], v[100:101], v[20:21]
	v_pk_fma_f32 v[6:7], v[14:15], v[102:103], v[10:11]
	v_pk_fma_f32 v[30:31], v[30:31], v[98:99], v[32:33]
	v_pk_mul_f32 v[26:27], v[26:27], v[28:29]
	v_pk_fma_f32 v[12:13], v[16:17], v[96:97], v[12:13]
	v_pk_mul_f32 v[0:1], v[0:1], v[8:9]
	v_pk_fma_f32 v[6:7], v[18:19], v[98:99], v[6:7]
	v_pk_mul_f32 v[2:3], v[2:3], v[4:5]
	v_pk_mul_f32 v[26:27], v[30:31], v[26:27]
	v_pk_mul_f32 v[0:1], v[12:13], v[0:1]
	v_pk_mul_f32 v[2:3], v[6:7], v[2:3]
	v_cvt_pk_bf16_f32 v25, v26, v27
	v_cvt_pk_bf16_f32 v0, v0, v1
	v_cvt_pk_bf16_f32 v1, v2, v3
	v_mov_b32_e32 v200, v24
	v_mov_b32_e32 v201, v25
	global_store_dwordx4 v[88:89], v[198:201], off
	v_mov_b32_e32 v150, v0
	v_mov_b32_e32 v151, v1
	global_store_dwordx4 v[82:83], v[148:151], off
	s_cbranch_vccnz .LBB0_324

; #define LAS __attribute__((address_space(3)))
; __device__ __forceinline__ float sigmoidf_(float x) { return __builtin_amdgcn_rcpf(1.0f + __expf(-x)); }
;     __device__ __forceinline__ void operator()(AccRef acc, const Unit& u, int wr, int wc, int fr, int fq) const {
;     ...
;                 f32x4 h2v = (f32x4){0.f, 0.f, 0.f, 0.f}, h3v = h2v, h2g = h2v, h3g = h2v;
;                 const int pb = ai * 2 + wr - 1;
;                 if (pb >= 0 && fr == 0) { const LAS float* xp = xch + (pb * 2) * 256 + clb + 4 * n;
;                     h2v = *(const LAS f32x4*)(xp); h3v = *(const LAS f32x4*)(xp + 256); h2g = *(const LAS f32x4*)(xp + 128); h3g = *(const LAS f32x4*)(xp + 256 + 128); }
;                 float o[4][4];
; #pragma unroll
;                 for (int j = 0; j < 4; ++j) {
;                     const float v0 = acc[ai][0][0][n][j], v1 = acc[ai][0][1][n][j], v2 = acc[ai][0][2][n][j], v3 = acc[ai][0][3][n][j];
;                     const float g0 = acc[ai][1][0][n][j], g1 = acc[ai][1][1][n][j], g2 = acc[ai][1][2][n][j], g3 = acc[ai][1][3][n][j];
;                     const float pv3 = dpp_upd<0x111>(h3v[j], v3), pv2 = dpp_upd<0x111>(h2v[j], v2), pg3 = dpp_upd<0x111>(h3g[j], g3), pg2 = dpp_upd<0x111>(h2g[j], g2);
;                     const float hv0 = bvv[j] + w2v[j] * v0 + w1v[j] * pv3 + w0v[j] * pv2, hv1 = bvv[j] + w2v[j] * v1 + w1v[j] * v0 + w0v[j] * pv3;
;                     const float hv2 = bvv[j] + w2v[j] * v2 + w1v[j] * v1 + w0v[j] * v0, hv3 = bvv[j] + w2v[j] * v3 + w1v[j] * v2 + w0v[j] * v1;
;                     const float hg0 = bvg[j] + w2g[j] * g0 + w1g[j] * pg3 + w0g[j] * pg2, hg1 = bvg[j] + w2g[j] * g1 + w1g[j] * g0 + w0g[j] * pg3;
;                     const float hg2 = bvg[j] + w2g[j] * g2 + w1g[j] * g1 + w0g[j] * g0, hg3 = bvg[j] + w2g[j] * g3 + w1g[j] * g2 + w0g[j] * g1;
;                     o[0][j] = hg0 * sigmoidf_(hg0) * hv0; o[1][j] = hg1 * sigmoidf_(hg1) * hv1; o[2][j] = hg2 * sigmoidf_(hg2) * hv2; o[3][j] = hg3 * sigmoidf_(hg3) * hv3; }
; #pragma unroll
;                 for (int m = 0; m < 4; ++m) { u32x2 w; w.x = cvt_pk_bf16(o[m][0], o[m][1]); w.y = cvt_pk_bf16(o[m][2], o[m][3]);
;                     *(u32x2*)(Aout + (size_t)(row0 + ai * 128 + m) * FH + hc0 + 4 * n) = w; } } }
.LBB0_316:
	s_or_b64 exec, exec, s[40:41]
	v_pk_fma_f32 v[248:249], v[152:153], v[184:185], v[188:189]
	v_mov_b32_dpp v206, v128 row_shr:1 row_mask:0xf bank_mask:0xf
	v_mov_b32_dpp v207, v129 row_shr:1 row_mask:0xf bank_mask:0xf
	v_pk_fma_f32 v[248:249], v[180:181], v[198:199], v[248:249]
	v_mov_b32_dpp v194, v148 row_shr:1 row_mask:0xf bank_mask:0xf
	v_pk_fma_f32 v[206:207], v[176:177], v[206:207], v[248:249]
	v_mov_b32_dpp v195, v149 row_shr:1 row_mask:0xf bank_mask:0xf
	v_exp_f32_e32 v248, v206
	v_exp_f32_e32 v249, v207
	v_pk_fma_f32 v[250:251], v[156:157], v[168:169], v[172:173]
	v_pk_add_f32 v[248:249], v[248:249], 1.0 op_sel_hi:[1,0]
	v_rcp_f32_e32 v248, v248
	v_rcp_f32_e32 v249, v249
	v_mov_b32_dpp v202, v136 row_shr:1 row_mask:0xf bank_mask:0xf
	v_mov_b32_dpp v203, v137 row_shr:1 row_mask:0xf bank_mask:0xf
	v_pk_fma_f32 v[250:251], v[164:165], v[194:195], v[250:251]
	v_pk_mul_f32 v[206:207], v[206:207], v[248:249]
	v_pk_fma_f32 v[202:203], v[160:161], v[202:203], v[250:251]
	v_mov_b32_dpp v200, v142 row_shr:1 row_mask:0xf bank_mask:0xf
	v_mov_b32_dpp v201, v143 row_shr:1 row_mask:0xf bank_mask:0xf
	v_pk_mul_f32 v[202:203], v[202:203], v[206:207]
	v_pk_fma_f32 v[206:207], v[154:155], v[186:187], v[190:191]
	v_mov_b32_dpp v208, v130 row_shr:1 row_mask:0xf bank_mask:0xf
	v_mov_b32_dpp v209, v131 row_shr:1 row_mask:0xf bank_mask:0xf
	v_pk_fma_f32 v[206:207], v[182:183], v[200:201], v[206:207]
	v_mov_b32_dpp v196, v150 row_shr:1 row_mask:0xf bank_mask:0xf
	v_pk_fma_f32 v[206:207], v[178:179], v[208:209], v[206:207]
	v_mov_b32_dpp v197, v151 row_shr:1 row_mask:0xf bank_mask:0xf
	v_exp_f32_e32 v193, v206
	v_exp_f32_e32 v209, v207
	v_cvt_pk_bf16_f32 v208, v202, v203
	v_add_f32_e32 v193, 1.0, v193
	v_rcp_f32_e32 v202, v193
	v_add_f32_e32 v193, 1.0, v209
	v_rcp_f32_e32 v203, v193
	v_pk_fma_f32 v[248:249], v[158:159], v[170:171], v[174:175]
	v_mov_b32_dpp v204, v138 row_shr:1 row_mask:0xf bank_mask:0xf
	v_mov_b32_dpp v205, v139 row_shr:1 row_mask:0xf bank_mask:0xf
	v_pk_fma_f32 v[248:249], v[166:167], v[196:197], v[248:249]
	v_pk_mul_f32 v[202:203], v[206:207], v[202:203]
	v_pk_fma_f32 v[204:205], v[162:163], v[204:205], v[248:249]
	v_lshl_add_u32 v246, s34, 8, v236
	v_pk_mul_f32 v[202:203], v[204:205], v[202:203]
	v_lshlrev_b64 v[204:205], 1, v[232:233]
	v_pk_fma_f32 v[232:233], v[132:133], v[184:185], v[188:189]
	v_mov_b64_e32 v[206:207], s[60:61]
	v_pk_fma_f32 v[232:233], v[152:153], v[180:181], v[232:233]
	v_cvt_pk_bf16_f32 v209, v202, v203
	v_pk_fma_f32 v[198:199], v[176:177], v[198:199], v[232:233]
	v_mad_i64_i32 v[202:203], s[34:35], v246, s74, v[206:207]
	v_exp_f32_e32 v193, v198
	v_exp_f32_e32 v232, v199
	v_lshl_add_u64 v[202:203], v[202:203], 0, v[204:205]
	v_add_f32_e32 v193, 1.0, v193
	v_mov_b32_e32 v247, v208
	v_mov_b32_e32 v248, v209
	v_rcp_f32_e32 v208, v193
	v_add_f32_e32 v193, 1.0, v232
	v_rcp_f32_e32 v209, v193
	v_pk_fma_f32 v[232:233], v[144:145], v[168:169], v[172:173]
	v_pk_fma_f32 v[140:141], v[140:141], v[184:185], v[188:189]
	v_pk_fma_f32 v[232:233], v[156:157], v[164:165], v[232:233]
	v_pk_mul_f32 v[198:199], v[198:199], v[208:209]
	v_pk_fma_f32 v[194:195], v[160:161], v[194:195], v[232:233]
	v_pk_fma_f32 v[208:209], v[146:147], v[170:171], v[174:175]
	v_pk_mul_f32 v[194:195], v[194:195], v[198:199]
	v_pk_fma_f32 v[198:199], v[134:135], v[186:187], v[190:191]
	v_pk_fma_f32 v[208:209], v[158:159], v[166:167], v[208:209]
	v_pk_fma_f32 v[198:199], v[154:155], v[182:183], v[198:199]
	v_pk_fma_f32 v[196:197], v[162:163], v[196:197], v[208:209]
	v_pk_fma_f32 v[198:199], v[178:179], v[200:201], v[198:199]
	v_cvt_pk_bf16_f32 v194, v194, v195
	v_exp_f32_e32 v200, v198
	v_exp_f32_e32 v201, v199
	v_pk_fma_f32 v[148:149], v[148:149], v[168:169], v[172:173]
	v_pk_add_f32 v[200:201], v[200:201], 1.0 op_sel_hi:[1,0]
	v_rcp_f32_e32 v200, v200
	v_rcp_f32_e32 v201, v201
	v_or_b32_e32 v193, 1, v246
	v_pk_mul_f32 v[198:199], v[198:199], v[200:201]
	s_nop 0
	v_pk_mul_f32 v[196:197], v[196:197], v[198:199]
	v_pk_fma_f32 v[198:199], v[128:129], v[184:185], v[188:189]
	v_cvt_pk_bf16_f32 v195, v196, v197
	v_pk_fma_f32 v[198:199], v[132:133], v[180:181], v[198:199]
	v_mad_i64_i32 v[196:197], s[34:35], v193, s74, v[206:207]
	v_pk_fma_f32 v[152:153], v[152:153], v[176:177], v[198:199]
	v_lshl_add_u64 v[196:197], v[196:197], 0, v[204:205]
	v_exp_f32_e32 v193, v152
	v_exp_f32_e32 v198, v153
	v_mov_b32_e32 v249, v194
	v_mov_b32_e32 v250, v195
	v_add_f32_e32 v193, 1.0, v193
	v_rcp_f32_e32 v194, v193
	v_add_f32_e32 v193, 1.0, v198
	v_rcp_f32_e32 v195, v193
	v_pk_fma_f32 v[198:199], v[136:137], v[168:169], v[172:173]
	v_pk_fma_f32 v[128:129], v[128:129], v[180:181], v[140:141]
	v_pk_fma_f32 v[198:199], v[144:145], v[164:165], v[198:199]
	v_pk_fma_f32 v[128:129], v[132:133], v[176:177], v[128:129]
	v_pk_fma_f32 v[156:157], v[156:157], v[160:161], v[198:199]
	v_pk_mul_f32 v[152:153], v[152:153], v[194:195]
	v_pk_mul_f32 v[152:153], v[156:157], v[152:153]
	v_pk_fma_f32 v[156:157], v[130:131], v[186:187], v[190:191]
	v_exp_f32_e32 v140, v128
	v_pk_fma_f32 v[132:133], v[142:143], v[186:187], v[190:191]
	v_pk_fma_f32 v[156:157], v[134:135], v[182:183], v[156:157]
	v_pk_fma_f32 v[130:131], v[130:131], v[182:183], v[132:133]
	v_pk_fma_f32 v[154:155], v[154:155], v[178:179], v[156:157]
	v_pk_fma_f32 v[130:131], v[134:135], v[178:179], v[130:131]
	v_exp_f32_e32 v157, v154
	v_exp_f32_e32 v141, v129
	v_exp_f32_e32 v132, v130
	v_exp_f32_e32 v133, v131
	v_exp_f32_e32 v193, v155
	v_pk_add_f32 v[140:141], v[140:141], 1.0 op_sel_hi:[1,0]
	v_pk_add_f32 v[132:133], v[132:133], 1.0 op_sel_hi:[1,0]
	v_cvt_pk_bf16_f32 v156, v152, v153
	v_add_f32_e32 v152, 1.0, v157
; #define LAS __attribute__((address_space(3)))
; __device__ __forceinline__ float sigmoidf_(float x) { return __builtin_amdgcn_rcpf(1.0f + __expf(-x)); }
;     __device__ __forceinline__ void operator()(AccRef acc, const Unit& u, int wr, int wc, int fr, int fq) const {
;     ...
;                 f32x4 h2v = (f32x4){0.f, 0.f, 0.f, 0.f}, h3v = h2v, h2g = h2v, h3g = h2v;
;                 const int pb = ai * 2 + wr - 1;
;                 if (pb >= 0 && fr == 0) { const LAS float* xp = xch + (pb * 2) * 256 + clb + 4 * n;
;                     h2v = *(const LAS f32x4*)(xp); h3v = *(const LAS f32x4*)(xp + 256); h2g = *(const LAS f32x4*)(xp + 128); h3g = *(const LAS f32x4*)(xp + 256 + 128); }
;                 float o[4][4];
; #pragma unroll
;                 for (int j = 0; j < 4; ++j) {
;                     const float v0 = acc[ai][0][0][n][j], v1 = acc[ai][0][1][n][j], v2 = acc[ai][0][2][n][j], v3 = acc[ai][0][3][n][j];
;                     const float g0 = acc[ai][1][0][n][j], g1 = acc[ai][1][1][n][j], g2 = acc[ai][1][2][n][j], g3 = acc[ai][1][3][n][j];
;                     const float pv3 = dpp_upd<0x111>(h3v[j], v3), pv2 = dpp_upd<0x111>(h2v[j], v2), pg3 = dpp_upd<0x111>(h3g[j], g3), pg2 = dpp_upd<0x111>(h2g[j], g2);
;                     const float hv0 = bvv[j] + w2v[j] * v0 + w1v[j] * pv3 + w0v[j] * pv2, hv1 = bvv[j] + w2v[j] * v1 + w1v[j] * v0 + w0v[j] * pv3;
;                     const float hv2 = bvv[j] + w2v[j] * v2 + w1v[j] * v1 + w0v[j] * v0, hv3 = bvv[j] + w2v[j] * v3 + w1v[j] * v2 + w0v[j] * v1;
;                     const float hg0 = bvg[j] + w2g[j] * g0 + w1g[j] * pg3 + w0g[j] * pg2, hg1 = bvg[j] + w2g[j] * g1 + w1g[j] * g0 + w0g[j] * pg3;
;                     const float hg2 = bvg[j] + w2g[j] * g2 + w1g[j] * g1 + w0g[j] * g0, hg3 = bvg[j] + w2g[j] * g3 + w1g[j] * g2 + w0g[j] * g1;
;                     o[0][j] = hg0 * sigmoidf_(hg0) * hv0; o[1][j] = hg1 * sigmoidf_(hg1) * hv1; o[2][j] = hg2 * sigmoidf_(hg2) * hv2; o[3][j] = hg3 * sigmoidf_(hg3) * hv3; }
; #pragma unroll
;                 for (int m = 0; m < 4; ++m) { u32x2 w; w.x = cvt_pk_bf16(o[m][0], o[m][1]); w.y = cvt_pk_bf16(o[m][2], o[m][3]);
;                     *(u32x2*)(Aout + (size_t)(row0 + ai * 128 + m) * FH + hc0 + 4 * n) = w; } } }
	v_add_f32_e32 v153, 1.0, v193
	v_rcp_f32_e32 v140, v140
	v_rcp_f32_e32 v141, v141
	v_rcp_f32_e32 v132, v132
	v_rcp_f32_e32 v133, v133
	v_rcp_f32_e32 v152, v152
	v_rcp_f32_e32 v153, v153
	v_pk_fma_f32 v[142:143], v[150:151], v[170:171], v[174:175]
	v_pk_fma_f32 v[194:195], v[138:139], v[170:171], v[174:175]
	v_pk_fma_f32 v[136:137], v[136:137], v[164:165], v[148:149]
	v_pk_fma_f32 v[134:135], v[138:139], v[166:167], v[142:143]
	v_pk_fma_f32 v[194:195], v[146:147], v[166:167], v[194:195]
	v_pk_fma_f32 v[136:137], v[144:145], v[160:161], v[136:137]
	v_pk_mul_f32 v[128:129], v[128:129], v[140:141]
	v_pk_fma_f32 v[134:135], v[146:147], v[162:163], v[134:135]
	v_pk_mul_f32 v[130:131], v[130:131], v[132:133]
	v_pk_fma_f32 v[158:159], v[158:159], v[162:163], v[194:195]
	v_pk_mul_f32 v[152:153], v[154:155], v[152:153]
	v_pk_mul_f32 v[128:129], v[136:137], v[128:129]
	v_pk_mul_f32 v[130:131], v[134:135], v[130:131]
	v_pk_mul_f32 v[152:153], v[158:159], v[152:153]
	v_cvt_pk_bf16_f32 v128, v128, v129
	v_cvt_pk_bf16_f32 v129, v130, v131
	v_or_b32_e32 v130, 3, v246
	v_cvt_pk_bf16_f32 v157, v152, v153
	v_or_b32_e32 v152, 2, v246
	v_mad_i64_i32 v[130:131], s[34:35], v130, s74, v[206:207]
	v_mad_i64_i32 v[152:153], s[34:35], v152, s74, v[206:207]
	v_lshl_add_u64 v[140:141], v[130:131], 0, v[204:205]
	v_lshl_add_u64 v[152:153], v[152:153], 0, v[204:205]
	v_mov_b32_e32 v251, v128
	v_mov_b32_e32 v253, v129
	v_mov_b32_e32 v193, 0
	v_mov_b32_e32 v194, 0
	v_mov_b32_e32 v195, 0
	v_mov_b32_e32 v136, 0
	v_mov_b32_e32 v137, 0
	v_mov_b32_e32 v138, 0
	v_mov_b32_e32 v139, 0
	v_mov_b32_e32 v128, 0
	v_mov_b32_e32 v129, 0
	v_mov_b32_e32 v130, 0
	v_mov_b32_e32 v131, 0
	v_mov_b32_e32 v132, 0
	v_mov_b32_e32 v133, 0
	v_mov_b32_e32 v134, 0
	v_mov_b32_e32 v135, 0
	v_mov_b32_e32 v254, v156
	v_mov_b32_e32 v255, v157
	s_and_saveexec_b64 s[34:35], s[22:23]
	s_cbranch_execz .LBB0_320
	ds_read_b128 v[132:135], v237 offset:2048
	ds_read_b128 v[136:139], v237 offset:2560
	ds_read_b128 v[128:131], v237 offset:3072
	ds_read_b128 v[192:195], v237 offset:3584
.LBB0_320:
	s_or_b64 exec, exec, s[34:35]
	s_waitcnt lgkmcnt(0)
	v_mov_b32_dpp v192, v72 row_shr:1 row_mask:0xf bank_mask:0xf
	v_mov_b32_dpp v193, v73 row_shr:1 row_mask:0xf bank_mask:0xf
	v_pk_fma_f32 v[142:143], v[88:89], v[184:185], v[188:189]
	v_mov_b32_dpp v136, v64 row_shr:1 row_mask:0xf bank_mask:0xf
	v_mov_b32_dpp v137, v65 row_shr:1 row_mask:0xf bank_mask:0xf
	v_pk_fma_f32 v[142:143], v[180:181], v[192:193], v[142:143]
	v_mov_b32_dpp v128, v84 row_shr:1 row_mask:0xf bank_mask:0xf
	v_pk_fma_f32 v[136:137], v[176:177], v[136:137], v[142:143]
	v_mov_b32_dpp v129, v85 row_shr:1 row_mask:0xf bank_mask:0xf
	v_exp_f32_e32 v142, v136
	v_exp_f32_e32 v143, v137
	v_pk_fma_f32 v[144:145], v[92:93], v[168:169], v[172:173]
	v_mov_b32_dpp v132, v76 row_shr:1 row_mask:0xf bank_mask:0xf
	v_pk_add_f32 v[142:143], v[142:143], 1.0 op_sel_hi:[1,0]
	v_rcp_f32_e32 v142, v142
	v_rcp_f32_e32 v143, v143
	v_mov_b32_dpp v133, v77 row_shr:1 row_mask:0xf bank_mask:0xf
	v_pk_fma_f32 v[144:145], v[164:165], v[128:129], v[144:145]
	v_mov_b32_dpp v194, v74 row_shr:1 row_mask:0xf bank_mask:0xf
	v_pk_fma_f32 v[132:133], v[160:161], v[132:133], v[144:145]
	v_pk_mul_f32 v[136:137], v[136:137], v[142:143]
	v_mov_b32_dpp v195, v75 row_shr:1 row_mask:0xf bank_mask:0xf
	v_pk_mul_f32 v[132:133], v[132:133], v[136:137]
	v_pk_fma_f32 v[136:137], v[90:91], v[186:187], v[190:191]
	v_mov_b32_dpp v138, v66 row_shr:1 row_mask:0xf bank_mask:0xf
	v_mov_b32_dpp v139, v67 row_shr:1 row_mask:0xf bank_mask:0xf
	v_pk_fma_f32 v[136:137], v[182:183], v[194:195], v[136:137]
	v_mov_b32_dpp v130, v86 row_shr:1 row_mask:0xf bank_mask:0xf
	v_pk_fma_f32 v[136:137], v[178:179], v[138:139], v[136:137]
	v_mov_b32_dpp v131, v87 row_shr:1 row_mask:0xf bank_mask:0xf
	v_exp_f32_e32 v139, v136
	v_exp_f32_e32 v142, v137
	v_cvt_pk_bf16_f32 v138, v132, v133
	v_add_f32_e32 v132, 1.0, v139
	v_rcp_f32_e32 v132, v132
	v_add_f32_e32 v133, 1.0, v142
	v_rcp_f32_e32 v133, v133
	v_pk_fma_f32 v[142:143], v[94:95], v[170:171], v[174:175]
	v_mov_b32_dpp v134, v78 row_shr:1 row_mask:0xf bank_mask:0xf
	v_mov_b32_dpp v135, v79 row_shr:1 row_mask:0xf bank_mask:0xf
	v_pk_mul_f32 v[132:133], v[136:137], v[132:133]
	v_pk_fma_f32 v[136:137], v[68:69], v[184:185], v[188:189]
	v_pk_fma_f32 v[142:143], v[166:167], v[130:131], v[142:143]
	v_pk_fma_f32 v[136:137], v[88:89], v[180:181], v[136:137]
	v_pk_fma_f32 v[134:135], v[162:163], v[134:135], v[142:143]
	v_pk_fma_f32 v[136:137], v[176:177], v[192:193], v[136:137]
	v_add_u32_e32 v146, 0x80, v246
	v_exp_f32_e32 v142, v136
	v_exp_f32_e32 v143, v137
	v_pk_mul_f32 v[132:133], v[134:135], v[132:133]
	v_mov_b64_e32 v[134:135], s[60:61]
	v_cvt_pk_bf16_f32 v139, v132, v133
	v_mad_i64_i32 v[132:133], s[34:35], v146, s74, v[134:135]
	v_lshl_add_u64 v[132:133], v[132:133], 0, v[204:205]
	v_mov_b32_e32 v144, v138
	v_mov_b32_e32 v145, v139
	v_add_f32_e32 v138, 1.0, v142
	v_add_f32_e32 v139, 1.0, v143
	v_rcp_f32_e32 v138, v138
	v_rcp_f32_e32 v139, v139
	v_pk_fma_f32 v[142:143], v[80:81], v[168:169], v[172:173]
	v_pk_fma_f32 v[72:73], v[72:73], v[184:185], v[188:189]
	v_pk_fma_f32 v[142:143], v[92:93], v[164:165], v[142:143]
	v_pk_mul_f32 v[136:137], v[136:137], v[138:139]
	v_pk_fma_f32 v[128:129], v[160:161], v[128:129], v[142:143]
	v_pk_fma_f32 v[84:85], v[84:85], v[168:169], v[172:173]
	v_pk_mul_f32 v[128:129], v[128:129], v[136:137]
	v_pk_fma_f32 v[136:137], v[70:71], v[186:187], v[190:191]
	s_nop 0
	v_pk_fma_f32 v[136:137], v[90:91], v[182:183], v[136:137]
	s_nop 0
	v_pk_fma_f32 v[136:137], v[178:179], v[194:195], v[136:137]
	s_nop 0
	v_exp_f32_e32 v139, v136
	v_exp_f32_e32 v142, v137
; #define LAS __attribute__((address_space(3)))
; __device__ __forceinline__ float sigmoidf_(float x) { return __builtin_amdgcn_rcpf(1.0f + __expf(-x)); }
;     __device__ __forceinline__ void operator()(AccRef acc, const Unit& u, int wr, int wc, int fr, int fq) const {
;     ...
;                 f32x4 h2v = (f32x4){0.f, 0.f, 0.f, 0.f}, h3v = h2v, h2g = h2v, h3g = h2v;
;                 const int pb = ai * 2 + wr - 1;
;                 if (pb >= 0 && fr == 0) { const LAS float* xp = xch + (pb * 2) * 256 + clb + 4 * n;
;                     h2v = *(const LAS f32x4*)(xp); h3v = *(const LAS f32x4*)(xp + 256); h2g = *(const LAS f32x4*)(xp + 128); h3g = *(const LAS f32x4*)(xp + 256 + 128); }
;                 float o[4][4];
; #pragma unroll
;                 for (int j = 0; j < 4; ++j) {
;                     const float v0 = acc[ai][0][0][n][j], v1 = acc[ai][0][1][n][j], v2 = acc[ai][0][2][n][j], v3 = acc[ai][0][3][n][j];
;                     const float g0 = acc[ai][1][0][n][j], g1 = acc[ai][1][1][n][j], g2 = acc[ai][1][2][n][j], g3 = acc[ai][1][3][n][j];
;                     const float pv3 = dpp_upd<0x111>(h3v[j], v3), pv2 = dpp_upd<0x111>(h2v[j], v2), pg3 = dpp_upd<0x111>(h3g[j], g3), pg2 = dpp_upd<0x111>(h2g[j], g2);
;                     const float hv0 = bvv[j] + w2v[j] * v0 + w1v[j] * pv3 + w0v[j] * pv2, hv1 = bvv[j] + w2v[j] * v1 + w1v[j] * v0 + w0v[j] * pv3;
;                     const float hv2 = bvv[j] + w2v[j] * v2 + w1v[j] * v1 + w0v[j] * v0, hv3 = bvv[j] + w2v[j] * v3 + w1v[j] * v2 + w0v[j] * v1;
;                     const float hg0 = bvg[j] + w2g[j] * g0 + w1g[j] * pg3 + w0g[j] * pg2, hg1 = bvg[j] + w2g[j] * g1 + w1g[j] * g0 + w0g[j] * pg3;
;                     const float hg2 = bvg[j] + w2g[j] * g2 + w1g[j] * g1 + w0g[j] * g0, hg3 = bvg[j] + w2g[j] * g3 + w1g[j] * g2 + w0g[j] * g1;
;                     o[0][j] = hg0 * sigmoidf_(hg0) * hv0; o[1][j] = hg1 * sigmoidf_(hg1) * hv1; o[2][j] = hg2 * sigmoidf_(hg2) * hv2; o[3][j] = hg3 * sigmoidf_(hg3) * hv3; }
; #pragma unroll
;                 for (int m = 0; m < 4; ++m) { u32x2 w; w.x = cvt_pk_bf16(o[m][0], o[m][1]); w.y = cvt_pk_bf16(o[m][2], o[m][3]);
;                     *(u32x2*)(Aout + (size_t)(row0 + ai * 128 + m) * FH + hc0 + 4 * n) = w; } } }
	v_cvt_pk_bf16_f32 v138, v128, v129
	v_add_f32_e32 v128, 1.0, v139
	v_rcp_f32_e32 v128, v128
	v_add_f32_e32 v129, 1.0, v142
	v_rcp_f32_e32 v129, v129
	v_pk_fma_f32 v[142:143], v[82:83], v[170:171], v[174:175]
	v_pk_mul_f32 v[128:129], v[136:137], v[128:129]
	v_pk_fma_f32 v[142:143], v[94:95], v[166:167], v[142:143]
	v_pk_fma_f32 v[136:137], v[76:77], v[168:169], v[172:173]
	v_pk_fma_f32 v[130:131], v[162:163], v[130:131], v[142:143]
	v_pk_fma_f32 v[136:137], v[80:81], v[164:165], v[136:137]
	v_pk_mul_f32 v[128:129], v[130:131], v[128:129]
	v_pk_fma_f32 v[130:131], v[64:65], v[184:185], v[188:189]
	v_pk_fma_f32 v[64:65], v[64:65], v[180:181], v[72:73]
	v_pk_fma_f32 v[130:131], v[68:69], v[180:181], v[130:131]
	v_pk_fma_f32 v[64:65], v[68:69], v[176:177], v[64:65]
	v_pk_fma_f32 v[88:89], v[88:89], v[176:177], v[130:131]
	v_pk_fma_f32 v[92:93], v[92:93], v[160:161], v[136:137]
	v_exp_f32_e32 v130, v88
	v_exp_f32_e32 v131, v89
	v_exp_f32_e32 v72, v64
	v_pk_add_f32 v[130:131], v[130:131], 1.0 op_sel_hi:[1,0]
	v_rcp_f32_e32 v130, v130
	v_rcp_f32_e32 v131, v131
	v_pk_fma_f32 v[68:69], v[74:75], v[186:187], v[190:191]
	v_exp_f32_e32 v73, v65
	v_pk_mul_f32 v[88:89], v[88:89], v[130:131]
	v_pk_mul_f32 v[88:89], v[92:93], v[88:89]
	v_pk_fma_f32 v[92:93], v[66:67], v[186:187], v[190:191]
	v_pk_fma_f32 v[66:67], v[66:67], v[182:183], v[68:69]
	v_pk_fma_f32 v[92:93], v[70:71], v[182:183], v[92:93]
	v_pk_fma_f32 v[66:67], v[70:71], v[178:179], v[66:67]
	v_pk_fma_f32 v[90:91], v[90:91], v[178:179], v[92:93]
	v_exp_f32_e32 v93, v90
	v_exp_f32_e32 v68, v66
	v_exp_f32_e32 v69, v67
	v_exp_f32_e32 v130, v91
	v_pk_add_f32 v[72:73], v[72:73], 1.0 op_sel_hi:[1,0]
	v_pk_add_f32 v[68:69], v[68:69], 1.0 op_sel_hi:[1,0]
	v_cvt_pk_bf16_f32 v92, v88, v89
	v_add_f32_e32 v88, 1.0, v93
	v_add_f32_e32 v89, 1.0, v130
	v_rcp_f32_e32 v72, v72
	v_rcp_f32_e32 v73, v73
	v_rcp_f32_e32 v68, v68
	v_rcp_f32_e32 v69, v69
	v_rcp_f32_e32 v88, v88
	v_rcp_f32_e32 v89, v89
	v_pk_fma_f32 v[74:75], v[86:87], v[170:171], v[174:175]
	v_pk_fma_f32 v[130:131], v[78:79], v[170:171], v[174:175]
	v_pk_fma_f32 v[76:77], v[76:77], v[164:165], v[84:85]
	v_pk_fma_f32 v[70:71], v[78:79], v[166:167], v[74:75]
	v_pk_fma_f32 v[130:131], v[82:83], v[166:167], v[130:131]
	v_pk_fma_f32 v[76:77], v[80:81], v[160:161], v[76:77]
	v_pk_mul_f32 v[64:65], v[64:65], v[72:73]
	v_pk_fma_f32 v[70:71], v[82:83], v[162:163], v[70:71]
	v_pk_mul_f32 v[66:67], v[66:67], v[68:69]
	v_pk_fma_f32 v[94:95], v[94:95], v[162:163], v[130:131]
	v_pk_mul_f32 v[88:89], v[90:91], v[88:89]
	v_pk_mul_f32 v[64:65], v[76:77], v[64:65]
	v_pk_mul_f32 v[66:67], v[70:71], v[66:67]
	v_pk_mul_f32 v[88:89], v[94:95], v[88:89]
	v_cvt_pk_bf16_f32 v64, v64, v65
	v_cvt_pk_bf16_f32 v65, v66, v67
	v_add_u32_e32 v66, 0x83, v246
	v_cvt_pk_bf16_f32 v139, v128, v129
	v_add_u32_e32 v128, 0x81, v246
	v_cvt_pk_bf16_f32 v93, v88, v89
	v_add_u32_e32 v88, 0x82, v246
	v_mad_i64_i32 v[66:67], s[34:35], v66, s74, v[134:135]
	v_mad_i64_i32 v[128:129], s[34:35], v128, s74, v[134:135]
	v_mad_i64_i32 v[88:89], s[34:35], v88, s74, v[134:135]
	v_lshl_add_u64 v[82:83], v[66:67], 0, v[204:205]
	v_lshl_add_u64 v[128:129], v[128:129], 0, v[204:205]
	v_lshl_add_u64 v[88:89], v[88:89], 0, v[204:205]
	v_mov_b32_e32 v148, v64
	v_mov_b32_e32 v149, v65
	v_mov_b32_e32 v64, 0
	v_mov_b32_e32 v70, 0
	v_mov_b32_e32 v71, 0
	v_mov_b32_e32 v72, 0
	v_mov_b32_e32 v73, 0
	v_mov_b32_e32 v78, 0
	v_mov_b32_e32 v79, 0
	v_mov_b32_e32 v80, 0
	v_mov_b32_e32 v81, 0
	v_mov_b32_e32 v66, 0
	v_mov_b32_e32 v67, 0
	v_mov_b32_e32 v68, 0
	v_mov_b32_e32 v69, 0
	v_mov_b32_e32 v74, 0
	v_mov_b32_e32 v75, 0
	v_mov_b32_e32 v76, 0
	v_mov_b32_e32 v77, 0
	v_mov_b32_e32 v154, v138
	v_mov_b32_e32 v155, v139
	v_mov_b32_e32 v198, v92
	v_mov_b32_e32 v199, v93
	s_and_saveexec_b64 s[34:35], s[18:19]
	s_cbranch_execz .LBB0_322
	ds_read_b128 v[74:77], v242
	ds_read_b128 v[66:69], v241
	ds_read_b128 v[78:81], v240
	ds_read_b128 v[70:73], v239
.LBB0_322:
	s_or_b64 exec, exec, s[34:35]
	s_waitcnt lgkmcnt(0)
	v_mov_b32_dpp v70, v44 row_shr:1 row_mask:0xf bank_mask:0xf
	v_mov_b32_dpp v71, v45 row_shr:1 row_mask:0xf bank_mask:0xf
	s_waitcnt vmcnt(0)
; #define LAS __attribute__((address_space(3)))
; __device__ __forceinline__ float sigmoidf_(float x) { return __builtin_amdgcn_rcpf(1.0f + __expf(-x)); }
;     __device__ __forceinline__ void operator()(AccRef acc, const Unit& u, int wr, int wc, int fr, int fq) const {
;     ...
;                 f32x4 h2v = (f32x4){0.f, 0.f, 0.f, 0.f}, h3v = h2v, h2g = h2v, h3g = h2v;
;                 const int pb = ai * 2 + wr - 1;
;                 if (pb >= 0 && fr == 0) { const LAS float* xp = xch + (pb * 2) * 256 + clb + 4 * n;
;                     h2v = *(const LAS f32x4*)(xp); h3v = *(const LAS f32x4*)(xp + 256); h2g = *(const LAS f32x4*)(xp + 128); h3g = *(const LAS f32x4*)(xp + 256 + 128); }
;                 float o[4][4];
; #pragma unroll
;                 for (int j = 0; j < 4; ++j) {
;                     const float v0 = acc[ai][0][0][n][j], v1 = acc[ai][0][1][n][j], v2 = acc[ai][0][2][n][j], v3 = acc[ai][0][3][n][j];
;                     const float g0 = acc[ai][1][0][n][j], g1 = acc[ai][1][1][n][j], g2 = acc[ai][1][2][n][j], g3 = acc[ai][1][3][n][j];
;                     const float pv3 = dpp_upd<0x111>(h3v[j], v3), pv2 = dpp_upd<0x111>(h2v[j], v2), pg3 = dpp_upd<0x111>(h3g[j], g3), pg2 = dpp_upd<0x111>(h2g[j], g2);
;                     const float hv0 = bvv[j] + w2v[j] * v0 + w1v[j] * pv3 + w0v[j] * pv2, hv1 = bvv[j] + w2v[j] * v1 + w1v[j] * v0 + w0v[j] * pv3;
;                     const float hv2 = bvv[j] + w2v[j] * v2 + w1v[j] * v1 + w0v[j] * v0, hv3 = bvv[j] + w2v[j] * v3 + w1v[j] * v2 + w0v[j] * v1;
;                     const float hg0 = bvg[j] + w2g[j] * g0 + w1g[j] * pg3 + w0g[j] * pg2, hg1 = bvg[j] + w2g[j] * g1 + w1g[j] * g0 + w0g[j] * pg3;
;                     const float hg2 = bvg[j] + w2g[j] * g2 + w1g[j] * g1 + w0g[j] * g0, hg3 = bvg[j] + w2g[j] * g3 + w1g[j] * g2 + w0g[j] * g1;
;                     o[0][j] = hg0 * sigmoidf_(hg0) * hv0; o[1][j] = hg1 * sigmoidf_(hg1) * hv1; o[2][j] = hg2 * sigmoidf_(hg2) * hv2; o[3][j] = hg3 * sigmoidf_(hg3) * hv3; }
; #pragma unroll
;                 for (int m = 0; m < 4; ++m) { u32x2 w; w.x = cvt_pk_bf16(o[m][0], o[m][1]); w.y = cvt_pk_bf16(o[m][2], o[m][3]);
;                     *(u32x2*)(Aout + (size_t)(row0 + ai * 128 + m) * FH + hc0 + 4 * n) = w; } } }
	v_pk_fma_f32 v[84:85], v[56:57], v[120:121], v[124:125]
	v_mov_b32_dpp v78, v32 row_shr:1 row_mask:0xf bank_mask:0xf
	v_mov_b32_dpp v79, v33 row_shr:1 row_mask:0xf bank_mask:0xf
	v_pk_fma_f32 v[84:85], v[116:117], v[70:71], v[84:85]
	v_mov_b32_dpp v66, v52 row_shr:1 row_mask:0xf bank_mask:0xf
	v_pk_fma_f32 v[78:79], v[112:113], v[78:79], v[84:85]
	v_mov_b32_dpp v67, v53 row_shr:1 row_mask:0xf bank_mask:0xf
	v_exp_f32_e32 v84, v78
	v_exp_f32_e32 v85, v79
	v_pk_fma_f32 v[86:87], v[60:61], v[104:105], v[108:109]
	v_pk_add_f32 v[84:85], v[84:85], 1.0 op_sel_hi:[1,0]
	v_rcp_f32_e32 v84, v84
	v_rcp_f32_e32 v85, v85
	v_mov_b32_dpp v74, v40 row_shr:1 row_mask:0xf bank_mask:0xf
	v_mov_b32_dpp v75, v41 row_shr:1 row_mask:0xf bank_mask:0xf
	v_pk_fma_f32 v[86:87], v[100:101], v[66:67], v[86:87]
	v_pk_mul_f32 v[78:79], v[78:79], v[84:85]
	v_pk_fma_f32 v[74:75], v[96:97], v[74:75], v[86:87]
	v_mov_b32_dpp v72, v46 row_shr:1 row_mask:0xf bank_mask:0xf
	v_mov_b32_dpp v73, v47 row_shr:1 row_mask:0xf bank_mask:0xf
	v_pk_mul_f32 v[74:75], v[74:75], v[78:79]
	v_pk_fma_f32 v[78:79], v[58:59], v[122:123], v[126:127]
	v_mov_b32_dpp v80, v34 row_shr:1 row_mask:0xf bank_mask:0xf
	v_mov_b32_dpp v81, v35 row_shr:1 row_mask:0xf bank_mask:0xf
	v_pk_fma_f32 v[78:79], v[118:119], v[72:73], v[78:79]
	v_mov_b32_dpp v68, v54 row_shr:1 row_mask:0xf bank_mask:0xf
	v_pk_fma_f32 v[78:79], v[114:115], v[80:81], v[78:79]
	v_mov_b32_dpp v69, v55 row_shr:1 row_mask:0xf bank_mask:0xf
	v_exp_f32_e32 v80, v78
	v_exp_f32_e32 v81, v79
	v_pk_fma_f32 v[84:85], v[62:63], v[106:107], v[110:111]
	v_pk_add_f32 v[80:81], v[80:81], 1.0 op_sel_hi:[1,0]
	v_rcp_f32_e32 v80, v80
	v_rcp_f32_e32 v81, v81
	v_mov_b32_dpp v76, v42 row_shr:1 row_mask:0xf bank_mask:0xf
	v_mov_b32_dpp v77, v43 row_shr:1 row_mask:0xf bank_mask:0xf
	v_pk_fma_f32 v[84:85], v[102:103], v[68:69], v[84:85]
	v_pk_mul_f32 v[78:79], v[78:79], v[80:81]
	v_pk_fma_f32 v[76:77], v[98:99], v[76:77], v[84:85]
	v_cvt_pk_bf16_f32 v74, v74, v75
	v_pk_mul_f32 v[76:77], v[76:77], v[78:79]
	v_pk_fma_f32 v[44:45], v[44:45], v[120:121], v[124:125]
	v_cvt_pk_bf16_f32 v75, v76, v77
	v_pk_fma_f32 v[76:77], v[36:37], v[120:121], v[124:125]
	v_mov_b32_e32 v90, v247
	v_mov_b32_e32 v91, v248
	v_mov_b32_e32 v92, v74
	v_mov_b32_e32 v93, v75
	global_store_dwordx4 v[202:203], v[90:93], off
	v_pk_fma_f32 v[76:77], v[56:57], v[116:117], v[76:77]
	v_pk_fma_f32 v[52:53], v[52:53], v[104:105], v[108:109]
	v_pk_fma_f32 v[70:71], v[112:113], v[70:71], v[76:77]
	s_nop 0
	v_exp_f32_e32 v74, v70
	v_exp_f32_e32 v75, v71
	s_nop 0
	v_pk_add_f32 v[74:75], v[74:75], 1.0 op_sel_hi:[1,0]
	v_rcp_f32_e32 v74, v74
	v_rcp_f32_e32 v75, v75
	v_pk_fma_f32 v[76:77], v[48:49], v[104:105], v[108:109]
	v_pk_mul_f32 v[70:71], v[70:71], v[74:75]
	v_pk_fma_f32 v[76:77], v[60:61], v[100:101], v[76:77]
	v_pk_fma_f32 v[74:75], v[50:51], v[106:107], v[110:111]
	v_pk_fma_f32 v[66:67], v[96:97], v[66:67], v[76:77]
	v_pk_fma_f32 v[74:75], v[62:63], v[102:103], v[74:75]
	v_pk_mul_f32 v[66:67], v[66:67], v[70:71]
	v_pk_fma_f32 v[70:71], v[38:39], v[122:123], v[126:127]
	v_pk_fma_f32 v[68:69], v[98:99], v[68:69], v[74:75]
	v_pk_fma_f32 v[70:71], v[58:59], v[118:119], v[70:71]
	v_cvt_pk_bf16_f32 v66, v66, v67
	v_pk_fma_f32 v[70:71], v[114:115], v[72:73], v[70:71]
	s_nop 0
	v_exp_f32_e32 v72, v70
	v_exp_f32_e32 v73, v71
	s_nop 0
	v_pk_add_f32 v[72:73], v[72:73], 1.0 op_sel_hi:[1,0]
	v_rcp_f32_e32 v72, v72
	v_rcp_f32_e32 v73, v73
	s_nop 0
	v_pk_mul_f32 v[70:71], v[70:71], v[72:73]
	s_nop 0
	v_pk_mul_f32 v[68:69], v[68:69], v[70:71]
	s_nop 0
	v_cvt_pk_bf16_f32 v67, v68, v69
	v_pk_fma_f32 v[68:69], v[32:33], v[120:121], v[124:125]
	v_mov_b32_e32 v134, v249
	v_mov_b32_e32 v135, v250
	v_mov_b32_e32 v136, v66
	v_mov_b32_e32 v137, v67
	global_store_dwordx4 v[196:197], v[134:137], off
	v_pk_fma_f32 v[68:69], v[36:37], v[116:117], v[68:69]
	v_pk_fma_f32 v[32:33], v[32:33], v[116:117], v[44:45]
	v_pk_fma_f32 v[56:57], v[56:57], v[112:113], v[68:69]
	v_pk_fma_f32 v[32:33], v[36:37], v[112:113], v[32:33]
	v_exp_f32_e32 v66, v56
	v_exp_f32_e32 v67, v57
	s_nop 0
	v_pk_add_f32 v[66:67], v[66:67], 1.0 op_sel_hi:[1,0]
	v_rcp_f32_e32 v66, v66
	v_rcp_f32_e32 v67, v67
	v_pk_fma_f32 v[68:69], v[40:41], v[104:105], v[108:109]
	v_exp_f32_e32 v44, v32
	v_pk_fma_f32 v[68:69], v[48:49], v[100:101], v[68:69]
	v_pk_mul_f32 v[56:57], v[56:57], v[66:67]
	v_pk_fma_f32 v[60:61], v[60:61], v[96:97], v[68:69]
	v_pk_fma_f32 v[36:37], v[46:47], v[122:123], v[126:127]
	v_pk_mul_f32 v[56:57], v[60:61], v[56:57]
	v_pk_fma_f32 v[60:61], v[34:35], v[122:123], v[126:127]
	v_pk_fma_f32 v[34:35], v[34:35], v[118:119], v[36:37]
	v_pk_fma_f32 v[60:61], v[38:39], v[118:119], v[60:61]
	v_pk_fma_f32 v[34:35], v[38:39], v[114:115], v[34:35]
	v_pk_fma_f32 v[58:59], v[58:59], v[114:115], v[60:61]
	v_exp_f32_e32 v60, v58
	v_exp_f32_e32 v45, v33
	v_exp_f32_e32 v36, v34
	v_exp_f32_e32 v37, v35
	v_exp_f32_e32 v61, v59
	v_cvt_pk_bf16_f32 v56, v56, v57
	v_pk_add_f32 v[44:45], v[44:45], 1.0 op_sel_hi:[1,0]
	v_pk_add_f32 v[36:37], v[36:37], 1.0 op_sel_hi:[1,0]
	v_pk_add_f32 v[60:61], v[60:61], 1.0 op_sel_hi:[1,0]
	v_rcp_f32_e32 v44, v44
	v_rcp_f32_e32 v45, v45
	v_rcp_f32_e32 v36, v36
	v_rcp_f32_e32 v37, v37
	v_rcp_f32_e32 v60, v60
	v_rcp_f32_e32 v61, v61
	v_pk_fma_f32 v[46:47], v[54:55], v[106:107], v[110:111]
	v_pk_fma_f32 v[66:67], v[42:43], v[106:107], v[110:111]
	v_pk_fma_f32 v[40:41], v[40:41], v[100:101], v[52:53]
	v_pk_fma_f32 v[38:39], v[42:43], v[102:103], v[46:47]
	v_pk_fma_f32 v[66:67], v[50:51], v[102:103], v[66:67]
	v_pk_fma_f32 v[40:41], v[48:49], v[96:97], v[40:41]
	v_pk_mul_f32 v[32:33], v[32:33], v[44:45]
	v_pk_fma_f32 v[38:39], v[50:51], v[98:99], v[38:39]
	v_pk_mul_f32 v[34:35], v[34:35], v[36:37]
	v_pk_fma_f32 v[62:63], v[62:63], v[98:99], v[66:67]
	v_pk_mul_f32 v[58:59], v[58:59], v[60:61]
	v_pk_mul_f32 v[32:33], v[40:41], v[32:33]
	v_pk_mul_f32 v[34:35], v[38:39], v[34:35]
	v_pk_mul_f32 v[58:59], v[62:63], v[58:59]
	v_cvt_pk_bf16_f32 v32, v32, v33
	v_cvt_pk_bf16_f32 v33, v34, v35
	v_cvt_pk_bf16_f32 v57, v58, v59
	v_mov_b32_e32 v158, v251
	v_mov_b32_e32 v159, v253
	v_mov_b32_e32 v160, v32
	v_mov_b32_e32 v161, v33
	global_store_dwordx4 v[140:141], v[158:161], off
	v_mov_b32_e32 v65, 0
	v_mov_b32_e32 v66, 0
	v_mov_b32_e32 v67, 0
	v_mov_b32_e32 v40, 0
	v_mov_b32_e32 v41, 0
	v_mov_b32_e32 v42, 0
	v_mov_b32_e32 v43, 0
	v_mov_b32_e32 v32, 0
	v_mov_b32_e32 v33, 0
	v_mov_b32_e32 v34, 0
	v_mov_b32_e32 v35, 0
	v_mov_b32_e32 v36, 0
	v_mov_b32_e32 v37, 0
	v_mov_b32_e32 v38, 0
	v_mov_b32_e32 v39, 0
	v_mov_b32_e32 v162, v254
	v_mov_b32_e32 v163, v255
	v_mov_b32_e32 v164, v56
	v_mov_b32_e32 v165, v57
	global_store_dwordx4 v[152:153], v[162:165], off
	s_and_saveexec_b64 s[34:35], s[22:23]
	s_cbranch_execz .LBB0_305
	ds_read_b128 v[36:39], v237 offset:2064
	ds_read_b128 v[40:43], v237 offset:2576
	ds_read_b128 v[32:35], v237 offset:3088
	ds_read_b128 v[64:67], v237 offset:3600
	s_branch .LBB0_305

; #define LAS __attribute__((address_space(3)))
; __device__ __forceinline__ float sigmoidf_(float x) { return __builtin_amdgcn_rcpf(1.0f + __expf(-x)); }
;     __device__ __forceinline__ void operator()(AccRef acc, const Unit& u, int wr, int wc, int fr, int fq) const {
;     ...
;                 f32x4 h2v = (f32x4){0.f, 0.f, 0.f, 0.f}, h3v = h2v, h2g = h2v, h3g = h2v;
;                 const int pb = ai * 2 + wr - 1;
;                 if (pb >= 0 && fr == 0) { const LAS float* xp = xch + (pb * 2) * 256 + clb + 4 * n;
;                     h2v = *(const LAS f32x4*)(xp); h3v = *(const LAS f32x4*)(xp + 256); h2g = *(const LAS f32x4*)(xp + 128); h3g = *(const LAS f32x4*)(xp + 256 + 128); }
;                 float o[4][4];
; #pragma unroll
;                 for (int j = 0; j < 4; ++j) {
;                     const float v0 = acc[ai][0][0][n][j], v1 = acc[ai][0][1][n][j], v2 = acc[ai][0][2][n][j], v3 = acc[ai][0][3][n][j];
;                     const float g0 = acc[ai][1][0][n][j], g1 = acc[ai][1][1][n][j], g2 = acc[ai][1][2][n][j], g3 = acc[ai][1][3][n][j];
;                     const float pv3 = dpp_upd<0x111>(h3v[j], v3), pv2 = dpp_upd<0x111>(h2v[j], v2), pg3 = dpp_upd<0x111>(h3g[j], g3), pg2 = dpp_upd<0x111>(h2g[j], g2);
;                     const float hv0 = bvv[j] + w2v[j] * v0 + w1v[j] * pv3 + w0v[j] * pv2, hv1 = bvv[j] + w2v[j] * v1 + w1v[j] * v0 + w0v[j] * pv3;
;                     const float hv2 = bvv[j] + w2v[j] * v2 + w1v[j] * v1 + w0v[j] * v0, hv3 = bvv[j] + w2v[j] * v3 + w1v[j] * v2 + w0v[j] * v1;
;                     const float hg0 = bvg[j] + w2g[j] * g0 + w1g[j] * pg3 + w0g[j] * pg2, hg1 = bvg[j] + w2g[j] * g1 + w1g[j] * g0 + w0g[j] * pg3;
;                     const float hg2 = bvg[j] + w2g[j] * g2 + w1g[j] * g1 + w0g[j] * g0, hg3 = bvg[j] + w2g[j] * g3 + w1g[j] * g2 + w0g[j] * g1;
;                     o[0][j] = hg0 * sigmoidf_(hg0) * hv0; o[1][j] = hg1 * sigmoidf_(hg1) * hv1; o[2][j] = hg2 * sigmoidf_(hg2) * hv2; o[3][j] = hg3 * sigmoidf_(hg3) * hv3; }
; #pragma unroll
;                 for (int m = 0; m < 4; ++m) { u32x2 w; w.x = cvt_pk_bf16(o[m][0], o[m][1]); w.y = cvt_pk_bf16(o[m][2], o[m][3]);
;                     *(u32x2*)(Aout + (size_t)(row0 + ai * 128 + m) * FH + hc0 + 4 * n) = w; } } }
.LBB0_754:
	s_or_b64 exec, exec, s[40:41]
	s_waitcnt lgkmcnt(0)
	v_mov_b32_dpp v64, v8 row_shr:1 row_mask:0xf bank_mask:0xf
	v_mov_b32_dpp v65, v9 row_shr:1 row_mask:0xf bank_mask:0xf
	v_pk_fma_f32 v[44:45], v[24:25], v[120:121], v[124:125]
	v_mov_b32_dpp v40, v0 row_shr:1 row_mask:0xf bank_mask:0xf
	v_mov_b32_dpp v41, v1 row_shr:1 row_mask:0xf bank_mask:0xf
	v_pk_fma_f32 v[44:45], v[116:117], v[64:65], v[44:45]
	v_mov_b32_dpp v32, v20 row_shr:1 row_mask:0xf bank_mask:0xf
	v_pk_fma_f32 v[40:41], v[112:113], v[40:41], v[44:45]
	v_mov_b32_dpp v33, v21 row_shr:1 row_mask:0xf bank_mask:0xf
	v_exp_f32_e32 v44, v40
	v_exp_f32_e32 v45, v41
	v_pk_fma_f32 v[46:47], v[28:29], v[104:105], v[108:109]
	v_mov_b32_dpp v36, v12 row_shr:1 row_mask:0xf bank_mask:0xf
	v_pk_add_f32 v[44:45], v[44:45], 1.0 op_sel_hi:[1,0]
	v_rcp_f32_e32 v44, v44
	v_rcp_f32_e32 v45, v45
	v_mov_b32_dpp v37, v13 row_shr:1 row_mask:0xf bank_mask:0xf
	v_pk_fma_f32 v[46:47], v[100:101], v[32:33], v[46:47]
	v_mov_b32_dpp v66, v10 row_shr:1 row_mask:0xf bank_mask:0xf
	v_pk_fma_f32 v[36:37], v[96:97], v[36:37], v[46:47]
	v_pk_mul_f32 v[40:41], v[40:41], v[44:45]
	v_mov_b32_dpp v67, v11 row_shr:1 row_mask:0xf bank_mask:0xf
	v_pk_mul_f32 v[36:37], v[36:37], v[40:41]
	v_pk_fma_f32 v[40:41], v[26:27], v[122:123], v[126:127]
	v_mov_b32_dpp v42, v2 row_shr:1 row_mask:0xf bank_mask:0xf
	v_mov_b32_dpp v43, v3 row_shr:1 row_mask:0xf bank_mask:0xf
	v_pk_fma_f32 v[40:41], v[118:119], v[66:67], v[40:41]
	v_cvt_pk_bf16_f32 v36, v36, v37
	v_pk_fma_f32 v[40:41], v[114:115], v[42:43], v[40:41]
	v_mov_b32_dpp v34, v22 row_shr:1 row_mask:0xf bank_mask:0xf
	v_exp_f32_e32 v42, v40
	v_exp_f32_e32 v43, v41
	v_mov_b32_dpp v35, v23 row_shr:1 row_mask:0xf bank_mask:0xf
	v_pk_add_f32 v[42:43], v[42:43], 1.0 op_sel_hi:[1,0]
	v_rcp_f32_e32 v42, v42
	v_rcp_f32_e32 v43, v43
	v_pk_fma_f32 v[44:45], v[30:31], v[106:107], v[110:111]
	v_mov_b32_dpp v38, v14 row_shr:1 row_mask:0xf bank_mask:0xf
	v_mov_b32_dpp v39, v15 row_shr:1 row_mask:0xf bank_mask:0xf
	v_pk_fma_f32 v[44:45], v[102:103], v[34:35], v[44:45]
	v_pk_mul_f32 v[40:41], v[40:41], v[42:43]
	v_pk_fma_f32 v[38:39], v[98:99], v[38:39], v[44:45]
	v_pk_fma_f32 v[8:9], v[8:9], v[120:121], v[124:125]
	v_pk_mul_f32 v[38:39], v[38:39], v[40:41]
	v_pk_fma_f32 v[20:21], v[20:21], v[104:105], v[108:109]
	v_cvt_pk_bf16_f32 v37, v38, v39
	v_pk_fma_f32 v[38:39], v[4:5], v[120:121], v[124:125]
	v_mov_b32_e32 v146, v36
	v_mov_b32_e32 v147, v37
	global_store_dwordx4 v[132:133], v[144:147], off
	v_pk_fma_f32 v[38:39], v[24:25], v[116:117], v[38:39]
	s_and_b64 vcc, exec, s[14:15]
	v_pk_fma_f32 v[38:39], v[112:113], v[64:65], v[38:39]
	s_mov_b32 s41, s30
	v_exp_f32_e32 v36, v38
	v_exp_f32_e32 v37, v39
	s_mov_b32 s40, s34
	s_mov_b64 s[44:45], s[38:39]
	v_pk_add_f32 v[36:37], v[36:37], 1.0 op_sel_hi:[1,0]
	v_rcp_f32_e32 v36, v36
	v_rcp_f32_e32 v37, v37
	v_pk_fma_f32 v[40:41], v[16:17], v[104:105], v[108:109]
	s_mov_b64 s[42:43], s[36:37]
	v_pk_fma_f32 v[40:41], v[28:29], v[100:101], v[40:41]
	v_pk_mul_f32 v[36:37], v[38:39], v[36:37]
	v_pk_fma_f32 v[32:33], v[96:97], v[32:33], v[40:41]
	v_pk_fma_f32 v[40:41], v[18:19], v[106:107], v[110:111]
	v_pk_mul_f32 v[32:33], v[32:33], v[36:37]
	v_pk_fma_f32 v[36:37], v[6:7], v[122:123], v[126:127]
	v_cvt_pk_bf16_f32 v32, v32, v33
	v_pk_fma_f32 v[36:37], v[26:27], v[118:119], v[36:37]
	v_pk_fma_f32 v[40:41], v[30:31], v[102:103], v[40:41]
	v_pk_fma_f32 v[36:37], v[114:115], v[66:67], v[36:37]
	v_pk_fma_f32 v[34:35], v[98:99], v[34:35], v[40:41]
	v_exp_f32_e32 v38, v36
	v_exp_f32_e32 v39, v37
	s_nop 0
	v_pk_add_f32 v[38:39], v[38:39], 1.0 op_sel_hi:[1,0]
	v_rcp_f32_e32 v38, v38
	v_rcp_f32_e32 v39, v39
	s_nop 0
	v_pk_mul_f32 v[36:37], v[36:37], v[38:39]
	s_nop 0
	v_pk_mul_f32 v[34:35], v[34:35], v[36:37]
	s_nop 0
	v_cvt_pk_bf16_f32 v33, v34, v35
	v_pk_fma_f32 v[34:35], v[0:1], v[120:121], v[124:125]
	v_mov_b32_e32 v156, v32
	v_mov_b32_e32 v157, v33
	global_store_dwordx4 v[128:129], v[154:157], off
	v_pk_fma_f32 v[34:35], v[4:5], v[116:117], v[34:35]
	v_pk_fma_f32 v[0:1], v[0:1], v[116:117], v[8:9]
	v_pk_fma_f32 v[24:25], v[24:25], v[112:113], v[34:35]
	v_pk_fma_f32 v[0:1], v[4:5], v[112:113], v[0:1]
	v_exp_f32_e32 v32, v24
	v_exp_f32_e32 v33, v25
	v_exp_f32_e32 v8, v0
	v_pk_add_f32 v[32:33], v[32:33], 1.0 op_sel_hi:[1,0]
	v_rcp_f32_e32 v32, v32
	v_rcp_f32_e32 v33, v33
	v_pk_fma_f32 v[34:35], v[12:13], v[104:105], v[108:109]
	v_pk_fma_f32 v[4:5], v[10:11], v[122:123], v[126:127]
	v_pk_fma_f32 v[34:35], v[16:17], v[100:101], v[34:35]
	v_pk_mul_f32 v[24:25], v[24:25], v[32:33]
	v_pk_fma_f32 v[28:29], v[28:29], v[96:97], v[34:35]
	v_pk_mul_f32 v[24:25], v[28:29], v[24:25]
	v_pk_fma_f32 v[28:29], v[2:3], v[122:123], v[126:127]
	v_pk_fma_f32 v[2:3], v[2:3], v[118:119], v[4:5]
	v_pk_fma_f32 v[28:29], v[6:7], v[118:119], v[28:29]
	v_pk_fma_f32 v[2:3], v[6:7], v[114:115], v[2:3]
	v_pk_fma_f32 v[26:27], v[26:27], v[114:115], v[28:29]
	v_exp_f32_e32 v28, v26
	v_exp_f32_e32 v29, v27
	v_exp_f32_e32 v9, v1
	v_exp_f32_e32 v4, v2
	v_exp_f32_e32 v5, v3
	v_cvt_pk_bf16_f32 v24, v24, v25
	v_pk_add_f32 v[28:29], v[28:29], 1.0 op_sel_hi:[1,0]
	v_pk_add_f32 v[8:9], v[8:9], 1.0 op_sel_hi:[1,0]
	v_pk_add_f32 v[4:5], v[4:5], 1.0 op_sel_hi:[1,0]
	v_rcp_f32_e32 v28, v28
	v_rcp_f32_e32 v29, v29
	v_rcp_f32_e32 v8, v8
	v_rcp_f32_e32 v9, v9
	v_rcp_f32_e32 v4, v4
	v_rcp_f32_e32 v5, v5
	v_pk_fma_f32 v[32:33], v[14:15], v[106:107], v[110:111]
	v_pk_fma_f32 v[10:11], v[22:23], v[106:107], v[110:111]
	v_pk_fma_f32 v[32:33], v[18:19], v[102:103], v[32:33]
	v_pk_fma_f32 v[12:13], v[12:13], v[100:101], v[20:21]
	v_pk_fma_f32 v[6:7], v[14:15], v[102:103], v[10:11]
	v_pk_fma_f32 v[30:31], v[30:31], v[98:99], v[32:33]
	v_pk_mul_f32 v[26:27], v[26:27], v[28:29]
	v_pk_fma_f32 v[12:13], v[16:17], v[96:97], v[12:13]
	v_pk_mul_f32 v[0:1], v[0:1], v[8:9]
	v_pk_fma_f32 v[6:7], v[18:19], v[98:99], v[6:7]
	v_pk_mul_f32 v[2:3], v[2:3], v[4:5]
	v_pk_mul_f32 v[26:27], v[30:31], v[26:27]
	v_pk_mul_f32 v[0:1], v[12:13], v[0:1]
	v_pk_mul_f32 v[2:3], v[6:7], v[2:3]
	v_cvt_pk_bf16_f32 v25, v26, v27
	v_cvt_pk_bf16_f32 v0, v0, v1
	v_cvt_pk_bf16_f32 v1, v2, v3
	v_mov_b32_e32 v200, v24
	v_mov_b32_e32 v201, v25
	global_store_dwordx4 v[88:89], v[198:201], off
	v_mov_b32_e32 v150, v0
	v_mov_b32_e32 v151, v1
	global_store_dwordx4 v[82:83], v[148:151], off
	s_cbranch_vccnz .LBB0_773

; #define LAS __attribute__((address_space(3)))
; __device__ __forceinline__ float sigmoidf_(float x) { return __builtin_amdgcn_rcpf(1.0f + __expf(-x)); }
;     __device__ __forceinline__ void operator()(AccRef acc, const Unit& u, int wr, int wc, int fr, int fq) const {
;     ...
;                 f32x4 h2v = (f32x4){0.f, 0.f, 0.f, 0.f}, h3v = h2v, h2g = h2v, h3g = h2v;
;                 const int pb = ai * 2 + wr - 1;
;                 if (pb >= 0 && fr == 0) { const LAS float* xp = xch + (pb * 2) * 256 + clb + 4 * n;
;                     h2v = *(const LAS f32x4*)(xp); h3v = *(const LAS f32x4*)(xp + 256); h2g = *(const LAS f32x4*)(xp + 128); h3g = *(const LAS f32x4*)(xp + 256 + 128); }
;                 float o[4][4];
; #pragma unroll
;                 for (int j = 0; j < 4; ++j) {
;                     const float v0 = acc[ai][0][0][n][j], v1 = acc[ai][0][1][n][j], v2 = acc[ai][0][2][n][j], v3 = acc[ai][0][3][n][j];
;                     const float g0 = acc[ai][1][0][n][j], g1 = acc[ai][1][1][n][j], g2 = acc[ai][1][2][n][j], g3 = acc[ai][1][3][n][j];
;                     const float pv3 = dpp_upd<0x111>(h3v[j], v3), pv2 = dpp_upd<0x111>(h2v[j], v2), pg3 = dpp_upd<0x111>(h3g[j], g3), pg2 = dpp_upd<0x111>(h2g[j], g2);
;                     const float hv0 = bvv[j] + w2v[j] * v0 + w1v[j] * pv3 + w0v[j] * pv2, hv1 = bvv[j] + w2v[j] * v1 + w1v[j] * v0 + w0v[j] * pv3;
;                     const float hv2 = bvv[j] + w2v[j] * v2 + w1v[j] * v1 + w0v[j] * v0, hv3 = bvv[j] + w2v[j] * v3 + w1v[j] * v2 + w0v[j] * v1;
;                     const float hg0 = bvg[j] + w2g[j] * g0 + w1g[j] * pg3 + w0g[j] * pg2, hg1 = bvg[j] + w2g[j] * g1 + w1g[j] * g0 + w0g[j] * pg3;
;                     const float hg2 = bvg[j] + w2g[j] * g2 + w1g[j] * g1 + w0g[j] * g0, hg3 = bvg[j] + w2g[j] * g3 + w1g[j] * g2 + w0g[j] * g1;
;                     o[0][j] = hg0 * sigmoidf_(hg0) * hv0; o[1][j] = hg1 * sigmoidf_(hg1) * hv1; o[2][j] = hg2 * sigmoidf_(hg2) * hv2; o[3][j] = hg3 * sigmoidf_(hg3) * hv3; }
; #pragma unroll
;                 for (int m = 0; m < 4; ++m) { u32x2 w; w.x = cvt_pk_bf16(o[m][0], o[m][1]); w.y = cvt_pk_bf16(o[m][2], o[m][3]);
;                     *(u32x2*)(Aout + (size_t)(row0 + ai * 128 + m) * FH + hc0 + 4 * n) = w; } } }
.LBB0_765:
	s_or_b64 exec, exec, s[46:47]
	v_pk_fma_f32 v[248:249], v[152:153], v[184:185], v[188:189]
	v_mov_b32_dpp v206, v128 row_shr:1 row_mask:0xf bank_mask:0xf
	v_mov_b32_dpp v207, v129 row_shr:1 row_mask:0xf bank_mask:0xf
	v_pk_fma_f32 v[248:249], v[180:181], v[198:199], v[248:249]
	v_mov_b32_dpp v194, v148 row_shr:1 row_mask:0xf bank_mask:0xf
	v_pk_fma_f32 v[206:207], v[176:177], v[206:207], v[248:249]
	v_mov_b32_dpp v195, v149 row_shr:1 row_mask:0xf bank_mask:0xf
	v_exp_f32_e32 v248, v206
	v_exp_f32_e32 v249, v207
	v_pk_fma_f32 v[250:251], v[156:157], v[168:169], v[172:173]
	v_pk_add_f32 v[248:249], v[248:249], 1.0 op_sel_hi:[1,0]
	v_rcp_f32_e32 v248, v248
	v_rcp_f32_e32 v249, v249
	v_mov_b32_dpp v202, v136 row_shr:1 row_mask:0xf bank_mask:0xf
	v_mov_b32_dpp v203, v137 row_shr:1 row_mask:0xf bank_mask:0xf
	v_pk_fma_f32 v[250:251], v[164:165], v[194:195], v[250:251]
	v_pk_mul_f32 v[206:207], v[206:207], v[248:249]
	v_pk_fma_f32 v[202:203], v[160:161], v[202:203], v[250:251]
	v_mov_b32_dpp v200, v142 row_shr:1 row_mask:0xf bank_mask:0xf
	v_mov_b32_dpp v201, v143 row_shr:1 row_mask:0xf bank_mask:0xf
	v_pk_mul_f32 v[202:203], v[202:203], v[206:207]
	v_pk_fma_f32 v[206:207], v[154:155], v[186:187], v[190:191]
	v_mov_b32_dpp v208, v130 row_shr:1 row_mask:0xf bank_mask:0xf
	v_mov_b32_dpp v209, v131 row_shr:1 row_mask:0xf bank_mask:0xf
	v_pk_fma_f32 v[206:207], v[182:183], v[200:201], v[206:207]
	v_mov_b32_dpp v196, v150 row_shr:1 row_mask:0xf bank_mask:0xf
	v_pk_fma_f32 v[206:207], v[178:179], v[208:209], v[206:207]
	v_mov_b32_dpp v197, v151 row_shr:1 row_mask:0xf bank_mask:0xf
	v_exp_f32_e32 v193, v206
	v_exp_f32_e32 v209, v207
	v_cvt_pk_bf16_f32 v208, v202, v203
	v_add_f32_e32 v193, 1.0, v193
	v_rcp_f32_e32 v202, v193
	v_add_f32_e32 v193, 1.0, v209
	v_rcp_f32_e32 v203, v193
	v_pk_fma_f32 v[248:249], v[158:159], v[170:171], v[174:175]
	v_mov_b32_dpp v204, v138 row_shr:1 row_mask:0xf bank_mask:0xf
	v_mov_b32_dpp v205, v139 row_shr:1 row_mask:0xf bank_mask:0xf
	v_pk_fma_f32 v[248:249], v[166:167], v[196:197], v[248:249]
	v_pk_mul_f32 v[202:203], v[206:207], v[202:203]
	v_pk_fma_f32 v[204:205], v[162:163], v[204:205], v[248:249]
	v_lshl_add_u32 v246, s40, 8, v236
	v_pk_mul_f32 v[202:203], v[204:205], v[202:203]
	v_lshlrev_b64 v[204:205], 1, v[232:233]
	v_pk_fma_f32 v[232:233], v[132:133], v[184:185], v[188:189]
	v_mov_b64_e32 v[206:207], s[60:61]
	v_pk_fma_f32 v[232:233], v[152:153], v[180:181], v[232:233]
	v_cvt_pk_bf16_f32 v209, v202, v203
	v_pk_fma_f32 v[198:199], v[176:177], v[198:199], v[232:233]
	v_mad_i64_i32 v[202:203], s[40:41], v246, s76, v[206:207]
	v_exp_f32_e32 v193, v198
	v_exp_f32_e32 v232, v199
	v_lshl_add_u64 v[202:203], v[202:203], 0, v[204:205]
	v_add_f32_e32 v193, 1.0, v193
	v_mov_b32_e32 v247, v208
	v_mov_b32_e32 v248, v209
	v_rcp_f32_e32 v208, v193
	v_add_f32_e32 v193, 1.0, v232
	v_rcp_f32_e32 v209, v193
	v_pk_fma_f32 v[232:233], v[144:145], v[168:169], v[172:173]
	v_pk_fma_f32 v[140:141], v[140:141], v[184:185], v[188:189]
	v_pk_fma_f32 v[232:233], v[156:157], v[164:165], v[232:233]
	v_pk_mul_f32 v[198:199], v[198:199], v[208:209]
	v_pk_fma_f32 v[194:195], v[160:161], v[194:195], v[232:233]
	v_pk_fma_f32 v[208:209], v[146:147], v[170:171], v[174:175]
	v_pk_mul_f32 v[194:195], v[194:195], v[198:199]
	v_pk_fma_f32 v[198:199], v[134:135], v[186:187], v[190:191]
	v_pk_fma_f32 v[208:209], v[158:159], v[166:167], v[208:209]
	v_pk_fma_f32 v[198:199], v[154:155], v[182:183], v[198:199]
	v_pk_fma_f32 v[196:197], v[162:163], v[196:197], v[208:209]
	v_pk_fma_f32 v[198:199], v[178:179], v[200:201], v[198:199]
	v_cvt_pk_bf16_f32 v194, v194, v195
	v_exp_f32_e32 v200, v198
	v_exp_f32_e32 v201, v199
	v_pk_fma_f32 v[148:149], v[148:149], v[168:169], v[172:173]
	v_pk_add_f32 v[200:201], v[200:201], 1.0 op_sel_hi:[1,0]
	v_rcp_f32_e32 v200, v200
	v_rcp_f32_e32 v201, v201
	v_or_b32_e32 v193, 1, v246
	v_pk_mul_f32 v[198:199], v[198:199], v[200:201]
	s_nop 0
	v_pk_mul_f32 v[196:197], v[196:197], v[198:199]
	v_pk_fma_f32 v[198:199], v[128:129], v[184:185], v[188:189]
	v_cvt_pk_bf16_f32 v195, v196, v197
	v_pk_fma_f32 v[198:199], v[132:133], v[180:181], v[198:199]
	v_mad_i64_i32 v[196:197], s[40:41], v193, s76, v[206:207]
	v_pk_fma_f32 v[152:153], v[152:153], v[176:177], v[198:199]
	v_lshl_add_u64 v[196:197], v[196:197], 0, v[204:205]
	v_exp_f32_e32 v193, v152
	v_exp_f32_e32 v198, v153
	v_mov_b32_e32 v249, v194
	v_mov_b32_e32 v250, v195
	v_add_f32_e32 v193, 1.0, v193
	v_rcp_f32_e32 v194, v193
	v_add_f32_e32 v193, 1.0, v198
	v_rcp_f32_e32 v195, v193
	v_pk_fma_f32 v[198:199], v[136:137], v[168:169], v[172:173]
	v_pk_fma_f32 v[128:129], v[128:129], v[180:181], v[140:141]
	v_pk_fma_f32 v[198:199], v[144:145], v[164:165], v[198:199]
	v_pk_fma_f32 v[128:129], v[132:133], v[176:177], v[128:129]
	v_pk_fma_f32 v[156:157], v[156:157], v[160:161], v[198:199]
	v_pk_mul_f32 v[152:153], v[152:153], v[194:195]
	v_pk_mul_f32 v[152:153], v[156:157], v[152:153]
	v_pk_fma_f32 v[156:157], v[130:131], v[186:187], v[190:191]
	v_exp_f32_e32 v140, v128
	v_pk_fma_f32 v[132:133], v[142:143], v[186:187], v[190:191]
	v_pk_fma_f32 v[156:157], v[134:135], v[182:183], v[156:157]
	v_pk_fma_f32 v[130:131], v[130:131], v[182:183], v[132:133]
	v_pk_fma_f32 v[154:155], v[154:155], v[178:179], v[156:157]
	v_pk_fma_f32 v[130:131], v[134:135], v[178:179], v[130:131]
	v_exp_f32_e32 v157, v154
	v_exp_f32_e32 v141, v129
	v_exp_f32_e32 v132, v130
	v_exp_f32_e32 v133, v131
	v_exp_f32_e32 v193, v155
	v_pk_add_f32 v[140:141], v[140:141], 1.0 op_sel_hi:[1,0]
	v_pk_add_f32 v[132:133], v[132:133], 1.0 op_sel_hi:[1,0]
	v_cvt_pk_bf16_f32 v156, v152, v153
	v_add_f32_e32 v152, 1.0, v157
; #define LAS __attribute__((address_space(3)))
; __device__ __forceinline__ float sigmoidf_(float x) { return __builtin_amdgcn_rcpf(1.0f + __expf(-x)); }
;     __device__ __forceinline__ void operator()(AccRef acc, const Unit& u, int wr, int wc, int fr, int fq) const {
;     ...
;                 f32x4 h2v = (f32x4){0.f, 0.f, 0.f, 0.f}, h3v = h2v, h2g = h2v, h3g = h2v;
;                 const int pb = ai * 2 + wr - 1;
;                 if (pb >= 0 && fr == 0) { const LAS float* xp = xch + (pb * 2) * 256 + clb + 4 * n;
;                     h2v = *(const LAS f32x4*)(xp); h3v = *(const LAS f32x4*)(xp + 256); h2g = *(const LAS f32x4*)(xp + 128); h3g = *(const LAS f32x4*)(xp + 256 + 128); }
;                 float o[4][4];
; #pragma unroll
;                 for (int j = 0; j < 4; ++j) {
;                     const float v0 = acc[ai][0][0][n][j], v1 = acc[ai][0][1][n][j], v2 = acc[ai][0][2][n][j], v3 = acc[ai][0][3][n][j];
;                     const float g0 = acc[ai][1][0][n][j], g1 = acc[ai][1][1][n][j], g2 = acc[ai][1][2][n][j], g3 = acc[ai][1][3][n][j];
;                     const float pv3 = dpp_upd<0x111>(h3v[j], v3), pv2 = dpp_upd<0x111>(h2v[j], v2), pg3 = dpp_upd<0x111>(h3g[j], g3), pg2 = dpp_upd<0x111>(h2g[j], g2);
;                     const float hv0 = bvv[j] + w2v[j] * v0 + w1v[j] * pv3 + w0v[j] * pv2, hv1 = bvv[j] + w2v[j] * v1 + w1v[j] * v0 + w0v[j] * pv3;
;                     const float hv2 = bvv[j] + w2v[j] * v2 + w1v[j] * v1 + w0v[j] * v0, hv3 = bvv[j] + w2v[j] * v3 + w1v[j] * v2 + w0v[j] * v1;
;                     const float hg0 = bvg[j] + w2g[j] * g0 + w1g[j] * pg3 + w0g[j] * pg2, hg1 = bvg[j] + w2g[j] * g1 + w1g[j] * g0 + w0g[j] * pg3;
;                     const float hg2 = bvg[j] + w2g[j] * g2 + w1g[j] * g1 + w0g[j] * g0, hg3 = bvg[j] + w2g[j] * g3 + w1g[j] * g2 + w0g[j] * g1;
;                     o[0][j] = hg0 * sigmoidf_(hg0) * hv0; o[1][j] = hg1 * sigmoidf_(hg1) * hv1; o[2][j] = hg2 * sigmoidf_(hg2) * hv2; o[3][j] = hg3 * sigmoidf_(hg3) * hv3; }
; #pragma unroll
;                 for (int m = 0; m < 4; ++m) { u32x2 w; w.x = cvt_pk_bf16(o[m][0], o[m][1]); w.y = cvt_pk_bf16(o[m][2], o[m][3]);
;                     *(u32x2*)(Aout + (size_t)(row0 + ai * 128 + m) * FH + hc0 + 4 * n) = w; } } }
	v_add_f32_e32 v153, 1.0, v193
	v_rcp_f32_e32 v140, v140
	v_rcp_f32_e32 v141, v141
	v_rcp_f32_e32 v132, v132
	v_rcp_f32_e32 v133, v133
	v_rcp_f32_e32 v152, v152
	v_rcp_f32_e32 v153, v153
	v_pk_fma_f32 v[142:143], v[150:151], v[170:171], v[174:175]
	v_pk_fma_f32 v[194:195], v[138:139], v[170:171], v[174:175]
	v_pk_fma_f32 v[136:137], v[136:137], v[164:165], v[148:149]
	v_pk_fma_f32 v[134:135], v[138:139], v[166:167], v[142:143]
	v_pk_fma_f32 v[194:195], v[146:147], v[166:167], v[194:195]
	v_pk_fma_f32 v[136:137], v[144:145], v[160:161], v[136:137]
	v_pk_mul_f32 v[128:129], v[128:129], v[140:141]
	v_pk_fma_f32 v[134:135], v[146:147], v[162:163], v[134:135]
	v_pk_mul_f32 v[130:131], v[130:131], v[132:133]
	v_pk_fma_f32 v[158:159], v[158:159], v[162:163], v[194:195]
	v_pk_mul_f32 v[152:153], v[154:155], v[152:153]
	v_pk_mul_f32 v[128:129], v[136:137], v[128:129]
	v_pk_mul_f32 v[130:131], v[134:135], v[130:131]
	v_pk_mul_f32 v[152:153], v[158:159], v[152:153]
	v_cvt_pk_bf16_f32 v128, v128, v129
	v_cvt_pk_bf16_f32 v129, v130, v131
	v_or_b32_e32 v130, 3, v246
	v_cvt_pk_bf16_f32 v157, v152, v153
	v_or_b32_e32 v152, 2, v246
	v_mad_i64_i32 v[130:131], s[40:41], v130, s76, v[206:207]
	v_mad_i64_i32 v[152:153], s[40:41], v152, s76, v[206:207]
	v_lshl_add_u64 v[140:141], v[130:131], 0, v[204:205]
	v_lshl_add_u64 v[152:153], v[152:153], 0, v[204:205]
	v_mov_b32_e32 v251, v128
	v_mov_b32_e32 v253, v129
	v_mov_b32_e32 v193, 0
	v_mov_b32_e32 v194, 0
	v_mov_b32_e32 v195, 0
	v_mov_b32_e32 v136, 0
	v_mov_b32_e32 v137, 0
	v_mov_b32_e32 v138, 0
	v_mov_b32_e32 v139, 0
	v_mov_b32_e32 v128, 0
	v_mov_b32_e32 v129, 0
	v_mov_b32_e32 v130, 0
	v_mov_b32_e32 v131, 0
	v_mov_b32_e32 v132, 0
	v_mov_b32_e32 v133, 0
	v_mov_b32_e32 v134, 0
	v_mov_b32_e32 v135, 0
	v_mov_b32_e32 v254, v156
	v_mov_b32_e32 v255, v157
	s_and_saveexec_b64 s[40:41], s[28:29]
	s_cbranch_execz .LBB0_769
	ds_read_b128 v[132:135], v237 offset:2048
	ds_read_b128 v[136:139], v237 offset:2560
	ds_read_b128 v[128:131], v237 offset:3072
	ds_read_b128 v[192:195], v237 offset:3584
.LBB0_769:
	s_or_b64 exec, exec, s[40:41]
	s_waitcnt lgkmcnt(0)
	v_mov_b32_dpp v192, v72 row_shr:1 row_mask:0xf bank_mask:0xf
	v_mov_b32_dpp v193, v73 row_shr:1 row_mask:0xf bank_mask:0xf
	v_pk_fma_f32 v[142:143], v[88:89], v[184:185], v[188:189]
	v_mov_b32_dpp v136, v64 row_shr:1 row_mask:0xf bank_mask:0xf
	v_mov_b32_dpp v137, v65 row_shr:1 row_mask:0xf bank_mask:0xf
	v_pk_fma_f32 v[142:143], v[180:181], v[192:193], v[142:143]
	v_mov_b32_dpp v128, v84 row_shr:1 row_mask:0xf bank_mask:0xf
	v_pk_fma_f32 v[136:137], v[176:177], v[136:137], v[142:143]
	v_mov_b32_dpp v129, v85 row_shr:1 row_mask:0xf bank_mask:0xf
	v_exp_f32_e32 v142, v136
	v_exp_f32_e32 v143, v137
	v_pk_fma_f32 v[144:145], v[92:93], v[168:169], v[172:173]
	v_mov_b32_dpp v132, v76 row_shr:1 row_mask:0xf bank_mask:0xf
	v_pk_add_f32 v[142:143], v[142:143], 1.0 op_sel_hi:[1,0]
	v_rcp_f32_e32 v142, v142
	v_rcp_f32_e32 v143, v143
	v_mov_b32_dpp v133, v77 row_shr:1 row_mask:0xf bank_mask:0xf
	v_pk_fma_f32 v[144:145], v[164:165], v[128:129], v[144:145]
	v_mov_b32_dpp v194, v74 row_shr:1 row_mask:0xf bank_mask:0xf
	v_pk_fma_f32 v[132:133], v[160:161], v[132:133], v[144:145]
	v_pk_mul_f32 v[136:137], v[136:137], v[142:143]
	v_mov_b32_dpp v195, v75 row_shr:1 row_mask:0xf bank_mask:0xf
	v_pk_mul_f32 v[132:133], v[132:133], v[136:137]
	v_pk_fma_f32 v[136:137], v[90:91], v[186:187], v[190:191]
	v_mov_b32_dpp v138, v66 row_shr:1 row_mask:0xf bank_mask:0xf
	v_mov_b32_dpp v139, v67 row_shr:1 row_mask:0xf bank_mask:0xf
	v_pk_fma_f32 v[136:137], v[182:183], v[194:195], v[136:137]
	v_mov_b32_dpp v130, v86 row_shr:1 row_mask:0xf bank_mask:0xf
	v_pk_fma_f32 v[136:137], v[178:179], v[138:139], v[136:137]
	v_mov_b32_dpp v131, v87 row_shr:1 row_mask:0xf bank_mask:0xf
	v_exp_f32_e32 v139, v136
	v_exp_f32_e32 v142, v137
	v_cvt_pk_bf16_f32 v138, v132, v133
	v_add_f32_e32 v132, 1.0, v139
	v_rcp_f32_e32 v132, v132
	v_add_f32_e32 v133, 1.0, v142
	v_rcp_f32_e32 v133, v133
	v_pk_fma_f32 v[142:143], v[94:95], v[170:171], v[174:175]
	v_mov_b32_dpp v134, v78 row_shr:1 row_mask:0xf bank_mask:0xf
	v_mov_b32_dpp v135, v79 row_shr:1 row_mask:0xf bank_mask:0xf
	v_pk_mul_f32 v[132:133], v[136:137], v[132:133]
	v_pk_fma_f32 v[136:137], v[68:69], v[184:185], v[188:189]
	v_pk_fma_f32 v[142:143], v[166:167], v[130:131], v[142:143]
	v_pk_fma_f32 v[136:137], v[88:89], v[180:181], v[136:137]
	v_pk_fma_f32 v[134:135], v[162:163], v[134:135], v[142:143]
	v_pk_fma_f32 v[136:137], v[176:177], v[192:193], v[136:137]
	v_add_u32_e32 v146, 0x80, v246
	v_exp_f32_e32 v142, v136
	v_exp_f32_e32 v143, v137
	v_pk_mul_f32 v[132:133], v[134:135], v[132:133]
	v_mov_b64_e32 v[134:135], s[60:61]
	v_cvt_pk_bf16_f32 v139, v132, v133
	v_mad_i64_i32 v[132:133], s[40:41], v146, s76, v[134:135]
	v_lshl_add_u64 v[132:133], v[132:133], 0, v[204:205]
	v_mov_b32_e32 v144, v138
	v_mov_b32_e32 v145, v139
	v_add_f32_e32 v138, 1.0, v142
	v_add_f32_e32 v139, 1.0, v143
	v_rcp_f32_e32 v138, v138
	v_rcp_f32_e32 v139, v139
	v_pk_fma_f32 v[142:143], v[80:81], v[168:169], v[172:173]
	v_pk_fma_f32 v[72:73], v[72:73], v[184:185], v[188:189]
	v_pk_fma_f32 v[142:143], v[92:93], v[164:165], v[142:143]
	v_pk_mul_f32 v[136:137], v[136:137], v[138:139]
	v_pk_fma_f32 v[128:129], v[160:161], v[128:129], v[142:143]
	v_pk_fma_f32 v[84:85], v[84:85], v[168:169], v[172:173]
	v_pk_mul_f32 v[128:129], v[128:129], v[136:137]
	v_pk_fma_f32 v[136:137], v[70:71], v[186:187], v[190:191]
	s_nop 0
	v_pk_fma_f32 v[136:137], v[90:91], v[182:183], v[136:137]
	s_nop 0
	v_pk_fma_f32 v[136:137], v[178:179], v[194:195], v[136:137]
	s_nop 0
	v_exp_f32_e32 v139, v136
	v_exp_f32_e32 v142, v137
; #define LAS __attribute__((address_space(3)))
; __device__ __forceinline__ float sigmoidf_(float x) { return __builtin_amdgcn_rcpf(1.0f + __expf(-x)); }
;     __device__ __forceinline__ void operator()(AccRef acc, const Unit& u, int wr, int wc, int fr, int fq) const {
;     ...
;                 f32x4 h2v = (f32x4){0.f, 0.f, 0.f, 0.f}, h3v = h2v, h2g = h2v, h3g = h2v;
;                 const int pb = ai * 2 + wr - 1;
;                 if (pb >= 0 && fr == 0) { const LAS float* xp = xch + (pb * 2) * 256 + clb + 4 * n;
;                     h2v = *(const LAS f32x4*)(xp); h3v = *(const LAS f32x4*)(xp + 256); h2g = *(const LAS f32x4*)(xp + 128); h3g = *(const LAS f32x4*)(xp + 256 + 128); }
;                 float o[4][4];
; #pragma unroll
;                 for (int j = 0; j < 4; ++j) {
;                     const float v0 = acc[ai][0][0][n][j], v1 = acc[ai][0][1][n][j], v2 = acc[ai][0][2][n][j], v3 = acc[ai][0][3][n][j];
;                     const float g0 = acc[ai][1][0][n][j], g1 = acc[ai][1][1][n][j], g2 = acc[ai][1][2][n][j], g3 = acc[ai][1][3][n][j];
;                     const float pv3 = dpp_upd<0x111>(h3v[j], v3), pv2 = dpp_upd<0x111>(h2v[j], v2), pg3 = dpp_upd<0x111>(h3g[j], g3), pg2 = dpp_upd<0x111>(h2g[j], g2);
;                     const float hv0 = bvv[j] + w2v[j] * v0 + w1v[j] * pv3 + w0v[j] * pv2, hv1 = bvv[j] + w2v[j] * v1 + w1v[j] * v0 + w0v[j] * pv3;
;                     const float hv2 = bvv[j] + w2v[j] * v2 + w1v[j] * v1 + w0v[j] * v0, hv3 = bvv[j] + w2v[j] * v3 + w1v[j] * v2 + w0v[j] * v1;
;                     const float hg0 = bvg[j] + w2g[j] * g0 + w1g[j] * pg3 + w0g[j] * pg2, hg1 = bvg[j] + w2g[j] * g1 + w1g[j] * g0 + w0g[j] * pg3;
;                     const float hg2 = bvg[j] + w2g[j] * g2 + w1g[j] * g1 + w0g[j] * g0, hg3 = bvg[j] + w2g[j] * g3 + w1g[j] * g2 + w0g[j] * g1;
;                     o[0][j] = hg0 * sigmoidf_(hg0) * hv0; o[1][j] = hg1 * sigmoidf_(hg1) * hv1; o[2][j] = hg2 * sigmoidf_(hg2) * hv2; o[3][j] = hg3 * sigmoidf_(hg3) * hv3; }
; #pragma unroll
;                 for (int m = 0; m < 4; ++m) { u32x2 w; w.x = cvt_pk_bf16(o[m][0], o[m][1]); w.y = cvt_pk_bf16(o[m][2], o[m][3]);
;                     *(u32x2*)(Aout + (size_t)(row0 + ai * 128 + m) * FH + hc0 + 4 * n) = w; } } }
	v_cvt_pk_bf16_f32 v138, v128, v129
	v_add_f32_e32 v128, 1.0, v139
	v_rcp_f32_e32 v128, v128
	v_add_f32_e32 v129, 1.0, v142
	v_rcp_f32_e32 v129, v129
	v_pk_fma_f32 v[142:143], v[82:83], v[170:171], v[174:175]
	v_pk_mul_f32 v[128:129], v[136:137], v[128:129]
	v_pk_fma_f32 v[142:143], v[94:95], v[166:167], v[142:143]
	v_pk_fma_f32 v[136:137], v[76:77], v[168:169], v[172:173]
	v_pk_fma_f32 v[130:131], v[162:163], v[130:131], v[142:143]
	v_pk_fma_f32 v[136:137], v[80:81], v[164:165], v[136:137]
	v_pk_mul_f32 v[128:129], v[130:131], v[128:129]
	v_pk_fma_f32 v[130:131], v[64:65], v[184:185], v[188:189]
	v_pk_fma_f32 v[64:65], v[64:65], v[180:181], v[72:73]
	v_pk_fma_f32 v[130:131], v[68:69], v[180:181], v[130:131]
	v_pk_fma_f32 v[64:65], v[68:69], v[176:177], v[64:65]
	v_pk_fma_f32 v[88:89], v[88:89], v[176:177], v[130:131]
	v_pk_fma_f32 v[92:93], v[92:93], v[160:161], v[136:137]
	v_exp_f32_e32 v130, v88
	v_exp_f32_e32 v131, v89
	v_exp_f32_e32 v72, v64
	v_pk_add_f32 v[130:131], v[130:131], 1.0 op_sel_hi:[1,0]
	v_rcp_f32_e32 v130, v130
	v_rcp_f32_e32 v131, v131
	v_pk_fma_f32 v[68:69], v[74:75], v[186:187], v[190:191]
	v_exp_f32_e32 v73, v65
	v_pk_mul_f32 v[88:89], v[88:89], v[130:131]
	v_pk_mul_f32 v[88:89], v[92:93], v[88:89]
	v_pk_fma_f32 v[92:93], v[66:67], v[186:187], v[190:191]
	v_pk_fma_f32 v[66:67], v[66:67], v[182:183], v[68:69]
	v_pk_fma_f32 v[92:93], v[70:71], v[182:183], v[92:93]
	v_pk_fma_f32 v[66:67], v[70:71], v[178:179], v[66:67]
	v_pk_fma_f32 v[90:91], v[90:91], v[178:179], v[92:93]
	v_exp_f32_e32 v93, v90
	v_exp_f32_e32 v68, v66
	v_exp_f32_e32 v69, v67
	v_exp_f32_e32 v130, v91
	v_pk_add_f32 v[72:73], v[72:73], 1.0 op_sel_hi:[1,0]
	v_pk_add_f32 v[68:69], v[68:69], 1.0 op_sel_hi:[1,0]
	v_cvt_pk_bf16_f32 v92, v88, v89
	v_add_f32_e32 v88, 1.0, v93
	v_add_f32_e32 v89, 1.0, v130
	v_rcp_f32_e32 v72, v72
	v_rcp_f32_e32 v73, v73
	v_rcp_f32_e32 v68, v68
	v_rcp_f32_e32 v69, v69
	v_rcp_f32_e32 v88, v88
	v_rcp_f32_e32 v89, v89
	v_pk_fma_f32 v[74:75], v[86:87], v[170:171], v[174:175]
	v_pk_fma_f32 v[130:131], v[78:79], v[170:171], v[174:175]
	v_pk_fma_f32 v[76:77], v[76:77], v[164:165], v[84:85]
	v_pk_fma_f32 v[70:71], v[78:79], v[166:167], v[74:75]
	v_pk_fma_f32 v[130:131], v[82:83], v[166:167], v[130:131]
	v_pk_fma_f32 v[76:77], v[80:81], v[160:161], v[76:77]
	v_pk_mul_f32 v[64:65], v[64:65], v[72:73]
	v_pk_fma_f32 v[70:71], v[82:83], v[162:163], v[70:71]
	v_pk_mul_f32 v[66:67], v[66:67], v[68:69]
	v_pk_fma_f32 v[94:95], v[94:95], v[162:163], v[130:131]
	v_pk_mul_f32 v[88:89], v[90:91], v[88:89]
	v_pk_mul_f32 v[64:65], v[76:77], v[64:65]
	v_pk_mul_f32 v[66:67], v[70:71], v[66:67]
	v_pk_mul_f32 v[88:89], v[94:95], v[88:89]
	v_cvt_pk_bf16_f32 v64, v64, v65
	v_cvt_pk_bf16_f32 v65, v66, v67
	v_add_u32_e32 v66, 0x83, v246
	v_cvt_pk_bf16_f32 v139, v128, v129
	v_add_u32_e32 v128, 0x81, v246
	v_cvt_pk_bf16_f32 v93, v88, v89
	v_add_u32_e32 v88, 0x82, v246
	v_mad_i64_i32 v[66:67], s[40:41], v66, s76, v[134:135]
	v_mad_i64_i32 v[128:129], s[40:41], v128, s76, v[134:135]
	v_mad_i64_i32 v[88:89], s[40:41], v88, s76, v[134:135]
	v_lshl_add_u64 v[82:83], v[66:67], 0, v[204:205]
	v_lshl_add_u64 v[128:129], v[128:129], 0, v[204:205]
	v_lshl_add_u64 v[88:89], v[88:89], 0, v[204:205]
	v_mov_b32_e32 v148, v64
	v_mov_b32_e32 v149, v65
	v_mov_b32_e32 v64, 0
	v_mov_b32_e32 v70, 0
	v_mov_b32_e32 v71, 0
	v_mov_b32_e32 v72, 0
	v_mov_b32_e32 v73, 0
	v_mov_b32_e32 v78, 0
	v_mov_b32_e32 v79, 0
	v_mov_b32_e32 v80, 0
	v_mov_b32_e32 v81, 0
	v_mov_b32_e32 v66, 0
	v_mov_b32_e32 v67, 0
	v_mov_b32_e32 v68, 0
	v_mov_b32_e32 v69, 0
	v_mov_b32_e32 v74, 0
	v_mov_b32_e32 v75, 0
	v_mov_b32_e32 v76, 0
	v_mov_b32_e32 v77, 0
	v_mov_b32_e32 v154, v138
	v_mov_b32_e32 v155, v139
	v_mov_b32_e32 v198, v92
	v_mov_b32_e32 v199, v93
	s_and_saveexec_b64 s[40:41], s[26:27]
	s_cbranch_execz .LBB0_771
	ds_read_b128 v[74:77], v242
	ds_read_b128 v[66:69], v241
	ds_read_b128 v[78:81], v240
	ds_read_b128 v[70:73], v239
.LBB0_771:
	s_or_b64 exec, exec, s[40:41]
	s_waitcnt lgkmcnt(0)
	v_mov_b32_dpp v70, v44 row_shr:1 row_mask:0xf bank_mask:0xf
	v_mov_b32_dpp v71, v45 row_shr:1 row_mask:0xf bank_mask:0xf
	s_waitcnt vmcnt(0)
; #define LAS __attribute__((address_space(3)))
; __device__ __forceinline__ float sigmoidf_(float x) { return __builtin_amdgcn_rcpf(1.0f + __expf(-x)); }
;     __device__ __forceinline__ void operator()(AccRef acc, const Unit& u, int wr, int wc, int fr, int fq) const {
;     ...
;                 f32x4 h2v = (f32x4){0.f, 0.f, 0.f, 0.f}, h3v = h2v, h2g = h2v, h3g = h2v;
;                 const int pb = ai * 2 + wr - 1;
;                 if (pb >= 0 && fr == 0) { const LAS float* xp = xch + (pb * 2) * 256 + clb + 4 * n;
;                     h2v = *(const LAS f32x4*)(xp); h3v = *(const LAS f32x4*)(xp + 256); h2g = *(const LAS f32x4*)(xp + 128); h3g = *(const LAS f32x4*)(xp + 256 + 128); }
;                 float o[4][4];
; #pragma unroll
;                 for (int j = 0; j < 4; ++j) {
;                     const float v0 = acc[ai][0][0][n][j], v1 = acc[ai][0][1][n][j], v2 = acc[ai][0][2][n][j], v3 = acc[ai][0][3][n][j];
;                     const float g0 = acc[ai][1][0][n][j], g1 = acc[ai][1][1][n][j], g2 = acc[ai][1][2][n][j], g3 = acc[ai][1][3][n][j];
;                     const float pv3 = dpp_upd<0x111>(h3v[j], v3), pv2 = dpp_upd<0x111>(h2v[j], v2), pg3 = dpp_upd<0x111>(h3g[j], g3), pg2 = dpp_upd<0x111>(h2g[j], g2);
;                     const float hv0 = bvv[j] + w2v[j] * v0 + w1v[j] * pv3 + w0v[j] * pv2, hv1 = bvv[j] + w2v[j] * v1 + w1v[j] * v0 + w0v[j] * pv3;
;                     const float hv2 = bvv[j] + w2v[j] * v2 + w1v[j] * v1 + w0v[j] * v0, hv3 = bvv[j] + w2v[j] * v3 + w1v[j] * v2 + w0v[j] * v1;
;                     const float hg0 = bvg[j] + w2g[j] * g0 + w1g[j] * pg3 + w0g[j] * pg2, hg1 = bvg[j] + w2g[j] * g1 + w1g[j] * g0 + w0g[j] * pg3;
;                     const float hg2 = bvg[j] + w2g[j] * g2 + w1g[j] * g1 + w0g[j] * g0, hg3 = bvg[j] + w2g[j] * g3 + w1g[j] * g2 + w0g[j] * g1;
;                     o[0][j] = hg0 * sigmoidf_(hg0) * hv0; o[1][j] = hg1 * sigmoidf_(hg1) * hv1; o[2][j] = hg2 * sigmoidf_(hg2) * hv2; o[3][j] = hg3 * sigmoidf_(hg3) * hv3; }
; #pragma unroll
;                 for (int m = 0; m < 4; ++m) { u32x2 w; w.x = cvt_pk_bf16(o[m][0], o[m][1]); w.y = cvt_pk_bf16(o[m][2], o[m][3]);
;                     *(u32x2*)(Aout + (size_t)(row0 + ai * 128 + m) * FH + hc0 + 4 * n) = w; } } }
	v_pk_fma_f32 v[84:85], v[56:57], v[120:121], v[124:125]
	v_mov_b32_dpp v78, v32 row_shr:1 row_mask:0xf bank_mask:0xf
	v_mov_b32_dpp v79, v33 row_shr:1 row_mask:0xf bank_mask:0xf
	v_pk_fma_f32 v[84:85], v[116:117], v[70:71], v[84:85]
	v_mov_b32_dpp v66, v52 row_shr:1 row_mask:0xf bank_mask:0xf
	v_pk_fma_f32 v[78:79], v[112:113], v[78:79], v[84:85]
	v_mov_b32_dpp v67, v53 row_shr:1 row_mask:0xf bank_mask:0xf
	v_exp_f32_e32 v84, v78
	v_exp_f32_e32 v85, v79
	v_pk_fma_f32 v[86:87], v[60:61], v[104:105], v[108:109]
	v_pk_add_f32 v[84:85], v[84:85], 1.0 op_sel_hi:[1,0]
	v_rcp_f32_e32 v84, v84
	v_rcp_f32_e32 v85, v85
	v_mov_b32_dpp v74, v40 row_shr:1 row_mask:0xf bank_mask:0xf
	v_mov_b32_dpp v75, v41 row_shr:1 row_mask:0xf bank_mask:0xf
	v_pk_fma_f32 v[86:87], v[100:101], v[66:67], v[86:87]
	v_pk_mul_f32 v[78:79], v[78:79], v[84:85]
	v_pk_fma_f32 v[74:75], v[96:97], v[74:75], v[86:87]
	v_mov_b32_dpp v72, v46 row_shr:1 row_mask:0xf bank_mask:0xf
	v_mov_b32_dpp v73, v47 row_shr:1 row_mask:0xf bank_mask:0xf
	v_pk_mul_f32 v[74:75], v[74:75], v[78:79]
	v_pk_fma_f32 v[78:79], v[58:59], v[122:123], v[126:127]
	v_mov_b32_dpp v80, v34 row_shr:1 row_mask:0xf bank_mask:0xf
	v_mov_b32_dpp v81, v35 row_shr:1 row_mask:0xf bank_mask:0xf
	v_pk_fma_f32 v[78:79], v[118:119], v[72:73], v[78:79]
	v_mov_b32_dpp v68, v54 row_shr:1 row_mask:0xf bank_mask:0xf
	v_pk_fma_f32 v[78:79], v[114:115], v[80:81], v[78:79]
	v_mov_b32_dpp v69, v55 row_shr:1 row_mask:0xf bank_mask:0xf
	v_exp_f32_e32 v80, v78
	v_exp_f32_e32 v81, v79
	v_pk_fma_f32 v[84:85], v[62:63], v[106:107], v[110:111]
	v_pk_add_f32 v[80:81], v[80:81], 1.0 op_sel_hi:[1,0]
	v_rcp_f32_e32 v80, v80
	v_rcp_f32_e32 v81, v81
	v_mov_b32_dpp v76, v42 row_shr:1 row_mask:0xf bank_mask:0xf
	v_mov_b32_dpp v77, v43 row_shr:1 row_mask:0xf bank_mask:0xf
	v_pk_fma_f32 v[84:85], v[102:103], v[68:69], v[84:85]
	v_pk_mul_f32 v[78:79], v[78:79], v[80:81]
	v_pk_fma_f32 v[76:77], v[98:99], v[76:77], v[84:85]
	v_cvt_pk_bf16_f32 v74, v74, v75
	v_pk_mul_f32 v[76:77], v[76:77], v[78:79]
	v_pk_fma_f32 v[44:45], v[44:45], v[120:121], v[124:125]
	v_cvt_pk_bf16_f32 v75, v76, v77
	v_pk_fma_f32 v[76:77], v[36:37], v[120:121], v[124:125]
	v_mov_b32_e32 v90, v247
	v_mov_b32_e32 v91, v248
	v_mov_b32_e32 v92, v74
	v_mov_b32_e32 v93, v75
	global_store_dwordx4 v[202:203], v[90:93], off
	v_pk_fma_f32 v[76:77], v[56:57], v[116:117], v[76:77]
	v_pk_fma_f32 v[52:53], v[52:53], v[104:105], v[108:109]
	v_pk_fma_f32 v[70:71], v[112:113], v[70:71], v[76:77]
	s_nop 0
	v_exp_f32_e32 v74, v70
	v_exp_f32_e32 v75, v71
	s_nop 0
	v_pk_add_f32 v[74:75], v[74:75], 1.0 op_sel_hi:[1,0]
	v_rcp_f32_e32 v74, v74
	v_rcp_f32_e32 v75, v75
	v_pk_fma_f32 v[76:77], v[48:49], v[104:105], v[108:109]
	v_pk_mul_f32 v[70:71], v[70:71], v[74:75]
	v_pk_fma_f32 v[76:77], v[60:61], v[100:101], v[76:77]
	v_pk_fma_f32 v[74:75], v[50:51], v[106:107], v[110:111]
	v_pk_fma_f32 v[66:67], v[96:97], v[66:67], v[76:77]
	v_pk_fma_f32 v[74:75], v[62:63], v[102:103], v[74:75]
	v_pk_mul_f32 v[66:67], v[66:67], v[70:71]
	v_pk_fma_f32 v[70:71], v[38:39], v[122:123], v[126:127]
	v_pk_fma_f32 v[68:69], v[98:99], v[68:69], v[74:75]
	v_pk_fma_f32 v[70:71], v[58:59], v[118:119], v[70:71]
	v_cvt_pk_bf16_f32 v66, v66, v67
	v_pk_fma_f32 v[70:71], v[114:115], v[72:73], v[70:71]
	s_nop 0
	v_exp_f32_e32 v72, v70
	v_exp_f32_e32 v73, v71
	s_nop 0
	v_pk_add_f32 v[72:73], v[72:73], 1.0 op_sel_hi:[1,0]
	v_rcp_f32_e32 v72, v72
	v_rcp_f32_e32 v73, v73
	s_nop 0
	v_pk_mul_f32 v[70:71], v[70:71], v[72:73]
	s_nop 0
	v_pk_mul_f32 v[68:69], v[68:69], v[70:71]
	s_nop 0
	v_cvt_pk_bf16_f32 v67, v68, v69
	v_pk_fma_f32 v[68:69], v[32:33], v[120:121], v[124:125]
	v_mov_b32_e32 v134, v249
	v_mov_b32_e32 v135, v250
	v_mov_b32_e32 v136, v66
	v_mov_b32_e32 v137, v67
	global_store_dwordx4 v[196:197], v[134:137], off
	v_pk_fma_f32 v[68:69], v[36:37], v[116:117], v[68:69]
	v_pk_fma_f32 v[32:33], v[32:33], v[116:117], v[44:45]
	v_pk_fma_f32 v[56:57], v[56:57], v[112:113], v[68:69]
	v_pk_fma_f32 v[32:33], v[36:37], v[112:113], v[32:33]
	v_exp_f32_e32 v66, v56
	v_exp_f32_e32 v67, v57
	s_nop 0
	v_pk_add_f32 v[66:67], v[66:67], 1.0 op_sel_hi:[1,0]
	v_rcp_f32_e32 v66, v66
	v_rcp_f32_e32 v67, v67
	v_pk_fma_f32 v[68:69], v[40:41], v[104:105], v[108:109]
	v_exp_f32_e32 v44, v32
	v_pk_fma_f32 v[68:69], v[48:49], v[100:101], v[68:69]
	v_pk_mul_f32 v[56:57], v[56:57], v[66:67]
	v_pk_fma_f32 v[60:61], v[60:61], v[96:97], v[68:69]
	v_pk_fma_f32 v[36:37], v[46:47], v[122:123], v[126:127]
	v_pk_mul_f32 v[56:57], v[60:61], v[56:57]
	v_pk_fma_f32 v[60:61], v[34:35], v[122:123], v[126:127]
	v_pk_fma_f32 v[34:35], v[34:35], v[118:119], v[36:37]
	v_pk_fma_f32 v[60:61], v[38:39], v[118:119], v[60:61]
	v_pk_fma_f32 v[34:35], v[38:39], v[114:115], v[34:35]
	v_pk_fma_f32 v[58:59], v[58:59], v[114:115], v[60:61]
	v_exp_f32_e32 v60, v58
	v_exp_f32_e32 v45, v33
	v_exp_f32_e32 v36, v34
	v_exp_f32_e32 v37, v35
	v_exp_f32_e32 v61, v59
	v_cvt_pk_bf16_f32 v56, v56, v57
	v_pk_add_f32 v[44:45], v[44:45], 1.0 op_sel_hi:[1,0]
	v_pk_add_f32 v[36:37], v[36:37], 1.0 op_sel_hi:[1,0]
	v_pk_add_f32 v[60:61], v[60:61], 1.0 op_sel_hi:[1,0]
	v_rcp_f32_e32 v44, v44
	v_rcp_f32_e32 v45, v45
	v_rcp_f32_e32 v36, v36
	v_rcp_f32_e32 v37, v37
	v_rcp_f32_e32 v60, v60
	v_rcp_f32_e32 v61, v61
	v_pk_fma_f32 v[46:47], v[54:55], v[106:107], v[110:111]
	v_pk_fma_f32 v[66:67], v[42:43], v[106:107], v[110:111]
	v_pk_fma_f32 v[40:41], v[40:41], v[100:101], v[52:53]
	v_pk_fma_f32 v[38:39], v[42:43], v[102:103], v[46:47]
	v_pk_fma_f32 v[66:67], v[50:51], v[102:103], v[66:67]
	v_pk_fma_f32 v[40:41], v[48:49], v[96:97], v[40:41]
	v_pk_mul_f32 v[32:33], v[32:33], v[44:45]
	v_pk_fma_f32 v[38:39], v[50:51], v[98:99], v[38:39]
	v_pk_mul_f32 v[34:35], v[34:35], v[36:37]
	v_pk_fma_f32 v[62:63], v[62:63], v[98:99], v[66:67]
	v_pk_mul_f32 v[58:59], v[58:59], v[60:61]
	v_pk_mul_f32 v[32:33], v[40:41], v[32:33]
	v_pk_mul_f32 v[34:35], v[38:39], v[34:35]
	v_pk_mul_f32 v[58:59], v[62:63], v[58:59]
	v_cvt_pk_bf16_f32 v32, v32, v33
	v_cvt_pk_bf16_f32 v33, v34, v35
	v_cvt_pk_bf16_f32 v57, v58, v59
	v_mov_b32_e32 v158, v251
	v_mov_b32_e32 v159, v253
	v_mov_b32_e32 v160, v32
	v_mov_b32_e32 v161, v33
	global_store_dwordx4 v[140:141], v[158:161], off
	v_mov_b32_e32 v65, 0
	v_mov_b32_e32 v66, 0
	v_mov_b32_e32 v67, 0
	v_mov_b32_e32 v40, 0
	v_mov_b32_e32 v41, 0
	v_mov_b32_e32 v42, 0
	v_mov_b32_e32 v43, 0
	v_mov_b32_e32 v32, 0
	v_mov_b32_e32 v33, 0
	v_mov_b32_e32 v34, 0
	v_mov_b32_e32 v35, 0
	v_mov_b32_e32 v36, 0
	v_mov_b32_e32 v37, 0
	v_mov_b32_e32 v38, 0
	v_mov_b32_e32 v39, 0
	v_mov_b32_e32 v162, v254
	v_mov_b32_e32 v163, v255
	v_mov_b32_e32 v164, v56
	v_mov_b32_e32 v165, v57
	global_store_dwordx4 v[152:153], v[162:165], off
	s_and_saveexec_b64 s[40:41], s[28:29]
	s_cbranch_execz .LBB0_754
	ds_read_b128 v[36:39], v237 offset:2064
	ds_read_b128 v[40:43], v237 offset:2576
	ds_read_b128 v[32:35], v237 offset:3088
	ds_read_b128 v[64:67], v237 offset:3600
	s_branch .LBB0_754

; #define LAS __attribute__((address_space(3)))
; __device__ __forceinline__ float sigmoidf_(float x) { return __builtin_amdgcn_rcpf(1.0f + __expf(-x)); }
;     __device__ __forceinline__ void operator()(AccRef acc, const Unit& u, int wr, int wc, int fr, int fq) const {
;     ...
;                 f32x4 h2v = (f32x4){0.f, 0.f, 0.f, 0.f}, h3v = h2v, h2g = h2v, h3g = h2v;
;                 const int pb = ai * 2 + wr - 1;
;                 if (pb >= 0 && fr == 0) { const LAS float* xp = xch + (pb * 2) * 256 + clb + 4 * n;
;                     h2v = *(const LAS f32x4*)(xp); h3v = *(const LAS f32x4*)(xp + 256); h2g = *(const LAS f32x4*)(xp + 128); h3g = *(const LAS f32x4*)(xp + 256 + 128); }
;                 float o[4][4];
; #pragma unroll
;                 for (int j = 0; j < 4; ++j) {
;                     const float v0 = acc[ai][0][0][n][j], v1 = acc[ai][0][1][n][j], v2 = acc[ai][0][2][n][j], v3 = acc[ai][0][3][n][j];
;                     const float g0 = acc[ai][1][0][n][j], g1 = acc[ai][1][1][n][j], g2 = acc[ai][1][2][n][j], g3 = acc[ai][1][3][n][j];
;                     const float pv3 = dpp_upd<0x111>(h3v[j], v3), pv2 = dpp_upd<0x111>(h2v[j], v2), pg3 = dpp_upd<0x111>(h3g[j], g3), pg2 = dpp_upd<0x111>(h2g[j], g2);
;                     const float hv0 = bvv[j] + w2v[j] * v0 + w1v[j] * pv3 + w0v[j] * pv2, hv1 = bvv[j] + w2v[j] * v1 + w1v[j] * v0 + w0v[j] * pv3;
;                     const float hv2 = bvv[j] + w2v[j] * v2 + w1v[j] * v1 + w0v[j] * v0, hv3 = bvv[j] + w2v[j] * v3 + w1v[j] * v2 + w0v[j] * v1;
;                     const float hg0 = bvg[j] + w2g[j] * g0 + w1g[j] * pg3 + w0g[j] * pg2, hg1 = bvg[j] + w2g[j] * g1 + w1g[j] * g0 + w0g[j] * pg3;
;                     const float hg2 = bvg[j] + w2g[j] * g2 + w1g[j] * g1 + w0g[j] * g0, hg3 = bvg[j] + w2g[j] * g3 + w1g[j] * g2 + w0g[j] * g1;
;                     o[0][j] = hg0 * sigmoidf_(hg0) * hv0; o[1][j] = hg1 * sigmoidf_(hg1) * hv1; o[2][j] = hg2 * sigmoidf_(hg2) * hv2; o[3][j] = hg3 * sigmoidf_(hg3) * hv3; }
; #pragma unroll
;                 for (int m = 0; m < 4; ++m) { u32x2 w; w.x = cvt_pk_bf16(o[m][0], o[m][1]); w.y = cvt_pk_bf16(o[m][2], o[m][3]);
;                     *(u32x2*)(Aout + (size_t)(row0 + ai * 128 + m) * FH + hc0 + 4 * n) = w; } } }
.LBB0_1355:
	s_or_b64 exec, exec, s[42:43]
	s_waitcnt lgkmcnt(0)
	v_mov_b32_dpp v64, v8 row_shr:1 row_mask:0xf bank_mask:0xf
	v_mov_b32_dpp v65, v9 row_shr:1 row_mask:0xf bank_mask:0xf
	v_pk_fma_f32 v[44:45], v[24:25], v[120:121], v[124:125]
	v_mov_b32_dpp v40, v0 row_shr:1 row_mask:0xf bank_mask:0xf
	v_mov_b32_dpp v41, v1 row_shr:1 row_mask:0xf bank_mask:0xf
	v_pk_fma_f32 v[44:45], v[116:117], v[64:65], v[44:45]
	v_mov_b32_dpp v32, v20 row_shr:1 row_mask:0xf bank_mask:0xf
	v_pk_fma_f32 v[40:41], v[112:113], v[40:41], v[44:45]
	v_mov_b32_dpp v33, v21 row_shr:1 row_mask:0xf bank_mask:0xf
	v_exp_f32_e32 v44, v40
	v_exp_f32_e32 v45, v41
	v_pk_fma_f32 v[46:47], v[28:29], v[104:105], v[108:109]
	v_mov_b32_dpp v36, v12 row_shr:1 row_mask:0xf bank_mask:0xf
	v_pk_add_f32 v[44:45], v[44:45], 1.0 op_sel_hi:[1,0]
	v_rcp_f32_e32 v44, v44
	v_rcp_f32_e32 v45, v45
	v_mov_b32_dpp v37, v13 row_shr:1 row_mask:0xf bank_mask:0xf
	v_pk_fma_f32 v[46:47], v[100:101], v[32:33], v[46:47]
	v_mov_b32_dpp v66, v10 row_shr:1 row_mask:0xf bank_mask:0xf
	v_pk_fma_f32 v[36:37], v[96:97], v[36:37], v[46:47]
	v_pk_mul_f32 v[40:41], v[40:41], v[44:45]
	v_mov_b32_dpp v67, v11 row_shr:1 row_mask:0xf bank_mask:0xf
	v_pk_mul_f32 v[36:37], v[36:37], v[40:41]
	v_pk_fma_f32 v[40:41], v[26:27], v[122:123], v[126:127]
	v_mov_b32_dpp v42, v2 row_shr:1 row_mask:0xf bank_mask:0xf
	v_mov_b32_dpp v43, v3 row_shr:1 row_mask:0xf bank_mask:0xf
	v_pk_fma_f32 v[40:41], v[118:119], v[66:67], v[40:41]
	v_cvt_pk_bf16_f32 v36, v36, v37
	v_pk_fma_f32 v[40:41], v[114:115], v[42:43], v[40:41]
	v_mov_b32_dpp v34, v22 row_shr:1 row_mask:0xf bank_mask:0xf
	v_exp_f32_e32 v42, v40
	v_exp_f32_e32 v43, v41
	v_mov_b32_dpp v35, v23 row_shr:1 row_mask:0xf bank_mask:0xf
	v_pk_add_f32 v[42:43], v[42:43], 1.0 op_sel_hi:[1,0]
	v_rcp_f32_e32 v42, v42
	v_rcp_f32_e32 v43, v43
	v_pk_fma_f32 v[44:45], v[30:31], v[106:107], v[110:111]
	v_mov_b32_dpp v38, v14 row_shr:1 row_mask:0xf bank_mask:0xf
	v_mov_b32_dpp v39, v15 row_shr:1 row_mask:0xf bank_mask:0xf
	v_pk_fma_f32 v[44:45], v[102:103], v[34:35], v[44:45]
	v_pk_mul_f32 v[40:41], v[40:41], v[42:43]
	v_pk_fma_f32 v[38:39], v[98:99], v[38:39], v[44:45]
	v_pk_fma_f32 v[8:9], v[8:9], v[120:121], v[124:125]
	v_pk_mul_f32 v[38:39], v[38:39], v[40:41]
	v_pk_fma_f32 v[20:21], v[20:21], v[104:105], v[108:109]
	v_cvt_pk_bf16_f32 v37, v38, v39
	v_pk_fma_f32 v[38:39], v[4:5], v[120:121], v[124:125]
	v_mov_b32_e32 v146, v36
	v_mov_b32_e32 v147, v37
	global_store_dwordx4 v[132:133], v[144:147], off
	v_pk_fma_f32 v[38:39], v[24:25], v[116:117], v[38:39]
	s_and_b64 vcc, exec, s[14:15]
	v_pk_fma_f32 v[38:39], v[112:113], v[64:65], v[38:39]
	s_mov_b32 s43, s34
	v_exp_f32_e32 v36, v38
	v_exp_f32_e32 v37, v39
	s_mov_b32 s42, s36
	s_mov_b64 s[46:47], s[40:41]
	v_pk_add_f32 v[36:37], v[36:37], 1.0 op_sel_hi:[1,0]
	v_rcp_f32_e32 v36, v36
	v_rcp_f32_e32 v37, v37
	v_pk_fma_f32 v[40:41], v[16:17], v[104:105], v[108:109]
	s_mov_b64 s[44:45], s[38:39]
	v_pk_fma_f32 v[40:41], v[28:29], v[100:101], v[40:41]
	v_pk_mul_f32 v[36:37], v[38:39], v[36:37]
	v_pk_fma_f32 v[32:33], v[96:97], v[32:33], v[40:41]
	v_pk_fma_f32 v[40:41], v[18:19], v[106:107], v[110:111]
	v_pk_mul_f32 v[32:33], v[32:33], v[36:37]
	v_pk_fma_f32 v[36:37], v[6:7], v[122:123], v[126:127]
	v_cvt_pk_bf16_f32 v32, v32, v33
	v_pk_fma_f32 v[36:37], v[26:27], v[118:119], v[36:37]
	v_pk_fma_f32 v[40:41], v[30:31], v[102:103], v[40:41]
	v_pk_fma_f32 v[36:37], v[114:115], v[66:67], v[36:37]
	v_pk_fma_f32 v[34:35], v[98:99], v[34:35], v[40:41]
	v_exp_f32_e32 v38, v36
	v_exp_f32_e32 v39, v37
	s_nop 0
	v_pk_add_f32 v[38:39], v[38:39], 1.0 op_sel_hi:[1,0]
	v_rcp_f32_e32 v38, v38
	v_rcp_f32_e32 v39, v39
	s_nop 0
	v_pk_mul_f32 v[36:37], v[36:37], v[38:39]
	s_nop 0
	v_pk_mul_f32 v[34:35], v[34:35], v[36:37]
	s_nop 0
	v_cvt_pk_bf16_f32 v33, v34, v35
	v_pk_fma_f32 v[34:35], v[0:1], v[120:121], v[124:125]
	v_mov_b32_e32 v156, v32
	v_mov_b32_e32 v157, v33
	global_store_dwordx4 v[128:129], v[154:157], off
	v_pk_fma_f32 v[34:35], v[4:5], v[116:117], v[34:35]
	v_pk_fma_f32 v[0:1], v[0:1], v[116:117], v[8:9]
	v_pk_fma_f32 v[24:25], v[24:25], v[112:113], v[34:35]
	v_pk_fma_f32 v[0:1], v[4:5], v[112:113], v[0:1]
	v_exp_f32_e32 v32, v24
	v_exp_f32_e32 v33, v25
	v_exp_f32_e32 v8, v0
	v_pk_add_f32 v[32:33], v[32:33], 1.0 op_sel_hi:[1,0]
	v_rcp_f32_e32 v32, v32
	v_rcp_f32_e32 v33, v33
	v_pk_fma_f32 v[34:35], v[12:13], v[104:105], v[108:109]
	v_pk_fma_f32 v[4:5], v[10:11], v[122:123], v[126:127]
	v_pk_fma_f32 v[34:35], v[16:17], v[100:101], v[34:35]
	v_pk_mul_f32 v[24:25], v[24:25], v[32:33]
	v_pk_fma_f32 v[28:29], v[28:29], v[96:97], v[34:35]
	v_pk_mul_f32 v[24:25], v[28:29], v[24:25]
	v_pk_fma_f32 v[28:29], v[2:3], v[122:123], v[126:127]
	v_pk_fma_f32 v[2:3], v[2:3], v[118:119], v[4:5]
	v_pk_fma_f32 v[28:29], v[6:7], v[118:119], v[28:29]
	v_pk_fma_f32 v[2:3], v[6:7], v[114:115], v[2:3]
	v_pk_fma_f32 v[26:27], v[26:27], v[114:115], v[28:29]
	v_exp_f32_e32 v28, v26
	v_exp_f32_e32 v29, v27
	v_exp_f32_e32 v9, v1
	v_exp_f32_e32 v4, v2
	v_exp_f32_e32 v5, v3
	v_cvt_pk_bf16_f32 v24, v24, v25
	v_pk_add_f32 v[28:29], v[28:29], 1.0 op_sel_hi:[1,0]
	v_pk_add_f32 v[8:9], v[8:9], 1.0 op_sel_hi:[1,0]
	v_pk_add_f32 v[4:5], v[4:5], 1.0 op_sel_hi:[1,0]
	v_rcp_f32_e32 v28, v28
	v_rcp_f32_e32 v29, v29
	v_rcp_f32_e32 v8, v8
	v_rcp_f32_e32 v9, v9
	v_rcp_f32_e32 v4, v4
	v_rcp_f32_e32 v5, v5
	v_pk_fma_f32 v[32:33], v[14:15], v[106:107], v[110:111]
	v_pk_fma_f32 v[10:11], v[22:23], v[106:107], v[110:111]
	v_pk_fma_f32 v[32:33], v[18:19], v[102:103], v[32:33]
	v_pk_fma_f32 v[12:13], v[12:13], v[100:101], v[20:21]
	v_pk_fma_f32 v[6:7], v[14:15], v[102:103], v[10:11]
	v_pk_fma_f32 v[30:31], v[30:31], v[98:99], v[32:33]
	v_pk_mul_f32 v[26:27], v[26:27], v[28:29]
	v_pk_fma_f32 v[12:13], v[16:17], v[96:97], v[12:13]
	v_pk_mul_f32 v[0:1], v[0:1], v[8:9]
	v_pk_fma_f32 v[6:7], v[18:19], v[98:99], v[6:7]
	v_pk_mul_f32 v[2:3], v[2:3], v[4:5]
	v_pk_mul_f32 v[26:27], v[30:31], v[26:27]
	v_pk_mul_f32 v[0:1], v[12:13], v[0:1]
	v_pk_mul_f32 v[2:3], v[6:7], v[2:3]
	v_cvt_pk_bf16_f32 v25, v26, v27
	v_cvt_pk_bf16_f32 v0, v0, v1
	v_cvt_pk_bf16_f32 v1, v2, v3
	v_mov_b32_e32 v200, v24
	v_mov_b32_e32 v201, v25
	global_store_dwordx4 v[88:89], v[198:201], off
	v_mov_b32_e32 v150, v0
	v_mov_b32_e32 v151, v1
	global_store_dwordx4 v[82:83], v[148:151], off
	s_cbranch_vccnz .LBB0_1374

; #define LAS __attribute__((address_space(3)))
; __device__ __forceinline__ float sigmoidf_(float x) { return __builtin_amdgcn_rcpf(1.0f + __expf(-x)); }
;     __device__ __forceinline__ void operator()(AccRef acc, const Unit& u, int wr, int wc, int fr, int fq) const {
;     ...
;                 f32x4 h2v = (f32x4){0.f, 0.f, 0.f, 0.f}, h3v = h2v, h2g = h2v, h3g = h2v;
;                 const int pb = ai * 2 + wr - 1;
;                 if (pb >= 0 && fr == 0) { const LAS float* xp = xch + (pb * 2) * 256 + clb + 4 * n;
;                     h2v = *(const LAS f32x4*)(xp); h3v = *(const LAS f32x4*)(xp + 256); h2g = *(const LAS f32x4*)(xp + 128); h3g = *(const LAS f32x4*)(xp + 256 + 128); }
;                 float o[4][4];
; #pragma unroll
;                 for (int j = 0; j < 4; ++j) {
;                     const float v0 = acc[ai][0][0][n][j], v1 = acc[ai][0][1][n][j], v2 = acc[ai][0][2][n][j], v3 = acc[ai][0][3][n][j];
;                     const float g0 = acc[ai][1][0][n][j], g1 = acc[ai][1][1][n][j], g2 = acc[ai][1][2][n][j], g3 = acc[ai][1][3][n][j];
;                     const float pv3 = dpp_upd<0x111>(h3v[j], v3), pv2 = dpp_upd<0x111>(h2v[j], v2), pg3 = dpp_upd<0x111>(h3g[j], g3), pg2 = dpp_upd<0x111>(h2g[j], g2);
;                     const float hv0 = bvv[j] + w2v[j] * v0 + w1v[j] * pv3 + w0v[j] * pv2, hv1 = bvv[j] + w2v[j] * v1 + w1v[j] * v0 + w0v[j] * pv3;
;                     const float hv2 = bvv[j] + w2v[j] * v2 + w1v[j] * v1 + w0v[j] * v0, hv3 = bvv[j] + w2v[j] * v3 + w1v[j] * v2 + w0v[j] * v1;
;                     const float hg0 = bvg[j] + w2g[j] * g0 + w1g[j] * pg3 + w0g[j] * pg2, hg1 = bvg[j] + w2g[j] * g1 + w1g[j] * g0 + w0g[j] * pg3;
;                     const float hg2 = bvg[j] + w2g[j] * g2 + w1g[j] * g1 + w0g[j] * g0, hg3 = bvg[j] + w2g[j] * g3 + w1g[j] * g2 + w0g[j] * g1;
;                     o[0][j] = hg0 * sigmoidf_(hg0) * hv0; o[1][j] = hg1 * sigmoidf_(hg1) * hv1; o[2][j] = hg2 * sigmoidf_(hg2) * hv2; o[3][j] = hg3 * sigmoidf_(hg3) * hv3; }
; #pragma unroll
;                 for (int m = 0; m < 4; ++m) { u32x2 w; w.x = cvt_pk_bf16(o[m][0], o[m][1]); w.y = cvt_pk_bf16(o[m][2], o[m][3]);
;                     *(u32x2*)(Aout + (size_t)(row0 + ai * 128 + m) * FH + hc0 + 4 * n) = w; } } }
.LBB0_1366:
	s_or_b64 exec, exec, s[48:49]
	v_pk_fma_f32 v[248:249], v[152:153], v[184:185], v[188:189]
	v_mov_b32_dpp v206, v128 row_shr:1 row_mask:0xf bank_mask:0xf
	v_mov_b32_dpp v207, v129 row_shr:1 row_mask:0xf bank_mask:0xf
	v_pk_fma_f32 v[248:249], v[180:181], v[198:199], v[248:249]
	v_mov_b32_dpp v194, v148 row_shr:1 row_mask:0xf bank_mask:0xf
	v_pk_fma_f32 v[206:207], v[176:177], v[206:207], v[248:249]
	v_mov_b32_dpp v195, v149 row_shr:1 row_mask:0xf bank_mask:0xf
	v_exp_f32_e32 v248, v206
	v_exp_f32_e32 v249, v207
	v_pk_fma_f32 v[250:251], v[156:157], v[168:169], v[172:173]
	v_pk_add_f32 v[248:249], v[248:249], 1.0 op_sel_hi:[1,0]
	v_rcp_f32_e32 v248, v248
	v_rcp_f32_e32 v249, v249
	v_mov_b32_dpp v202, v136 row_shr:1 row_mask:0xf bank_mask:0xf
	v_mov_b32_dpp v203, v137 row_shr:1 row_mask:0xf bank_mask:0xf
	v_pk_fma_f32 v[250:251], v[164:165], v[194:195], v[250:251]
	v_pk_mul_f32 v[206:207], v[206:207], v[248:249]
	v_pk_fma_f32 v[202:203], v[160:161], v[202:203], v[250:251]
	v_mov_b32_dpp v200, v142 row_shr:1 row_mask:0xf bank_mask:0xf
	v_mov_b32_dpp v201, v143 row_shr:1 row_mask:0xf bank_mask:0xf
	v_pk_mul_f32 v[202:203], v[202:203], v[206:207]
	v_pk_fma_f32 v[206:207], v[154:155], v[186:187], v[190:191]
	v_mov_b32_dpp v208, v130 row_shr:1 row_mask:0xf bank_mask:0xf
	v_mov_b32_dpp v209, v131 row_shr:1 row_mask:0xf bank_mask:0xf
	v_pk_fma_f32 v[206:207], v[182:183], v[200:201], v[206:207]
	v_mov_b32_dpp v196, v150 row_shr:1 row_mask:0xf bank_mask:0xf
	v_pk_fma_f32 v[206:207], v[178:179], v[208:209], v[206:207]
	v_mov_b32_dpp v197, v151 row_shr:1 row_mask:0xf bank_mask:0xf
	v_exp_f32_e32 v193, v206
	v_exp_f32_e32 v209, v207
	v_cvt_pk_bf16_f32 v208, v202, v203
	v_add_f32_e32 v193, 1.0, v193
	v_rcp_f32_e32 v202, v193
	v_add_f32_e32 v193, 1.0, v209
	v_rcp_f32_e32 v203, v193
	v_pk_fma_f32 v[248:249], v[158:159], v[170:171], v[174:175]
	v_mov_b32_dpp v204, v138 row_shr:1 row_mask:0xf bank_mask:0xf
	v_mov_b32_dpp v205, v139 row_shr:1 row_mask:0xf bank_mask:0xf
	v_pk_fma_f32 v[248:249], v[166:167], v[196:197], v[248:249]
	v_pk_mul_f32 v[202:203], v[206:207], v[202:203]
	v_pk_fma_f32 v[204:205], v[162:163], v[204:205], v[248:249]
	v_lshl_add_u32 v246, s42, 8, v236
	v_pk_mul_f32 v[202:203], v[204:205], v[202:203]
	v_lshlrev_b64 v[204:205], 1, v[232:233]
	v_pk_fma_f32 v[232:233], v[132:133], v[184:185], v[188:189]
	v_mov_b64_e32 v[206:207], s[60:61]
	v_pk_fma_f32 v[232:233], v[152:153], v[180:181], v[232:233]
	v_cvt_pk_bf16_f32 v209, v202, v203
	v_pk_fma_f32 v[198:199], v[176:177], v[198:199], v[232:233]
	v_mad_i64_i32 v[202:203], s[42:43], v246, s82, v[206:207]
	v_exp_f32_e32 v193, v198
	v_exp_f32_e32 v232, v199
	v_lshl_add_u64 v[202:203], v[202:203], 0, v[204:205]
	v_add_f32_e32 v193, 1.0, v193
	v_mov_b32_e32 v247, v208
	v_mov_b32_e32 v248, v209
	v_rcp_f32_e32 v208, v193
	v_add_f32_e32 v193, 1.0, v232
	v_rcp_f32_e32 v209, v193
	v_pk_fma_f32 v[232:233], v[144:145], v[168:169], v[172:173]
	v_pk_fma_f32 v[140:141], v[140:141], v[184:185], v[188:189]
	v_pk_fma_f32 v[232:233], v[156:157], v[164:165], v[232:233]
	v_pk_mul_f32 v[198:199], v[198:199], v[208:209]
	v_pk_fma_f32 v[194:195], v[160:161], v[194:195], v[232:233]
	v_pk_fma_f32 v[208:209], v[146:147], v[170:171], v[174:175]
	v_pk_mul_f32 v[194:195], v[194:195], v[198:199]
	v_pk_fma_f32 v[198:199], v[134:135], v[186:187], v[190:191]
	v_pk_fma_f32 v[208:209], v[158:159], v[166:167], v[208:209]
	v_pk_fma_f32 v[198:199], v[154:155], v[182:183], v[198:199]
	v_pk_fma_f32 v[196:197], v[162:163], v[196:197], v[208:209]
	v_pk_fma_f32 v[198:199], v[178:179], v[200:201], v[198:199]
	v_cvt_pk_bf16_f32 v194, v194, v195
	v_exp_f32_e32 v200, v198
	v_exp_f32_e32 v201, v199
	v_pk_fma_f32 v[148:149], v[148:149], v[168:169], v[172:173]
	v_pk_add_f32 v[200:201], v[200:201], 1.0 op_sel_hi:[1,0]
	v_rcp_f32_e32 v200, v200
	v_rcp_f32_e32 v201, v201
	v_or_b32_e32 v193, 1, v246
	v_pk_mul_f32 v[198:199], v[198:199], v[200:201]
	s_nop 0
	v_pk_mul_f32 v[196:197], v[196:197], v[198:199]
	v_pk_fma_f32 v[198:199], v[128:129], v[184:185], v[188:189]
	v_cvt_pk_bf16_f32 v195, v196, v197
	v_pk_fma_f32 v[198:199], v[132:133], v[180:181], v[198:199]
	v_mad_i64_i32 v[196:197], s[42:43], v193, s82, v[206:207]
	v_pk_fma_f32 v[152:153], v[152:153], v[176:177], v[198:199]
	v_lshl_add_u64 v[196:197], v[196:197], 0, v[204:205]
	v_exp_f32_e32 v193, v152
	v_exp_f32_e32 v198, v153
	v_mov_b32_e32 v249, v194
	v_mov_b32_e32 v250, v195
	v_add_f32_e32 v193, 1.0, v193
	v_rcp_f32_e32 v194, v193
	v_add_f32_e32 v193, 1.0, v198
	v_rcp_f32_e32 v195, v193
	v_pk_fma_f32 v[198:199], v[136:137], v[168:169], v[172:173]
	v_pk_fma_f32 v[128:129], v[128:129], v[180:181], v[140:141]
	v_pk_fma_f32 v[198:199], v[144:145], v[164:165], v[198:199]
	v_pk_fma_f32 v[128:129], v[132:133], v[176:177], v[128:129]
	v_pk_fma_f32 v[156:157], v[156:157], v[160:161], v[198:199]
	v_pk_mul_f32 v[152:153], v[152:153], v[194:195]
	v_pk_mul_f32 v[152:153], v[156:157], v[152:153]
	v_pk_fma_f32 v[156:157], v[130:131], v[186:187], v[190:191]
	v_exp_f32_e32 v140, v128
	v_pk_fma_f32 v[132:133], v[142:143], v[186:187], v[190:191]
	v_pk_fma_f32 v[156:157], v[134:135], v[182:183], v[156:157]
	v_pk_fma_f32 v[130:131], v[130:131], v[182:183], v[132:133]
	v_pk_fma_f32 v[154:155], v[154:155], v[178:179], v[156:157]
	v_pk_fma_f32 v[130:131], v[134:135], v[178:179], v[130:131]
	v_exp_f32_e32 v157, v154
	v_exp_f32_e32 v141, v129
	v_exp_f32_e32 v132, v130
	v_exp_f32_e32 v133, v131
	v_exp_f32_e32 v193, v155
	v_pk_add_f32 v[140:141], v[140:141], 1.0 op_sel_hi:[1,0]
	v_pk_add_f32 v[132:133], v[132:133], 1.0 op_sel_hi:[1,0]
	v_cvt_pk_bf16_f32 v156, v152, v153
	v_add_f32_e32 v152, 1.0, v157
; #define LAS __attribute__((address_space(3)))
; __device__ __forceinline__ float sigmoidf_(float x) { return __builtin_amdgcn_rcpf(1.0f + __expf(-x)); }
;     __device__ __forceinline__ void operator()(AccRef acc, const Unit& u, int wr, int wc, int fr, int fq) const {
;     ...
;                 f32x4 h2v = (f32x4){0.f, 0.f, 0.f, 0.f}, h3v = h2v, h2g = h2v, h3g = h2v;
;                 const int pb = ai * 2 + wr - 1;
;                 if (pb >= 0 && fr == 0) { const LAS float* xp = xch + (pb * 2) * 256 + clb + 4 * n;
;                     h2v = *(const LAS f32x4*)(xp); h3v = *(const LAS f32x4*)(xp + 256); h2g = *(const LAS f32x4*)(xp + 128); h3g = *(const LAS f32x4*)(xp + 256 + 128); }
;                 float o[4][4];
; #pragma unroll
;                 for (int j = 0; j < 4; ++j) {
;                     const float v0 = acc[ai][0][0][n][j], v1 = acc[ai][0][1][n][j], v2 = acc[ai][0][2][n][j], v3 = acc[ai][0][3][n][j];
;                     const float g0 = acc[ai][1][0][n][j], g1 = acc[ai][1][1][n][j], g2 = acc[ai][1][2][n][j], g3 = acc[ai][1][3][n][j];
;                     const float pv3 = dpp_upd<0x111>(h3v[j], v3), pv2 = dpp_upd<0x111>(h2v[j], v2), pg3 = dpp_upd<0x111>(h3g[j], g3), pg2 = dpp_upd<0x111>(h2g[j], g2);
;                     const float hv0 = bvv[j] + w2v[j] * v0 + w1v[j] * pv3 + w0v[j] * pv2, hv1 = bvv[j] + w2v[j] * v1 + w1v[j] * v0 + w0v[j] * pv3;
;                     const float hv2 = bvv[j] + w2v[j] * v2 + w1v[j] * v1 + w0v[j] * v0, hv3 = bvv[j] + w2v[j] * v3 + w1v[j] * v2 + w0v[j] * v1;
;                     const float hg0 = bvg[j] + w2g[j] * g0 + w1g[j] * pg3 + w0g[j] * pg2, hg1 = bvg[j] + w2g[j] * g1 + w1g[j] * g0 + w0g[j] * pg3;
;                     const float hg2 = bvg[j] + w2g[j] * g2 + w1g[j] * g1 + w0g[j] * g0, hg3 = bvg[j] + w2g[j] * g3 + w1g[j] * g2 + w0g[j] * g1;
;                     o[0][j] = hg0 * sigmoidf_(hg0) * hv0; o[1][j] = hg1 * sigmoidf_(hg1) * hv1; o[2][j] = hg2 * sigmoidf_(hg2) * hv2; o[3][j] = hg3 * sigmoidf_(hg3) * hv3; }
; #pragma unroll
;                 for (int m = 0; m < 4; ++m) { u32x2 w; w.x = cvt_pk_bf16(o[m][0], o[m][1]); w.y = cvt_pk_bf16(o[m][2], o[m][3]);
;                     *(u32x2*)(Aout + (size_t)(row0 + ai * 128 + m) * FH + hc0 + 4 * n) = w; } } }
	v_add_f32_e32 v153, 1.0, v193
	v_rcp_f32_e32 v140, v140
	v_rcp_f32_e32 v141, v141
	v_rcp_f32_e32 v132, v132
	v_rcp_f32_e32 v133, v133
	v_rcp_f32_e32 v152, v152
	v_rcp_f32_e32 v153, v153
	v_pk_fma_f32 v[142:143], v[150:151], v[170:171], v[174:175]
	v_pk_fma_f32 v[194:195], v[138:139], v[170:171], v[174:175]
	v_pk_fma_f32 v[136:137], v[136:137], v[164:165], v[148:149]
	v_pk_fma_f32 v[134:135], v[138:139], v[166:167], v[142:143]
	v_pk_fma_f32 v[194:195], v[146:147], v[166:167], v[194:195]
	v_pk_fma_f32 v[136:137], v[144:145], v[160:161], v[136:137]
	v_pk_mul_f32 v[128:129], v[128:129], v[140:141]
	v_pk_fma_f32 v[134:135], v[146:147], v[162:163], v[134:135]
	v_pk_mul_f32 v[130:131], v[130:131], v[132:133]
	v_pk_fma_f32 v[158:159], v[158:159], v[162:163], v[194:195]
	v_pk_mul_f32 v[152:153], v[154:155], v[152:153]
	v_pk_mul_f32 v[128:129], v[136:137], v[128:129]
	v_pk_mul_f32 v[130:131], v[134:135], v[130:131]
	v_pk_mul_f32 v[152:153], v[158:159], v[152:153]
	v_cvt_pk_bf16_f32 v128, v128, v129
	v_cvt_pk_bf16_f32 v129, v130, v131
	v_or_b32_e32 v130, 3, v246
	v_cvt_pk_bf16_f32 v157, v152, v153
	v_or_b32_e32 v152, 2, v246
	v_mad_i64_i32 v[130:131], s[42:43], v130, s82, v[206:207]
	v_mad_i64_i32 v[152:153], s[42:43], v152, s82, v[206:207]
	v_lshl_add_u64 v[140:141], v[130:131], 0, v[204:205]
	v_lshl_add_u64 v[152:153], v[152:153], 0, v[204:205]
	v_mov_b32_e32 v251, v128
	v_mov_b32_e32 v253, v129
	v_mov_b32_e32 v193, 0
	v_mov_b32_e32 v194, 0
	v_mov_b32_e32 v195, 0
	v_mov_b32_e32 v136, 0
	v_mov_b32_e32 v137, 0
	v_mov_b32_e32 v138, 0
	v_mov_b32_e32 v139, 0
	v_mov_b32_e32 v128, 0
	v_mov_b32_e32 v129, 0
	v_mov_b32_e32 v130, 0
	v_mov_b32_e32 v131, 0
	v_mov_b32_e32 v132, 0
	v_mov_b32_e32 v133, 0
	v_mov_b32_e32 v134, 0
	v_mov_b32_e32 v135, 0
	v_mov_b32_e32 v254, v156
	v_mov_b32_e32 v255, v157
	s_and_saveexec_b64 s[42:43], s[30:31]
	s_cbranch_execz .LBB0_1370
	ds_read_b128 v[132:135], v237 offset:2048
	ds_read_b128 v[136:139], v237 offset:2560
	ds_read_b128 v[128:131], v237 offset:3072
	ds_read_b128 v[192:195], v237 offset:3584
.LBB0_1370:
	s_or_b64 exec, exec, s[42:43]
	s_waitcnt lgkmcnt(0)
	v_mov_b32_dpp v192, v72 row_shr:1 row_mask:0xf bank_mask:0xf
	v_mov_b32_dpp v193, v73 row_shr:1 row_mask:0xf bank_mask:0xf
	v_pk_fma_f32 v[142:143], v[88:89], v[184:185], v[188:189]
	v_mov_b32_dpp v136, v64 row_shr:1 row_mask:0xf bank_mask:0xf
	v_mov_b32_dpp v137, v65 row_shr:1 row_mask:0xf bank_mask:0xf
	v_pk_fma_f32 v[142:143], v[180:181], v[192:193], v[142:143]
	v_mov_b32_dpp v128, v84 row_shr:1 row_mask:0xf bank_mask:0xf
	v_pk_fma_f32 v[136:137], v[176:177], v[136:137], v[142:143]
	v_mov_b32_dpp v129, v85 row_shr:1 row_mask:0xf bank_mask:0xf
	v_exp_f32_e32 v142, v136
	v_exp_f32_e32 v143, v137
	v_pk_fma_f32 v[144:145], v[92:93], v[168:169], v[172:173]
	v_mov_b32_dpp v132, v76 row_shr:1 row_mask:0xf bank_mask:0xf
	v_pk_add_f32 v[142:143], v[142:143], 1.0 op_sel_hi:[1,0]
	v_rcp_f32_e32 v142, v142
	v_rcp_f32_e32 v143, v143
	v_mov_b32_dpp v133, v77 row_shr:1 row_mask:0xf bank_mask:0xf
	v_pk_fma_f32 v[144:145], v[164:165], v[128:129], v[144:145]
	v_mov_b32_dpp v194, v74 row_shr:1 row_mask:0xf bank_mask:0xf
	v_pk_fma_f32 v[132:133], v[160:161], v[132:133], v[144:145]
	v_pk_mul_f32 v[136:137], v[136:137], v[142:143]
	v_mov_b32_dpp v195, v75 row_shr:1 row_mask:0xf bank_mask:0xf
	v_pk_mul_f32 v[132:133], v[132:133], v[136:137]
	v_pk_fma_f32 v[136:137], v[90:91], v[186:187], v[190:191]
	v_mov_b32_dpp v138, v66 row_shr:1 row_mask:0xf bank_mask:0xf
	v_mov_b32_dpp v139, v67 row_shr:1 row_mask:0xf bank_mask:0xf
	v_pk_fma_f32 v[136:137], v[182:183], v[194:195], v[136:137]
	v_mov_b32_dpp v130, v86 row_shr:1 row_mask:0xf bank_mask:0xf
	v_pk_fma_f32 v[136:137], v[178:179], v[138:139], v[136:137]
	v_mov_b32_dpp v131, v87 row_shr:1 row_mask:0xf bank_mask:0xf
	v_exp_f32_e32 v139, v136
	v_exp_f32_e32 v142, v137
	v_cvt_pk_bf16_f32 v138, v132, v133
	v_add_f32_e32 v132, 1.0, v139
	v_rcp_f32_e32 v132, v132
	v_add_f32_e32 v133, 1.0, v142
	v_rcp_f32_e32 v133, v133
	v_pk_fma_f32 v[142:143], v[94:95], v[170:171], v[174:175]
	v_mov_b32_dpp v134, v78 row_shr:1 row_mask:0xf bank_mask:0xf
	v_mov_b32_dpp v135, v79 row_shr:1 row_mask:0xf bank_mask:0xf
	v_pk_mul_f32 v[132:133], v[136:137], v[132:133]
	v_pk_fma_f32 v[136:137], v[68:69], v[184:185], v[188:189]
	v_pk_fma_f32 v[142:143], v[166:167], v[130:131], v[142:143]
	v_pk_fma_f32 v[136:137], v[88:89], v[180:181], v[136:137]
	v_pk_fma_f32 v[134:135], v[162:163], v[134:135], v[142:143]
	v_pk_fma_f32 v[136:137], v[176:177], v[192:193], v[136:137]
	v_add_u32_e32 v146, 0x80, v246
	v_exp_f32_e32 v142, v136
	v_exp_f32_e32 v143, v137
	v_pk_mul_f32 v[132:133], v[134:135], v[132:133]
	v_mov_b64_e32 v[134:135], s[60:61]
	v_cvt_pk_bf16_f32 v139, v132, v133
	v_mad_i64_i32 v[132:133], s[42:43], v146, s82, v[134:135]
	v_lshl_add_u64 v[132:133], v[132:133], 0, v[204:205]
	v_mov_b32_e32 v144, v138
	v_mov_b32_e32 v145, v139
	v_add_f32_e32 v138, 1.0, v142
	v_add_f32_e32 v139, 1.0, v143
	v_rcp_f32_e32 v138, v138
	v_rcp_f32_e32 v139, v139
	v_pk_fma_f32 v[142:143], v[80:81], v[168:169], v[172:173]
	v_pk_fma_f32 v[72:73], v[72:73], v[184:185], v[188:189]
	v_pk_fma_f32 v[142:143], v[92:93], v[164:165], v[142:143]
	v_pk_mul_f32 v[136:137], v[136:137], v[138:139]
	v_pk_fma_f32 v[128:129], v[160:161], v[128:129], v[142:143]
	v_pk_fma_f32 v[84:85], v[84:85], v[168:169], v[172:173]
	v_pk_mul_f32 v[128:129], v[128:129], v[136:137]
	v_pk_fma_f32 v[136:137], v[70:71], v[186:187], v[190:191]
	s_nop 0
	v_pk_fma_f32 v[136:137], v[90:91], v[182:183], v[136:137]
	s_nop 0
	v_pk_fma_f32 v[136:137], v[178:179], v[194:195], v[136:137]
	s_nop 0
	v_exp_f32_e32 v139, v136
	v_exp_f32_e32 v142, v137
; #define LAS __attribute__((address_space(3)))
; __device__ __forceinline__ float sigmoidf_(float x) { return __builtin_amdgcn_rcpf(1.0f + __expf(-x)); }
;     __device__ __forceinline__ void operator()(AccRef acc, const Unit& u, int wr, int wc, int fr, int fq) const {
;     ...
;                 f32x4 h2v = (f32x4){0.f, 0.f, 0.f, 0.f}, h3v = h2v, h2g = h2v, h3g = h2v;
;                 const int pb = ai * 2 + wr - 1;
;                 if (pb >= 0 && fr == 0) { const LAS float* xp = xch + (pb * 2) * 256 + clb + 4 * n;
;                     h2v = *(const LAS f32x4*)(xp); h3v = *(const LAS f32x4*)(xp + 256); h2g = *(const LAS f32x4*)(xp + 128); h3g = *(const LAS f32x4*)(xp + 256 + 128); }
;                 float o[4][4];
; #pragma unroll
;                 for (int j = 0; j < 4; ++j) {
;                     const float v0 = acc[ai][0][0][n][j], v1 = acc[ai][0][1][n][j], v2 = acc[ai][0][2][n][j], v3 = acc[ai][0][3][n][j];
;                     const float g0 = acc[ai][1][0][n][j], g1 = acc[ai][1][1][n][j], g2 = acc[ai][1][2][n][j], g3 = acc[ai][1][3][n][j];
;                     const float pv3 = dpp_upd<0x111>(h3v[j], v3), pv2 = dpp_upd<0x111>(h2v[j], v2), pg3 = dpp_upd<0x111>(h3g[j], g3), pg2 = dpp_upd<0x111>(h2g[j], g2);
;                     const float hv0 = bvv[j] + w2v[j] * v0 + w1v[j] * pv3 + w0v[j] * pv2, hv1 = bvv[j] + w2v[j] * v1 + w1v[j] * v0 + w0v[j] * pv3;
;                     const float hv2 = bvv[j] + w2v[j] * v2 + w1v[j] * v1 + w0v[j] * v0, hv3 = bvv[j] + w2v[j] * v3 + w1v[j] * v2 + w0v[j] * v1;
;                     const float hg0 = bvg[j] + w2g[j] * g0 + w1g[j] * pg3 + w0g[j] * pg2, hg1 = bvg[j] + w2g[j] * g1 + w1g[j] * g0 + w0g[j] * pg3;
;                     const float hg2 = bvg[j] + w2g[j] * g2 + w1g[j] * g1 + w0g[j] * g0, hg3 = bvg[j] + w2g[j] * g3 + w1g[j] * g2 + w0g[j] * g1;
;                     o[0][j] = hg0 * sigmoidf_(hg0) * hv0; o[1][j] = hg1 * sigmoidf_(hg1) * hv1; o[2][j] = hg2 * sigmoidf_(hg2) * hv2; o[3][j] = hg3 * sigmoidf_(hg3) * hv3; }
; #pragma unroll
;                 for (int m = 0; m < 4; ++m) { u32x2 w; w.x = cvt_pk_bf16(o[m][0], o[m][1]); w.y = cvt_pk_bf16(o[m][2], o[m][3]);
;                     *(u32x2*)(Aout + (size_t)(row0 + ai * 128 + m) * FH + hc0 + 4 * n) = w; } } }
	v_cvt_pk_bf16_f32 v138, v128, v129
	v_add_f32_e32 v128, 1.0, v139
	v_rcp_f32_e32 v128, v128
	v_add_f32_e32 v129, 1.0, v142
	v_rcp_f32_e32 v129, v129
	v_pk_fma_f32 v[142:143], v[82:83], v[170:171], v[174:175]
	v_pk_mul_f32 v[128:129], v[136:137], v[128:129]
	v_pk_fma_f32 v[142:143], v[94:95], v[166:167], v[142:143]
	v_pk_fma_f32 v[136:137], v[76:77], v[168:169], v[172:173]
	v_pk_fma_f32 v[130:131], v[162:163], v[130:131], v[142:143]
	v_pk_fma_f32 v[136:137], v[80:81], v[164:165], v[136:137]
	v_pk_mul_f32 v[128:129], v[130:131], v[128:129]
	v_pk_fma_f32 v[130:131], v[64:65], v[184:185], v[188:189]
	v_pk_fma_f32 v[64:65], v[64:65], v[180:181], v[72:73]
	v_pk_fma_f32 v[130:131], v[68:69], v[180:181], v[130:131]
	v_pk_fma_f32 v[64:65], v[68:69], v[176:177], v[64:65]
	v_pk_fma_f32 v[88:89], v[88:89], v[176:177], v[130:131]
	v_pk_fma_f32 v[92:93], v[92:93], v[160:161], v[136:137]
	v_exp_f32_e32 v130, v88
	v_exp_f32_e32 v131, v89
	v_exp_f32_e32 v72, v64
	v_pk_add_f32 v[130:131], v[130:131], 1.0 op_sel_hi:[1,0]
	v_rcp_f32_e32 v130, v130
	v_rcp_f32_e32 v131, v131
	v_pk_fma_f32 v[68:69], v[74:75], v[186:187], v[190:191]
	v_exp_f32_e32 v73, v65
	v_pk_mul_f32 v[88:89], v[88:89], v[130:131]
	v_pk_mul_f32 v[88:89], v[92:93], v[88:89]
	v_pk_fma_f32 v[92:93], v[66:67], v[186:187], v[190:191]
	v_pk_fma_f32 v[66:67], v[66:67], v[182:183], v[68:69]
	v_pk_fma_f32 v[92:93], v[70:71], v[182:183], v[92:93]
	v_pk_fma_f32 v[66:67], v[70:71], v[178:179], v[66:67]
	v_pk_fma_f32 v[90:91], v[90:91], v[178:179], v[92:93]
	v_exp_f32_e32 v93, v90
	v_exp_f32_e32 v68, v66
	v_exp_f32_e32 v69, v67
	v_exp_f32_e32 v130, v91
	v_pk_add_f32 v[72:73], v[72:73], 1.0 op_sel_hi:[1,0]
	v_pk_add_f32 v[68:69], v[68:69], 1.0 op_sel_hi:[1,0]
	v_cvt_pk_bf16_f32 v92, v88, v89
	v_add_f32_e32 v88, 1.0, v93
	v_add_f32_e32 v89, 1.0, v130
	v_rcp_f32_e32 v72, v72
	v_rcp_f32_e32 v73, v73
	v_rcp_f32_e32 v68, v68
	v_rcp_f32_e32 v69, v69
	v_rcp_f32_e32 v88, v88
	v_rcp_f32_e32 v89, v89
	v_pk_fma_f32 v[74:75], v[86:87], v[170:171], v[174:175]
	v_pk_fma_f32 v[130:131], v[78:79], v[170:171], v[174:175]
	v_pk_fma_f32 v[76:77], v[76:77], v[164:165], v[84:85]
	v_pk_fma_f32 v[70:71], v[78:79], v[166:167], v[74:75]
	v_pk_fma_f32 v[130:131], v[82:83], v[166:167], v[130:131]
	v_pk_fma_f32 v[76:77], v[80:81], v[160:161], v[76:77]
	v_pk_mul_f32 v[64:65], v[64:65], v[72:73]
	v_pk_fma_f32 v[70:71], v[82:83], v[162:163], v[70:71]
	v_pk_mul_f32 v[66:67], v[66:67], v[68:69]
	v_pk_fma_f32 v[94:95], v[94:95], v[162:163], v[130:131]
	v_pk_mul_f32 v[88:89], v[90:91], v[88:89]
	v_pk_mul_f32 v[64:65], v[76:77], v[64:65]
	v_pk_mul_f32 v[66:67], v[70:71], v[66:67]
	v_pk_mul_f32 v[88:89], v[94:95], v[88:89]
	v_cvt_pk_bf16_f32 v64, v64, v65
	v_cvt_pk_bf16_f32 v65, v66, v67
	v_add_u32_e32 v66, 0x83, v246
	v_cvt_pk_bf16_f32 v139, v128, v129
	v_add_u32_e32 v128, 0x81, v246
	v_cvt_pk_bf16_f32 v93, v88, v89
	v_add_u32_e32 v88, 0x82, v246
	v_mad_i64_i32 v[66:67], s[42:43], v66, s82, v[134:135]
	v_mad_i64_i32 v[128:129], s[42:43], v128, s82, v[134:135]
	v_mad_i64_i32 v[88:89], s[42:43], v88, s82, v[134:135]
	v_lshl_add_u64 v[82:83], v[66:67], 0, v[204:205]
	v_lshl_add_u64 v[128:129], v[128:129], 0, v[204:205]
	v_lshl_add_u64 v[88:89], v[88:89], 0, v[204:205]
	v_mov_b32_e32 v148, v64
	v_mov_b32_e32 v149, v65
	v_mov_b32_e32 v64, 0
	v_mov_b32_e32 v70, 0
	v_mov_b32_e32 v71, 0
	v_mov_b32_e32 v72, 0
	v_mov_b32_e32 v73, 0
	v_mov_b32_e32 v78, 0
	v_mov_b32_e32 v79, 0
	v_mov_b32_e32 v80, 0
	v_mov_b32_e32 v81, 0
	v_mov_b32_e32 v66, 0
	v_mov_b32_e32 v67, 0
	v_mov_b32_e32 v68, 0
	v_mov_b32_e32 v69, 0
	v_mov_b32_e32 v74, 0
	v_mov_b32_e32 v75, 0
	v_mov_b32_e32 v76, 0
	v_mov_b32_e32 v77, 0
	v_mov_b32_e32 v154, v138
	v_mov_b32_e32 v155, v139
	v_mov_b32_e32 v198, v92
	v_mov_b32_e32 v199, v93
	s_and_saveexec_b64 s[42:43], s[28:29]
	s_cbranch_execz .LBB0_1372
	ds_read_b128 v[74:77], v242
	ds_read_b128 v[66:69], v241
	ds_read_b128 v[78:81], v240
	ds_read_b128 v[70:73], v239
.LBB0_1372:
	s_or_b64 exec, exec, s[42:43]
	s_waitcnt lgkmcnt(0)
	v_mov_b32_dpp v70, v44 row_shr:1 row_mask:0xf bank_mask:0xf
	v_mov_b32_dpp v71, v45 row_shr:1 row_mask:0xf bank_mask:0xf
	s_waitcnt vmcnt(0)
; #define LAS __attribute__((address_space(3)))
; __device__ __forceinline__ float sigmoidf_(float x) { return __builtin_amdgcn_rcpf(1.0f + __expf(-x)); }
;     __device__ __forceinline__ void operator()(AccRef acc, const Unit& u, int wr, int wc, int fr, int fq) const {
;     ...
;                 f32x4 h2v = (f32x4){0.f, 0.f, 0.f, 0.f}, h3v = h2v, h2g = h2v, h3g = h2v;
;                 const int pb = ai * 2 + wr - 1;
;                 if (pb >= 0 && fr == 0) { const LAS float* xp = xch + (pb * 2) * 256 + clb + 4 * n;
;                     h2v = *(const LAS f32x4*)(xp); h3v = *(const LAS f32x4*)(xp + 256); h2g = *(const LAS f32x4*)(xp + 128); h3g = *(const LAS f32x4*)(xp + 256 + 128); }
;                 float o[4][4];
; #pragma unroll
;                 for (int j = 0; j < 4; ++j) {
;                     const float v0 = acc[ai][0][0][n][j], v1 = acc[ai][0][1][n][j], v2 = acc[ai][0][2][n][j], v3 = acc[ai][0][3][n][j];
;                     const float g0 = acc[ai][1][0][n][j], g1 = acc[ai][1][1][n][j], g2 = acc[ai][1][2][n][j], g3 = acc[ai][1][3][n][j];
;                     const float pv3 = dpp_upd<0x111>(h3v[j], v3), pv2 = dpp_upd<0x111>(h2v[j], v2), pg3 = dpp_upd<0x111>(h3g[j], g3), pg2 = dpp_upd<0x111>(h2g[j], g2);
;                     const float hv0 = bvv[j] + w2v[j] * v0 + w1v[j] * pv3 + w0v[j] * pv2, hv1 = bvv[j] + w2v[j] * v1 + w1v[j] * v0 + w0v[j] * pv3;
;                     const float hv2 = bvv[j] + w2v[j] * v2 + w1v[j] * v1 + w0v[j] * v0, hv3 = bvv[j] + w2v[j] * v3 + w1v[j] * v2 + w0v[j] * v1;
;                     const float hg0 = bvg[j] + w2g[j] * g0 + w1g[j] * pg3 + w0g[j] * pg2, hg1 = bvg[j] + w2g[j] * g1 + w1g[j] * g0 + w0g[j] * pg3;
;                     const float hg2 = bvg[j] + w2g[j] * g2 + w1g[j] * g1 + w0g[j] * g0, hg3 = bvg[j] + w2g[j] * g3 + w1g[j] * g2 + w0g[j] * g1;
;                     o[0][j] = hg0 * sigmoidf_(hg0) * hv0; o[1][j] = hg1 * sigmoidf_(hg1) * hv1; o[2][j] = hg2 * sigmoidf_(hg2) * hv2; o[3][j] = hg3 * sigmoidf_(hg3) * hv3; }
; #pragma unroll
;                 for (int m = 0; m < 4; ++m) { u32x2 w; w.x = cvt_pk_bf16(o[m][0], o[m][1]); w.y = cvt_pk_bf16(o[m][2], o[m][3]);
;                     *(u32x2*)(Aout + (size_t)(row0 + ai * 128 + m) * FH + hc0 + 4 * n) = w; } } }
	v_pk_fma_f32 v[84:85], v[56:57], v[120:121], v[124:125]
	v_mov_b32_dpp v78, v32 row_shr:1 row_mask:0xf bank_mask:0xf
	v_mov_b32_dpp v79, v33 row_shr:1 row_mask:0xf bank_mask:0xf
	v_pk_fma_f32 v[84:85], v[116:117], v[70:71], v[84:85]
	v_mov_b32_dpp v66, v52 row_shr:1 row_mask:0xf bank_mask:0xf
	v_pk_fma_f32 v[78:79], v[112:113], v[78:79], v[84:85]
	v_mov_b32_dpp v67, v53 row_shr:1 row_mask:0xf bank_mask:0xf
	v_exp_f32_e32 v84, v78
	v_exp_f32_e32 v85, v79
	v_pk_fma_f32 v[86:87], v[60:61], v[104:105], v[108:109]
	v_pk_add_f32 v[84:85], v[84:85], 1.0 op_sel_hi:[1,0]
	v_rcp_f32_e32 v84, v84
	v_rcp_f32_e32 v85, v85
	v_mov_b32_dpp v74, v40 row_shr:1 row_mask:0xf bank_mask:0xf
	v_mov_b32_dpp v75, v41 row_shr:1 row_mask:0xf bank_mask:0xf
	v_pk_fma_f32 v[86:87], v[100:101], v[66:67], v[86:87]
	v_pk_mul_f32 v[78:79], v[78:79], v[84:85]
	v_pk_fma_f32 v[74:75], v[96:97], v[74:75], v[86:87]
	v_mov_b32_dpp v72, v46 row_shr:1 row_mask:0xf bank_mask:0xf
	v_mov_b32_dpp v73, v47 row_shr:1 row_mask:0xf bank_mask:0xf
	v_pk_mul_f32 v[74:75], v[74:75], v[78:79]
	v_pk_fma_f32 v[78:79], v[58:59], v[122:123], v[126:127]
	v_mov_b32_dpp v80, v34 row_shr:1 row_mask:0xf bank_mask:0xf
	v_mov_b32_dpp v81, v35 row_shr:1 row_mask:0xf bank_mask:0xf
	v_pk_fma_f32 v[78:79], v[118:119], v[72:73], v[78:79]
	v_mov_b32_dpp v68, v54 row_shr:1 row_mask:0xf bank_mask:0xf
	v_pk_fma_f32 v[78:79], v[114:115], v[80:81], v[78:79]
	v_mov_b32_dpp v69, v55 row_shr:1 row_mask:0xf bank_mask:0xf
	v_exp_f32_e32 v80, v78
	v_exp_f32_e32 v81, v79
	v_pk_fma_f32 v[84:85], v[62:63], v[106:107], v[110:111]
	v_pk_add_f32 v[80:81], v[80:81], 1.0 op_sel_hi:[1,0]
	v_rcp_f32_e32 v80, v80
	v_rcp_f32_e32 v81, v81
	v_mov_b32_dpp v76, v42 row_shr:1 row_mask:0xf bank_mask:0xf
	v_mov_b32_dpp v77, v43 row_shr:1 row_mask:0xf bank_mask:0xf
	v_pk_fma_f32 v[84:85], v[102:103], v[68:69], v[84:85]
	v_pk_mul_f32 v[78:79], v[78:79], v[80:81]
	v_pk_fma_f32 v[76:77], v[98:99], v[76:77], v[84:85]
	v_cvt_pk_bf16_f32 v74, v74, v75
	v_pk_mul_f32 v[76:77], v[76:77], v[78:79]
	v_pk_fma_f32 v[44:45], v[44:45], v[120:121], v[124:125]
	v_cvt_pk_bf16_f32 v75, v76, v77
	v_pk_fma_f32 v[76:77], v[36:37], v[120:121], v[124:125]
	v_mov_b32_e32 v90, v247
	v_mov_b32_e32 v91, v248
	v_mov_b32_e32 v92, v74
	v_mov_b32_e32 v93, v75
	global_store_dwordx4 v[202:203], v[90:93], off
	v_pk_fma_f32 v[76:77], v[56:57], v[116:117], v[76:77]
	v_pk_fma_f32 v[52:53], v[52:53], v[104:105], v[108:109]
	v_pk_fma_f32 v[70:71], v[112:113], v[70:71], v[76:77]
	s_nop 0
	v_exp_f32_e32 v74, v70
	v_exp_f32_e32 v75, v71
	s_nop 0
	v_pk_add_f32 v[74:75], v[74:75], 1.0 op_sel_hi:[1,0]
	v_rcp_f32_e32 v74, v74
	v_rcp_f32_e32 v75, v75
	v_pk_fma_f32 v[76:77], v[48:49], v[104:105], v[108:109]
	v_pk_mul_f32 v[70:71], v[70:71], v[74:75]
	v_pk_fma_f32 v[76:77], v[60:61], v[100:101], v[76:77]
	v_pk_fma_f32 v[74:75], v[50:51], v[106:107], v[110:111]
	v_pk_fma_f32 v[66:67], v[96:97], v[66:67], v[76:77]
	v_pk_fma_f32 v[74:75], v[62:63], v[102:103], v[74:75]
	v_pk_mul_f32 v[66:67], v[66:67], v[70:71]
	v_pk_fma_f32 v[70:71], v[38:39], v[122:123], v[126:127]
	v_pk_fma_f32 v[68:69], v[98:99], v[68:69], v[74:75]
	v_pk_fma_f32 v[70:71], v[58:59], v[118:119], v[70:71]
	v_cvt_pk_bf16_f32 v66, v66, v67
	v_pk_fma_f32 v[70:71], v[114:115], v[72:73], v[70:71]
	s_nop 0
	v_exp_f32_e32 v72, v70
	v_exp_f32_e32 v73, v71
	s_nop 0
	v_pk_add_f32 v[72:73], v[72:73], 1.0 op_sel_hi:[1,0]
	v_rcp_f32_e32 v72, v72
	v_rcp_f32_e32 v73, v73
	s_nop 0
	v_pk_mul_f32 v[70:71], v[70:71], v[72:73]
	s_nop 0
	v_pk_mul_f32 v[68:69], v[68:69], v[70:71]
	s_nop 0
	v_cvt_pk_bf16_f32 v67, v68, v69
	v_pk_fma_f32 v[68:69], v[32:33], v[120:121], v[124:125]
	v_mov_b32_e32 v134, v249
	v_mov_b32_e32 v135, v250
	v_mov_b32_e32 v136, v66
	v_mov_b32_e32 v137, v67
	global_store_dwordx4 v[196:197], v[134:137], off
	v_pk_fma_f32 v[68:69], v[36:37], v[116:117], v[68:69]
	v_pk_fma_f32 v[32:33], v[32:33], v[116:117], v[44:45]
	v_pk_fma_f32 v[56:57], v[56:57], v[112:113], v[68:69]
	v_pk_fma_f32 v[32:33], v[36:37], v[112:113], v[32:33]
	v_exp_f32_e32 v66, v56
	v_exp_f32_e32 v67, v57
	s_nop 0
	v_pk_add_f32 v[66:67], v[66:67], 1.0 op_sel_hi:[1,0]
	v_rcp_f32_e32 v66, v66
	v_rcp_f32_e32 v67, v67
	v_pk_fma_f32 v[68:69], v[40:41], v[104:105], v[108:109]
	v_exp_f32_e32 v44, v32
	v_pk_fma_f32 v[68:69], v[48:49], v[100:101], v[68:69]
	v_pk_mul_f32 v[56:57], v[56:57], v[66:67]
	v_pk_fma_f32 v[60:61], v[60:61], v[96:97], v[68:69]
	v_pk_fma_f32 v[36:37], v[46:47], v[122:123], v[126:127]
	v_pk_mul_f32 v[56:57], v[60:61], v[56:57]
	v_pk_fma_f32 v[60:61], v[34:35], v[122:123], v[126:127]
	v_pk_fma_f32 v[34:35], v[34:35], v[118:119], v[36:37]
	v_pk_fma_f32 v[60:61], v[38:39], v[118:119], v[60:61]
	v_pk_fma_f32 v[34:35], v[38:39], v[114:115], v[34:35]
	v_pk_fma_f32 v[58:59], v[58:59], v[114:115], v[60:61]
	v_exp_f32_e32 v60, v58
	v_exp_f32_e32 v45, v33
	v_exp_f32_e32 v36, v34
	v_exp_f32_e32 v37, v35
	v_exp_f32_e32 v61, v59
	v_cvt_pk_bf16_f32 v56, v56, v57
	v_pk_add_f32 v[44:45], v[44:45], 1.0 op_sel_hi:[1,0]
	v_pk_add_f32 v[36:37], v[36:37], 1.0 op_sel_hi:[1,0]
	v_pk_add_f32 v[60:61], v[60:61], 1.0 op_sel_hi:[1,0]
	v_rcp_f32_e32 v44, v44
	v_rcp_f32_e32 v45, v45
	v_rcp_f32_e32 v36, v36
	v_rcp_f32_e32 v37, v37
	v_rcp_f32_e32 v60, v60
	v_rcp_f32_e32 v61, v61
	v_pk_fma_f32 v[46:47], v[54:55], v[106:107], v[110:111]
	v_pk_fma_f32 v[66:67], v[42:43], v[106:107], v[110:111]
	v_pk_fma_f32 v[40:41], v[40:41], v[100:101], v[52:53]
	v_pk_fma_f32 v[38:39], v[42:43], v[102:103], v[46:47]
	v_pk_fma_f32 v[66:67], v[50:51], v[102:103], v[66:67]
	v_pk_fma_f32 v[40:41], v[48:49], v[96:97], v[40:41]
	v_pk_mul_f32 v[32:33], v[32:33], v[44:45]
	v_pk_fma_f32 v[38:39], v[50:51], v[98:99], v[38:39]
	v_pk_mul_f32 v[34:35], v[34:35], v[36:37]
	v_pk_fma_f32 v[62:63], v[62:63], v[98:99], v[66:67]
	v_pk_mul_f32 v[58:59], v[58:59], v[60:61]
	v_pk_mul_f32 v[32:33], v[40:41], v[32:33]
	v_pk_mul_f32 v[34:35], v[38:39], v[34:35]
	v_pk_mul_f32 v[58:59], v[62:63], v[58:59]
	v_cvt_pk_bf16_f32 v32, v32, v33
	v_cvt_pk_bf16_f32 v33, v34, v35
	v_cvt_pk_bf16_f32 v57, v58, v59
	v_mov_b32_e32 v158, v251
	v_mov_b32_e32 v159, v253
	v_mov_b32_e32 v160, v32
	v_mov_b32_e32 v161, v33
	global_store_dwordx4 v[140:141], v[158:161], off
	v_mov_b32_e32 v65, 0
	v_mov_b32_e32 v66, 0
	v_mov_b32_e32 v67, 0
	v_mov_b32_e32 v40, 0
	v_mov_b32_e32 v41, 0
	v_mov_b32_e32 v42, 0
	v_mov_b32_e32 v43, 0
	v_mov_b32_e32 v32, 0
	v_mov_b32_e32 v33, 0
	v_mov_b32_e32 v34, 0
	v_mov_b32_e32 v35, 0
	v_mov_b32_e32 v36, 0
	v_mov_b32_e32 v37, 0
	v_mov_b32_e32 v38, 0
	v_mov_b32_e32 v39, 0
	v_mov_b32_e32 v162, v254
	v_mov_b32_e32 v163, v255
	v_mov_b32_e32 v164, v56
	v_mov_b32_e32 v165, v57
	global_store_dwordx4 v[152:153], v[162:165], off
	s_and_saveexec_b64 s[42:43], s[30:31]
	s_cbranch_execz .LBB0_1355
	ds_read_b128 v[36:39], v237 offset:2064
	ds_read_b128 v[40:43], v237 offset:2576
	ds_read_b128 v[32:35], v237 offset:3088
	ds_read_b128 v[64:67], v237 offset:3600
	s_branch .LBB0_1355

; #define LAS __attribute__((address_space(3)))
; __device__ __forceinline__ float sigmoidf_(float x) { return __builtin_amdgcn_rcpf(1.0f + __expf(-x)); }
;     __device__ __forceinline__ void operator()(AccRef acc, const Unit& u, int wr, int wc, int fr, int fq) const {
;     ...
;                 if (pb >= 0 && fr == 0) { const LAS float* xp = xch + (pb * 2) * 256 + clb + 4 * n;
;                     h2v = *(const LAS f32x4*)(xp); h3v = *(const LAS f32x4*)(xp + 256); h2g = *(const LAS f32x4*)(xp + 128); h3g = *(const LAS f32x4*)(xp + 256 + 128); }
;                 float o[4][4];
; #pragma unroll
;                 for (int j = 0; j < 4; ++j) {
;                     const float v0 = acc[ai][0][0][n][j], v1 = acc[ai][0][1][n][j], v2 = acc[ai][0][2][n][j], v3 = acc[ai][0][3][n][j];
;                     const float g0 = acc[ai][1][0][n][j], g1 = acc[ai][1][1][n][j], g2 = acc[ai][1][2][n][j], g3 = acc[ai][1][3][n][j];
;                     const float pv3 = dpp_upd<0x111>(h3v[j], v3), pv2 = dpp_upd<0x111>(h2v[j], v2), pg3 = dpp_upd<0x111>(h3g[j], g3), pg2 = dpp_upd<0x111>(h2g[j], g2);
;                     const float hv0 = bvv[j] + w2v[j] * v0 + w1v[j] * pv3 + w0v[j] * pv2, hv1 = bvv[j] + w2v[j] * v1 + w1v[j] * v0 + w0v[j] * pv3;
;                     const float hv2 = bvv[j] + w2v[j] * v2 + w1v[j] * v1 + w0v[j] * v0, hv3 = bvv[j] + w2v[j] * v3 + w1v[j] * v2 + w0v[j] * v1;
;                     const float hg0 = bvg[j] + w2g[j] * g0 + w1g[j] * pg3 + w0g[j] * pg2, hg1 = bvg[j] + w2g[j] * g1 + w1g[j] * g0 + w0g[j] * pg3;
;                     const float hg2 = bvg[j] + w2g[j] * g2 + w1g[j] * g1 + w0g[j] * g0, hg3 = bvg[j] + w2g[j] * g3 + w1g[j] * g2 + w0g[j] * g1;
;                     o[0][j] = hg0 * sigmoidf_(hg0) * hv0; o[1][j] = hg1 * sigmoidf_(hg1) * hv1; o[2][j] = hg2 * sigmoidf_(hg2) * hv2; o[3][j] = hg3 * sigmoidf_(hg3) * hv3; }
; #pragma unroll
;                 for (int m = 0; m < 4; ++m) { u32x2 w; w.x = cvt_pk_bf16(o[m][0], o[m][1]); w.y = cvt_pk_bf16(o[m][2], o[m][3]);
;                     *(u32x2*)(Aout + (size_t)(row0 + ai * 128 + m) * FH + hc0 + 4 * n) = w; } } }
.LBB0_1936:
	s_or_b64 exec, exec, s[34:35]
	s_waitcnt lgkmcnt(0)
	v_mov_b32_dpp v64, v8 row_shr:1 row_mask:0xf bank_mask:0xf
	v_mov_b32_dpp v65, v9 row_shr:1 row_mask:0xf bank_mask:0xf
	v_pk_fma_f32 v[44:45], v[24:25], v[120:121], v[124:125]
	v_mov_b32_dpp v40, v0 row_shr:1 row_mask:0xf bank_mask:0xf
	v_mov_b32_dpp v41, v1 row_shr:1 row_mask:0xf bank_mask:0xf
	v_pk_fma_f32 v[44:45], v[116:117], v[64:65], v[44:45]
	v_mov_b32_dpp v32, v20 row_shr:1 row_mask:0xf bank_mask:0xf
	v_pk_fma_f32 v[40:41], v[112:113], v[40:41], v[44:45]
	v_mov_b32_dpp v33, v21 row_shr:1 row_mask:0xf bank_mask:0xf
	v_exp_f32_e32 v44, v40
	v_exp_f32_e32 v45, v41
	v_pk_fma_f32 v[46:47], v[28:29], v[104:105], v[108:109]
	v_mov_b32_dpp v36, v12 row_shr:1 row_mask:0xf bank_mask:0xf
	v_pk_add_f32 v[44:45], v[44:45], 1.0 op_sel_hi:[1,0]
	v_rcp_f32_e32 v44, v44
	v_rcp_f32_e32 v45, v45
	v_mov_b32_dpp v37, v13 row_shr:1 row_mask:0xf bank_mask:0xf
	v_pk_fma_f32 v[46:47], v[100:101], v[32:33], v[46:47]
	v_mov_b32_dpp v66, v10 row_shr:1 row_mask:0xf bank_mask:0xf
	v_pk_fma_f32 v[36:37], v[96:97], v[36:37], v[46:47]
	v_pk_mul_f32 v[40:41], v[40:41], v[44:45]
	v_mov_b32_dpp v67, v11 row_shr:1 row_mask:0xf bank_mask:0xf
	v_pk_mul_f32 v[36:37], v[36:37], v[40:41]
	v_pk_fma_f32 v[40:41], v[26:27], v[122:123], v[126:127]
	v_mov_b32_dpp v42, v2 row_shr:1 row_mask:0xf bank_mask:0xf
	v_mov_b32_dpp v43, v3 row_shr:1 row_mask:0xf bank_mask:0xf
	v_pk_fma_f32 v[40:41], v[118:119], v[66:67], v[40:41]
	v_cvt_pk_bf16_f32 v36, v36, v37
	v_pk_fma_f32 v[40:41], v[114:115], v[42:43], v[40:41]
	v_mov_b32_dpp v34, v22 row_shr:1 row_mask:0xf bank_mask:0xf
	v_exp_f32_e32 v42, v40
	v_exp_f32_e32 v43, v41
	v_mov_b32_dpp v35, v23 row_shr:1 row_mask:0xf bank_mask:0xf
	v_pk_add_f32 v[42:43], v[42:43], 1.0 op_sel_hi:[1,0]
	v_rcp_f32_e32 v42, v42
	v_rcp_f32_e32 v43, v43
	v_pk_fma_f32 v[44:45], v[30:31], v[106:107], v[110:111]
	v_mov_b32_dpp v38, v14 row_shr:1 row_mask:0xf bank_mask:0xf
	v_mov_b32_dpp v39, v15 row_shr:1 row_mask:0xf bank_mask:0xf
	v_pk_fma_f32 v[44:45], v[102:103], v[34:35], v[44:45]
	v_pk_mul_f32 v[40:41], v[40:41], v[42:43]
	v_pk_fma_f32 v[38:39], v[98:99], v[38:39], v[44:45]
	v_pk_fma_f32 v[8:9], v[8:9], v[120:121], v[124:125]
	v_pk_mul_f32 v[38:39], v[38:39], v[40:41]
	v_pk_fma_f32 v[20:21], v[20:21], v[104:105], v[108:109]
	v_cvt_pk_bf16_f32 v37, v38, v39
	v_pk_fma_f32 v[38:39], v[4:5], v[120:121], v[124:125]
	v_mov_b32_e32 v146, v36
	v_mov_b32_e32 v147, v37
	global_store_dwordx4 v[132:133], v[144:147], off
	v_pk_fma_f32 v[38:39], v[24:25], v[116:117], v[38:39]
	s_and_b64 vcc, exec, s[10:11]
	v_pk_fma_f32 v[38:39], v[112:113], v[64:65], v[38:39]
	s_mov_b32 s35, s24
	v_exp_f32_e32 v36, v38
	v_exp_f32_e32 v37, v39
	s_mov_b32 s34, s26
	s_mov_b64 s[38:39], s[30:31]
	v_pk_add_f32 v[36:37], v[36:37], 1.0 op_sel_hi:[1,0]
	v_rcp_f32_e32 v36, v36
	v_rcp_f32_e32 v37, v37
	v_pk_fma_f32 v[40:41], v[16:17], v[104:105], v[108:109]
	s_mov_b64 s[36:37], s[28:29]
	v_pk_fma_f32 v[40:41], v[28:29], v[100:101], v[40:41]
	v_pk_mul_f32 v[36:37], v[38:39], v[36:37]
	v_pk_fma_f32 v[32:33], v[96:97], v[32:33], v[40:41]
	v_pk_fma_f32 v[40:41], v[18:19], v[106:107], v[110:111]
	v_pk_mul_f32 v[32:33], v[32:33], v[36:37]
	v_pk_fma_f32 v[36:37], v[6:7], v[122:123], v[126:127]
	v_cvt_pk_bf16_f32 v32, v32, v33
	v_pk_fma_f32 v[36:37], v[26:27], v[118:119], v[36:37]
	v_pk_fma_f32 v[40:41], v[30:31], v[102:103], v[40:41]
	v_pk_fma_f32 v[36:37], v[114:115], v[66:67], v[36:37]
	v_pk_fma_f32 v[34:35], v[98:99], v[34:35], v[40:41]
	v_exp_f32_e32 v38, v36
	v_exp_f32_e32 v39, v37
	s_nop 0
	v_pk_add_f32 v[38:39], v[38:39], 1.0 op_sel_hi:[1,0]
	v_rcp_f32_e32 v38, v38
	v_rcp_f32_e32 v39, v39
	s_nop 0
	v_pk_mul_f32 v[36:37], v[36:37], v[38:39]
	s_nop 0
	v_pk_mul_f32 v[34:35], v[34:35], v[36:37]
	s_nop 0
	v_cvt_pk_bf16_f32 v33, v34, v35
	v_pk_fma_f32 v[34:35], v[0:1], v[120:121], v[124:125]
	v_mov_b32_e32 v156, v32
	v_mov_b32_e32 v157, v33
	global_store_dwordx4 v[128:129], v[154:157], off
	v_pk_fma_f32 v[34:35], v[4:5], v[116:117], v[34:35]
	v_pk_fma_f32 v[0:1], v[0:1], v[116:117], v[8:9]
	v_pk_fma_f32 v[24:25], v[24:25], v[112:113], v[34:35]
	v_pk_fma_f32 v[0:1], v[4:5], v[112:113], v[0:1]
	v_exp_f32_e32 v32, v24
	v_exp_f32_e32 v33, v25
	v_exp_f32_e32 v8, v0
	v_pk_add_f32 v[32:33], v[32:33], 1.0 op_sel_hi:[1,0]
	v_rcp_f32_e32 v32, v32
	v_rcp_f32_e32 v33, v33
	v_pk_fma_f32 v[34:35], v[12:13], v[104:105], v[108:109]
	v_pk_fma_f32 v[4:5], v[10:11], v[122:123], v[126:127]
	v_pk_fma_f32 v[34:35], v[16:17], v[100:101], v[34:35]
	v_pk_mul_f32 v[24:25], v[24:25], v[32:33]
	v_pk_fma_f32 v[28:29], v[28:29], v[96:97], v[34:35]
	v_pk_mul_f32 v[24:25], v[28:29], v[24:25]
	v_pk_fma_f32 v[28:29], v[2:3], v[122:123], v[126:127]
	v_pk_fma_f32 v[2:3], v[2:3], v[118:119], v[4:5]
	v_pk_fma_f32 v[28:29], v[6:7], v[118:119], v[28:29]
	v_pk_fma_f32 v[2:3], v[6:7], v[114:115], v[2:3]
	v_pk_fma_f32 v[26:27], v[26:27], v[114:115], v[28:29]
	v_exp_f32_e32 v28, v26
	v_exp_f32_e32 v29, v27
	v_exp_f32_e32 v9, v1
	v_exp_f32_e32 v4, v2
	v_exp_f32_e32 v5, v3
	v_cvt_pk_bf16_f32 v24, v24, v25
	v_pk_add_f32 v[28:29], v[28:29], 1.0 op_sel_hi:[1,0]
	v_pk_add_f32 v[8:9], v[8:9], 1.0 op_sel_hi:[1,0]
	v_pk_add_f32 v[4:5], v[4:5], 1.0 op_sel_hi:[1,0]
	v_rcp_f32_e32 v28, v28
	v_rcp_f32_e32 v29, v29
	v_rcp_f32_e32 v8, v8
	v_rcp_f32_e32 v9, v9
	v_rcp_f32_e32 v4, v4
	v_rcp_f32_e32 v5, v5
	v_pk_fma_f32 v[32:33], v[14:15], v[106:107], v[110:111]
	v_pk_fma_f32 v[10:11], v[22:23], v[106:107], v[110:111]
	v_pk_fma_f32 v[32:33], v[18:19], v[102:103], v[32:33]
	v_pk_fma_f32 v[12:13], v[12:13], v[100:101], v[20:21]
	v_pk_fma_f32 v[6:7], v[14:15], v[102:103], v[10:11]
	v_pk_fma_f32 v[30:31], v[30:31], v[98:99], v[32:33]
	v_pk_mul_f32 v[26:27], v[26:27], v[28:29]
	v_pk_fma_f32 v[12:13], v[16:17], v[96:97], v[12:13]
	v_pk_mul_f32 v[0:1], v[0:1], v[8:9]
	v_pk_fma_f32 v[6:7], v[18:19], v[98:99], v[6:7]
	v_pk_mul_f32 v[2:3], v[2:3], v[4:5]
	v_pk_mul_f32 v[26:27], v[30:31], v[26:27]
	v_pk_mul_f32 v[0:1], v[12:13], v[0:1]
	v_pk_mul_f32 v[2:3], v[6:7], v[2:3]
	v_cvt_pk_bf16_f32 v25, v26, v27
	v_cvt_pk_bf16_f32 v0, v0, v1
	v_cvt_pk_bf16_f32 v1, v2, v3
	v_mov_b32_e32 v200, v24
	v_mov_b32_e32 v201, v25
	global_store_dwordx4 v[88:89], v[198:201], off
	v_mov_b32_e32 v150, v0
	v_mov_b32_e32 v151, v1
	global_store_dwordx4 v[82:83], v[148:151], off
	s_cbranch_vccnz .LBB0_1955

; #define LAS __attribute__((address_space(3)))
; __device__ __forceinline__ float sigmoidf_(float x) { return __builtin_amdgcn_rcpf(1.0f + __expf(-x)); }
;     __device__ __forceinline__ void operator()(AccRef acc, const Unit& u, int wr, int wc, int fr, int fq) const {
;     ...
;                 f32x4 h2v = (f32x4){0.f, 0.f, 0.f, 0.f}, h3v = h2v, h2g = h2v, h3g = h2v;
;                 const int pb = ai * 2 + wr - 1;
;                 if (pb >= 0 && fr == 0) { const LAS float* xp = xch + (pb * 2) * 256 + clb + 4 * n;
;                     h2v = *(const LAS f32x4*)(xp); h3v = *(const LAS f32x4*)(xp + 256); h2g = *(const LAS f32x4*)(xp + 128); h3g = *(const LAS f32x4*)(xp + 256 + 128); }
;                 float o[4][4];
; #pragma unroll
;                 for (int j = 0; j < 4; ++j) {
;                     const float v0 = acc[ai][0][0][n][j], v1 = acc[ai][0][1][n][j], v2 = acc[ai][0][2][n][j], v3 = acc[ai][0][3][n][j];
;                     const float g0 = acc[ai][1][0][n][j], g1 = acc[ai][1][1][n][j], g2 = acc[ai][1][2][n][j], g3 = acc[ai][1][3][n][j];
;                     const float pv3 = dpp_upd<0x111>(h3v[j], v3), pv2 = dpp_upd<0x111>(h2v[j], v2), pg3 = dpp_upd<0x111>(h3g[j], g3), pg2 = dpp_upd<0x111>(h2g[j], g2);
;                     const float hv0 = bvv[j] + w2v[j] * v0 + w1v[j] * pv3 + w0v[j] * pv2, hv1 = bvv[j] + w2v[j] * v1 + w1v[j] * v0 + w0v[j] * pv3;
;                     const float hv2 = bvv[j] + w2v[j] * v2 + w1v[j] * v1 + w0v[j] * v0, hv3 = bvv[j] + w2v[j] * v3 + w1v[j] * v2 + w0v[j] * v1;
;                     const float hg0 = bvg[j] + w2g[j] * g0 + w1g[j] * pg3 + w0g[j] * pg2, hg1 = bvg[j] + w2g[j] * g1 + w1g[j] * g0 + w0g[j] * pg3;
;                     const float hg2 = bvg[j] + w2g[j] * g2 + w1g[j] * g1 + w0g[j] * g0, hg3 = bvg[j] + w2g[j] * g3 + w1g[j] * g2 + w0g[j] * g1;
;                     o[0][j] = hg0 * sigmoidf_(hg0) * hv0; o[1][j] = hg1 * sigmoidf_(hg1) * hv1; o[2][j] = hg2 * sigmoidf_(hg2) * hv2; o[3][j] = hg3 * sigmoidf_(hg3) * hv3; }
; #pragma unroll
;                 for (int m = 0; m < 4; ++m) { u32x2 w; w.x = cvt_pk_bf16(o[m][0], o[m][1]); w.y = cvt_pk_bf16(o[m][2], o[m][3]);
;                     *(u32x2*)(Aout + (size_t)(row0 + ai * 128 + m) * FH + hc0 + 4 * n) = w; } } }
.LBB0_1947:
	s_or_b64 exec, exec, s[40:41]
	v_pk_fma_f32 v[246:247], v[152:153], v[184:185], v[188:189]
	v_mov_b32_dpp v206, v128 row_shr:1 row_mask:0xf bank_mask:0xf
	v_mov_b32_dpp v207, v129 row_shr:1 row_mask:0xf bank_mask:0xf
	v_pk_fma_f32 v[246:247], v[180:181], v[198:199], v[246:247]
	v_mov_b32_dpp v194, v148 row_shr:1 row_mask:0xf bank_mask:0xf
	v_pk_fma_f32 v[206:207], v[176:177], v[206:207], v[246:247]
	v_mov_b32_dpp v195, v149 row_shr:1 row_mask:0xf bank_mask:0xf
	v_exp_f32_e32 v246, v206
	v_exp_f32_e32 v247, v207
	v_pk_fma_f32 v[248:249], v[156:157], v[168:169], v[172:173]
	v_pk_add_f32 v[246:247], v[246:247], 1.0 op_sel_hi:[1,0]
	v_rcp_f32_e32 v246, v246
	v_rcp_f32_e32 v247, v247
	v_mov_b32_dpp v202, v136 row_shr:1 row_mask:0xf bank_mask:0xf
	v_mov_b32_dpp v203, v137 row_shr:1 row_mask:0xf bank_mask:0xf
	v_pk_fma_f32 v[248:249], v[164:165], v[194:195], v[248:249]
	v_pk_mul_f32 v[206:207], v[206:207], v[246:247]
	v_pk_fma_f32 v[202:203], v[160:161], v[202:203], v[248:249]
	v_mov_b32_dpp v200, v142 row_shr:1 row_mask:0xf bank_mask:0xf
	v_mov_b32_dpp v201, v143 row_shr:1 row_mask:0xf bank_mask:0xf
	v_pk_mul_f32 v[202:203], v[202:203], v[206:207]
	v_pk_fma_f32 v[206:207], v[154:155], v[186:187], v[190:191]
	v_mov_b32_dpp v208, v130 row_shr:1 row_mask:0xf bank_mask:0xf
	v_mov_b32_dpp v209, v131 row_shr:1 row_mask:0xf bank_mask:0xf
	v_pk_fma_f32 v[206:207], v[182:183], v[200:201], v[206:207]
	v_mov_b32_dpp v196, v150 row_shr:1 row_mask:0xf bank_mask:0xf
	v_pk_fma_f32 v[206:207], v[178:179], v[208:209], v[206:207]
	v_mov_b32_dpp v197, v151 row_shr:1 row_mask:0xf bank_mask:0xf
	v_exp_f32_e32 v193, v206
	v_exp_f32_e32 v209, v207
	v_cvt_pk_bf16_f32 v208, v202, v203
	v_add_f32_e32 v193, 1.0, v193
	v_rcp_f32_e32 v202, v193
	v_add_f32_e32 v193, 1.0, v209
	v_rcp_f32_e32 v203, v193
	v_pk_fma_f32 v[246:247], v[158:159], v[170:171], v[174:175]
	v_mov_b32_dpp v204, v138 row_shr:1 row_mask:0xf bank_mask:0xf
	v_mov_b32_dpp v205, v139 row_shr:1 row_mask:0xf bank_mask:0xf
	v_pk_fma_f32 v[246:247], v[166:167], v[196:197], v[246:247]
	v_pk_mul_f32 v[202:203], v[206:207], v[202:203]
	v_pk_fma_f32 v[204:205], v[162:163], v[204:205], v[246:247]
	v_lshl_add_u32 v245, s34, 8, v235
	v_pk_mul_f32 v[202:203], v[204:205], v[202:203]
	v_lshlrev_b64 v[204:205], 1, v[232:233]
	v_pk_fma_f32 v[232:233], v[132:133], v[184:185], v[188:189]
	v_mov_b64_e32 v[206:207], s[60:61]
	v_pk_fma_f32 v[232:233], v[152:153], v[180:181], v[232:233]
	v_cvt_pk_bf16_f32 v209, v202, v203
	v_pk_fma_f32 v[198:199], v[176:177], v[198:199], v[232:233]
	v_mad_i64_i32 v[202:203], s[34:35], v245, s63, v[206:207]
	v_exp_f32_e32 v193, v198
	v_exp_f32_e32 v232, v199
	v_lshl_add_u64 v[202:203], v[202:203], 0, v[204:205]
	v_add_f32_e32 v193, 1.0, v193
	v_mov_b32_e32 v246, v208
	v_mov_b32_e32 v247, v209
	v_rcp_f32_e32 v208, v193
	v_add_f32_e32 v193, 1.0, v232
	v_rcp_f32_e32 v209, v193
	v_pk_fma_f32 v[232:233], v[144:145], v[168:169], v[172:173]
	v_pk_fma_f32 v[140:141], v[140:141], v[184:185], v[188:189]
	v_pk_fma_f32 v[232:233], v[156:157], v[164:165], v[232:233]
	v_pk_mul_f32 v[198:199], v[198:199], v[208:209]
	v_pk_fma_f32 v[194:195], v[160:161], v[194:195], v[232:233]
	v_pk_fma_f32 v[208:209], v[146:147], v[170:171], v[174:175]
	v_pk_mul_f32 v[194:195], v[194:195], v[198:199]
	v_pk_fma_f32 v[198:199], v[134:135], v[186:187], v[190:191]
	v_pk_fma_f32 v[208:209], v[158:159], v[166:167], v[208:209]
	v_pk_fma_f32 v[198:199], v[154:155], v[182:183], v[198:199]
	v_pk_fma_f32 v[196:197], v[162:163], v[196:197], v[208:209]
	v_pk_fma_f32 v[198:199], v[178:179], v[200:201], v[198:199]
	v_cvt_pk_bf16_f32 v194, v194, v195
	v_exp_f32_e32 v200, v198
	v_exp_f32_e32 v201, v199
	v_pk_fma_f32 v[148:149], v[148:149], v[168:169], v[172:173]
	v_pk_add_f32 v[200:201], v[200:201], 1.0 op_sel_hi:[1,0]
	v_rcp_f32_e32 v200, v200
	v_rcp_f32_e32 v201, v201
	v_or_b32_e32 v193, 1, v245
	v_pk_mul_f32 v[198:199], v[198:199], v[200:201]
	s_nop 0
	v_pk_mul_f32 v[196:197], v[196:197], v[198:199]
	v_pk_fma_f32 v[198:199], v[128:129], v[184:185], v[188:189]
	v_cvt_pk_bf16_f32 v195, v196, v197
	v_pk_fma_f32 v[198:199], v[132:133], v[180:181], v[198:199]
	v_mad_i64_i32 v[196:197], s[34:35], v193, s63, v[206:207]
	v_pk_fma_f32 v[152:153], v[152:153], v[176:177], v[198:199]
	v_lshl_add_u64 v[196:197], v[196:197], 0, v[204:205]
	v_exp_f32_e32 v193, v152
	v_exp_f32_e32 v198, v153
	v_mov_b32_e32 v248, v194
	v_mov_b32_e32 v249, v195
	v_add_f32_e32 v193, 1.0, v193
	v_rcp_f32_e32 v194, v193
	v_add_f32_e32 v193, 1.0, v198
	v_rcp_f32_e32 v195, v193
	v_pk_fma_f32 v[198:199], v[136:137], v[168:169], v[172:173]
	v_pk_fma_f32 v[128:129], v[128:129], v[180:181], v[140:141]
	v_pk_fma_f32 v[198:199], v[144:145], v[164:165], v[198:199]
	v_pk_fma_f32 v[128:129], v[132:133], v[176:177], v[128:129]
	v_pk_fma_f32 v[156:157], v[156:157], v[160:161], v[198:199]
	v_pk_mul_f32 v[152:153], v[152:153], v[194:195]
	v_pk_mul_f32 v[152:153], v[156:157], v[152:153]
	v_pk_fma_f32 v[156:157], v[130:131], v[186:187], v[190:191]
	v_exp_f32_e32 v140, v128
	v_pk_fma_f32 v[132:133], v[142:143], v[186:187], v[190:191]
	v_pk_fma_f32 v[156:157], v[134:135], v[182:183], v[156:157]
	v_pk_fma_f32 v[130:131], v[130:131], v[182:183], v[132:133]
	v_pk_fma_f32 v[154:155], v[154:155], v[178:179], v[156:157]
	v_pk_fma_f32 v[130:131], v[134:135], v[178:179], v[130:131]
	v_exp_f32_e32 v157, v154
	v_exp_f32_e32 v141, v129
	v_exp_f32_e32 v132, v130
	v_exp_f32_e32 v133, v131
	v_exp_f32_e32 v193, v155
	v_pk_add_f32 v[140:141], v[140:141], 1.0 op_sel_hi:[1,0]
	v_pk_add_f32 v[132:133], v[132:133], 1.0 op_sel_hi:[1,0]
	v_cvt_pk_bf16_f32 v156, v152, v153
	v_add_f32_e32 v152, 1.0, v157
; #define LAS __attribute__((address_space(3)))
; __device__ __forceinline__ float sigmoidf_(float x) { return __builtin_amdgcn_rcpf(1.0f + __expf(-x)); }
;     __device__ __forceinline__ void operator()(AccRef acc, const Unit& u, int wr, int wc, int fr, int fq) const {
;     ...
;                 f32x4 h2v = (f32x4){0.f, 0.f, 0.f, 0.f}, h3v = h2v, h2g = h2v, h3g = h2v;
;                 const int pb = ai * 2 + wr - 1;
;                 if (pb >= 0 && fr == 0) { const LAS float* xp = xch + (pb * 2) * 256 + clb + 4 * n;
;                     h2v = *(const LAS f32x4*)(xp); h3v = *(const LAS f32x4*)(xp + 256); h2g = *(const LAS f32x4*)(xp + 128); h3g = *(const LAS f32x4*)(xp + 256 + 128); }
;                 float o[4][4];
; #pragma unroll
;                 for (int j = 0; j < 4; ++j) {
;                     const float v0 = acc[ai][0][0][n][j], v1 = acc[ai][0][1][n][j], v2 = acc[ai][0][2][n][j], v3 = acc[ai][0][3][n][j];
;                     const float g0 = acc[ai][1][0][n][j], g1 = acc[ai][1][1][n][j], g2 = acc[ai][1][2][n][j], g3 = acc[ai][1][3][n][j];
;                     const float pv3 = dpp_upd<0x111>(h3v[j], v3), pv2 = dpp_upd<0x111>(h2v[j], v2), pg3 = dpp_upd<0x111>(h3g[j], g3), pg2 = dpp_upd<0x111>(h2g[j], g2);
;                     const float hv0 = bvv[j] + w2v[j] * v0 + w1v[j] * pv3 + w0v[j] * pv2, hv1 = bvv[j] + w2v[j] * v1 + w1v[j] * v0 + w0v[j] * pv3;
;                     const float hv2 = bvv[j] + w2v[j] * v2 + w1v[j] * v1 + w0v[j] * v0, hv3 = bvv[j] + w2v[j] * v3 + w1v[j] * v2 + w0v[j] * v1;
;                     const float hg0 = bvg[j] + w2g[j] * g0 + w1g[j] * pg3 + w0g[j] * pg2, hg1 = bvg[j] + w2g[j] * g1 + w1g[j] * g0 + w0g[j] * pg3;
;                     const float hg2 = bvg[j] + w2g[j] * g2 + w1g[j] * g1 + w0g[j] * g0, hg3 = bvg[j] + w2g[j] * g3 + w1g[j] * g2 + w0g[j] * g1;
;                     o[0][j] = hg0 * sigmoidf_(hg0) * hv0; o[1][j] = hg1 * sigmoidf_(hg1) * hv1; o[2][j] = hg2 * sigmoidf_(hg2) * hv2; o[3][j] = hg3 * sigmoidf_(hg3) * hv3; }
; #pragma unroll
;                 for (int m = 0; m < 4; ++m) { u32x2 w; w.x = cvt_pk_bf16(o[m][0], o[m][1]); w.y = cvt_pk_bf16(o[m][2], o[m][3]);
;                     *(u32x2*)(Aout + (size_t)(row0 + ai * 128 + m) * FH + hc0 + 4 * n) = w; } } }
	v_add_f32_e32 v153, 1.0, v193
	v_rcp_f32_e32 v140, v140
	v_rcp_f32_e32 v141, v141
	v_rcp_f32_e32 v132, v132
	v_rcp_f32_e32 v133, v133
	v_rcp_f32_e32 v152, v152
	v_rcp_f32_e32 v153, v153
	v_pk_fma_f32 v[142:143], v[150:151], v[170:171], v[174:175]
	v_pk_fma_f32 v[194:195], v[138:139], v[170:171], v[174:175]
	v_pk_fma_f32 v[136:137], v[136:137], v[164:165], v[148:149]
	v_pk_fma_f32 v[134:135], v[138:139], v[166:167], v[142:143]
	v_pk_fma_f32 v[194:195], v[146:147], v[166:167], v[194:195]
	v_pk_fma_f32 v[136:137], v[144:145], v[160:161], v[136:137]
	v_pk_mul_f32 v[128:129], v[128:129], v[140:141]
	v_pk_fma_f32 v[134:135], v[146:147], v[162:163], v[134:135]
	v_pk_mul_f32 v[130:131], v[130:131], v[132:133]
	v_pk_fma_f32 v[158:159], v[158:159], v[162:163], v[194:195]
	v_pk_mul_f32 v[152:153], v[154:155], v[152:153]
	v_pk_mul_f32 v[128:129], v[136:137], v[128:129]
	v_pk_mul_f32 v[130:131], v[134:135], v[130:131]
	v_pk_mul_f32 v[152:153], v[158:159], v[152:153]
	v_cvt_pk_bf16_f32 v128, v128, v129
	v_cvt_pk_bf16_f32 v129, v130, v131
	v_or_b32_e32 v130, 3, v245
	v_cvt_pk_bf16_f32 v157, v152, v153
	v_or_b32_e32 v152, 2, v245
	v_mad_i64_i32 v[130:131], s[34:35], v130, s63, v[206:207]
	v_mad_i64_i32 v[152:153], s[34:35], v152, s63, v[206:207]
	v_lshl_add_u64 v[140:141], v[130:131], 0, v[204:205]
	v_lshl_add_u64 v[152:153], v[152:153], 0, v[204:205]
	v_mov_b32_e32 v250, v128
	v_mov_b32_e32 v251, v129
	v_mov_b32_e32 v193, 0
	v_mov_b32_e32 v194, 0
	v_mov_b32_e32 v195, 0
	v_mov_b32_e32 v136, 0
	v_mov_b32_e32 v137, 0
	v_mov_b32_e32 v138, 0
	v_mov_b32_e32 v139, 0
	v_mov_b32_e32 v128, 0
	v_mov_b32_e32 v129, 0
	v_mov_b32_e32 v130, 0
	v_mov_b32_e32 v131, 0
	v_mov_b32_e32 v132, 0
	v_mov_b32_e32 v133, 0
	v_mov_b32_e32 v134, 0
	v_mov_b32_e32 v135, 0
	v_mov_b32_e32 v253, v156
	v_mov_b32_e32 v254, v157
	s_and_saveexec_b64 s[34:35], s[22:23]
	s_cbranch_execz .LBB0_1951
	ds_read_b128 v[132:135], v236 offset:2048
	ds_read_b128 v[136:139], v236 offset:2560
	ds_read_b128 v[128:131], v236 offset:3072
	ds_read_b128 v[192:195], v236 offset:3584
.LBB0_1951:
	s_or_b64 exec, exec, s[34:35]
	s_waitcnt lgkmcnt(0)
	v_mov_b32_dpp v192, v72 row_shr:1 row_mask:0xf bank_mask:0xf
	v_mov_b32_dpp v193, v73 row_shr:1 row_mask:0xf bank_mask:0xf
	v_pk_fma_f32 v[142:143], v[88:89], v[184:185], v[188:189]
	v_mov_b32_dpp v136, v64 row_shr:1 row_mask:0xf bank_mask:0xf
	v_mov_b32_dpp v137, v65 row_shr:1 row_mask:0xf bank_mask:0xf
	v_pk_fma_f32 v[142:143], v[180:181], v[192:193], v[142:143]
	v_mov_b32_dpp v128, v84 row_shr:1 row_mask:0xf bank_mask:0xf
	v_pk_fma_f32 v[136:137], v[176:177], v[136:137], v[142:143]
	v_mov_b32_dpp v129, v85 row_shr:1 row_mask:0xf bank_mask:0xf
	v_exp_f32_e32 v142, v136
	v_exp_f32_e32 v143, v137
	v_pk_fma_f32 v[144:145], v[92:93], v[168:169], v[172:173]
	v_mov_b32_dpp v132, v76 row_shr:1 row_mask:0xf bank_mask:0xf
	v_pk_add_f32 v[142:143], v[142:143], 1.0 op_sel_hi:[1,0]
	v_rcp_f32_e32 v142, v142
	v_rcp_f32_e32 v143, v143
	v_mov_b32_dpp v133, v77 row_shr:1 row_mask:0xf bank_mask:0xf
	v_pk_fma_f32 v[144:145], v[164:165], v[128:129], v[144:145]
	v_mov_b32_dpp v194, v74 row_shr:1 row_mask:0xf bank_mask:0xf
	v_pk_fma_f32 v[132:133], v[160:161], v[132:133], v[144:145]
	v_pk_mul_f32 v[136:137], v[136:137], v[142:143]
	v_mov_b32_dpp v195, v75 row_shr:1 row_mask:0xf bank_mask:0xf
	v_pk_mul_f32 v[132:133], v[132:133], v[136:137]
	v_pk_fma_f32 v[136:137], v[90:91], v[186:187], v[190:191]
	v_mov_b32_dpp v138, v66 row_shr:1 row_mask:0xf bank_mask:0xf
	v_mov_b32_dpp v139, v67 row_shr:1 row_mask:0xf bank_mask:0xf
	v_pk_fma_f32 v[136:137], v[182:183], v[194:195], v[136:137]
	v_mov_b32_dpp v130, v86 row_shr:1 row_mask:0xf bank_mask:0xf
	v_pk_fma_f32 v[136:137], v[178:179], v[138:139], v[136:137]
	v_mov_b32_dpp v131, v87 row_shr:1 row_mask:0xf bank_mask:0xf
	v_exp_f32_e32 v139, v136
	v_exp_f32_e32 v142, v137
	v_cvt_pk_bf16_f32 v138, v132, v133
	v_add_f32_e32 v132, 1.0, v139
	v_rcp_f32_e32 v132, v132
	v_add_f32_e32 v133, 1.0, v142
	v_rcp_f32_e32 v133, v133
	v_pk_fma_f32 v[142:143], v[94:95], v[170:171], v[174:175]
	v_mov_b32_dpp v134, v78 row_shr:1 row_mask:0xf bank_mask:0xf
	v_mov_b32_dpp v135, v79 row_shr:1 row_mask:0xf bank_mask:0xf
	v_pk_mul_f32 v[132:133], v[136:137], v[132:133]
	v_pk_fma_f32 v[136:137], v[68:69], v[184:185], v[188:189]
	v_pk_fma_f32 v[142:143], v[166:167], v[130:131], v[142:143]
	v_pk_fma_f32 v[136:137], v[88:89], v[180:181], v[136:137]
	v_pk_fma_f32 v[134:135], v[162:163], v[134:135], v[142:143]
	v_pk_fma_f32 v[136:137], v[176:177], v[192:193], v[136:137]
	v_add_u32_e32 v146, 0x80, v245
	v_exp_f32_e32 v142, v136
	v_exp_f32_e32 v143, v137
	v_pk_mul_f32 v[132:133], v[134:135], v[132:133]
	v_mov_b64_e32 v[134:135], s[60:61]
	v_cvt_pk_bf16_f32 v139, v132, v133
	v_mad_i64_i32 v[132:133], s[34:35], v146, s63, v[134:135]
	v_lshl_add_u64 v[132:133], v[132:133], 0, v[204:205]
	v_mov_b32_e32 v144, v138
	v_mov_b32_e32 v145, v139
	v_add_f32_e32 v138, 1.0, v142
	v_add_f32_e32 v139, 1.0, v143
	v_rcp_f32_e32 v138, v138
	v_rcp_f32_e32 v139, v139
	v_pk_fma_f32 v[142:143], v[80:81], v[168:169], v[172:173]
	v_pk_fma_f32 v[72:73], v[72:73], v[184:185], v[188:189]
	v_pk_fma_f32 v[142:143], v[92:93], v[164:165], v[142:143]
	v_pk_mul_f32 v[136:137], v[136:137], v[138:139]
	v_pk_fma_f32 v[128:129], v[160:161], v[128:129], v[142:143]
	v_pk_fma_f32 v[84:85], v[84:85], v[168:169], v[172:173]
	v_pk_mul_f32 v[128:129], v[128:129], v[136:137]
	v_pk_fma_f32 v[136:137], v[70:71], v[186:187], v[190:191]
	s_nop 0
	v_pk_fma_f32 v[136:137], v[90:91], v[182:183], v[136:137]
	s_nop 0
	v_pk_fma_f32 v[136:137], v[178:179], v[194:195], v[136:137]
	s_nop 0
	v_exp_f32_e32 v139, v136
	v_exp_f32_e32 v142, v137
; #define LAS __attribute__((address_space(3)))
; __device__ __forceinline__ float sigmoidf_(float x) { return __builtin_amdgcn_rcpf(1.0f + __expf(-x)); }
;     __device__ __forceinline__ void operator()(AccRef acc, const Unit& u, int wr, int wc, int fr, int fq) const {
;     ...
;                 f32x4 h2v = (f32x4){0.f, 0.f, 0.f, 0.f}, h3v = h2v, h2g = h2v, h3g = h2v;
;                 const int pb = ai * 2 + wr - 1;
;                 if (pb >= 0 && fr == 0) { const LAS float* xp = xch + (pb * 2) * 256 + clb + 4 * n;
;                     h2v = *(const LAS f32x4*)(xp); h3v = *(const LAS f32x4*)(xp + 256); h2g = *(const LAS f32x4*)(xp + 128); h3g = *(const LAS f32x4*)(xp + 256 + 128); }
;                 float o[4][4];
; #pragma unroll
;                 for (int j = 0; j < 4; ++j) {
;                     const float v0 = acc[ai][0][0][n][j], v1 = acc[ai][0][1][n][j], v2 = acc[ai][0][2][n][j], v3 = acc[ai][0][3][n][j];
;                     const float g0 = acc[ai][1][0][n][j], g1 = acc[ai][1][1][n][j], g2 = acc[ai][1][2][n][j], g3 = acc[ai][1][3][n][j];
;                     const float pv3 = dpp_upd<0x111>(h3v[j], v3), pv2 = dpp_upd<0x111>(h2v[j], v2), pg3 = dpp_upd<0x111>(h3g[j], g3), pg2 = dpp_upd<0x111>(h2g[j], g2);
;                     const float hv0 = bvv[j] + w2v[j] * v0 + w1v[j] * pv3 + w0v[j] * pv2, hv1 = bvv[j] + w2v[j] * v1 + w1v[j] * v0 + w0v[j] * pv3;
;                     const float hv2 = bvv[j] + w2v[j] * v2 + w1v[j] * v1 + w0v[j] * v0, hv3 = bvv[j] + w2v[j] * v3 + w1v[j] * v2 + w0v[j] * v1;
;                     const float hg0 = bvg[j] + w2g[j] * g0 + w1g[j] * pg3 + w0g[j] * pg2, hg1 = bvg[j] + w2g[j] * g1 + w1g[j] * g0 + w0g[j] * pg3;
;                     const float hg2 = bvg[j] + w2g[j] * g2 + w1g[j] * g1 + w0g[j] * g0, hg3 = bvg[j] + w2g[j] * g3 + w1g[j] * g2 + w0g[j] * g1;
;                     o[0][j] = hg0 * sigmoidf_(hg0) * hv0; o[1][j] = hg1 * sigmoidf_(hg1) * hv1; o[2][j] = hg2 * sigmoidf_(hg2) * hv2; o[3][j] = hg3 * sigmoidf_(hg3) * hv3; }
; #pragma unroll
;                 for (int m = 0; m < 4; ++m) { u32x2 w; w.x = cvt_pk_bf16(o[m][0], o[m][1]); w.y = cvt_pk_bf16(o[m][2], o[m][3]);
;                     *(u32x2*)(Aout + (size_t)(row0 + ai * 128 + m) * FH + hc0 + 4 * n) = w; } } }
	v_cvt_pk_bf16_f32 v138, v128, v129
	v_add_f32_e32 v128, 1.0, v139
	v_rcp_f32_e32 v128, v128
	v_add_f32_e32 v129, 1.0, v142
	v_rcp_f32_e32 v129, v129
	v_pk_fma_f32 v[142:143], v[82:83], v[170:171], v[174:175]
	v_pk_mul_f32 v[128:129], v[136:137], v[128:129]
	v_pk_fma_f32 v[142:143], v[94:95], v[166:167], v[142:143]
	v_pk_fma_f32 v[136:137], v[76:77], v[168:169], v[172:173]
	v_pk_fma_f32 v[130:131], v[162:163], v[130:131], v[142:143]
	v_pk_fma_f32 v[136:137], v[80:81], v[164:165], v[136:137]
	v_pk_mul_f32 v[128:129], v[130:131], v[128:129]
	v_pk_fma_f32 v[130:131], v[64:65], v[184:185], v[188:189]
	v_pk_fma_f32 v[64:65], v[64:65], v[180:181], v[72:73]
	v_pk_fma_f32 v[130:131], v[68:69], v[180:181], v[130:131]
	v_pk_fma_f32 v[64:65], v[68:69], v[176:177], v[64:65]
	v_pk_fma_f32 v[88:89], v[88:89], v[176:177], v[130:131]
	v_pk_fma_f32 v[92:93], v[92:93], v[160:161], v[136:137]
	v_exp_f32_e32 v130, v88
	v_exp_f32_e32 v131, v89
	v_exp_f32_e32 v72, v64
	v_pk_add_f32 v[130:131], v[130:131], 1.0 op_sel_hi:[1,0]
	v_rcp_f32_e32 v130, v130
	v_rcp_f32_e32 v131, v131
	v_pk_fma_f32 v[68:69], v[74:75], v[186:187], v[190:191]
	v_exp_f32_e32 v73, v65
	v_pk_mul_f32 v[88:89], v[88:89], v[130:131]
	v_pk_mul_f32 v[88:89], v[92:93], v[88:89]
	v_pk_fma_f32 v[92:93], v[66:67], v[186:187], v[190:191]
	v_pk_fma_f32 v[66:67], v[66:67], v[182:183], v[68:69]
	v_pk_fma_f32 v[92:93], v[70:71], v[182:183], v[92:93]
	v_pk_fma_f32 v[66:67], v[70:71], v[178:179], v[66:67]
	v_pk_fma_f32 v[90:91], v[90:91], v[178:179], v[92:93]
	v_exp_f32_e32 v93, v90
	v_exp_f32_e32 v68, v66
	v_exp_f32_e32 v69, v67
	v_exp_f32_e32 v130, v91
	v_pk_add_f32 v[72:73], v[72:73], 1.0 op_sel_hi:[1,0]
	v_pk_add_f32 v[68:69], v[68:69], 1.0 op_sel_hi:[1,0]
	v_cvt_pk_bf16_f32 v92, v88, v89
	v_add_f32_e32 v88, 1.0, v93
	v_add_f32_e32 v89, 1.0, v130
	v_rcp_f32_e32 v72, v72
	v_rcp_f32_e32 v73, v73
	v_rcp_f32_e32 v68, v68
	v_rcp_f32_e32 v69, v69
	v_rcp_f32_e32 v88, v88
	v_rcp_f32_e32 v89, v89
	v_pk_fma_f32 v[74:75], v[86:87], v[170:171], v[174:175]
	v_pk_fma_f32 v[130:131], v[78:79], v[170:171], v[174:175]
	v_pk_fma_f32 v[76:77], v[76:77], v[164:165], v[84:85]
	v_pk_fma_f32 v[70:71], v[78:79], v[166:167], v[74:75]
	v_pk_fma_f32 v[130:131], v[82:83], v[166:167], v[130:131]
	v_pk_fma_f32 v[76:77], v[80:81], v[160:161], v[76:77]
	v_pk_mul_f32 v[64:65], v[64:65], v[72:73]
	v_pk_fma_f32 v[70:71], v[82:83], v[162:163], v[70:71]
	v_pk_mul_f32 v[66:67], v[66:67], v[68:69]
	v_pk_fma_f32 v[94:95], v[94:95], v[162:163], v[130:131]
	v_pk_mul_f32 v[88:89], v[90:91], v[88:89]
	v_pk_mul_f32 v[64:65], v[76:77], v[64:65]
	v_pk_mul_f32 v[66:67], v[70:71], v[66:67]
	v_pk_mul_f32 v[88:89], v[94:95], v[88:89]
	v_cvt_pk_bf16_f32 v64, v64, v65
	v_cvt_pk_bf16_f32 v65, v66, v67
	v_add_u32_e32 v66, 0x83, v245
	v_cvt_pk_bf16_f32 v139, v128, v129
	v_add_u32_e32 v128, 0x81, v245
	v_cvt_pk_bf16_f32 v93, v88, v89
	v_add_u32_e32 v88, 0x82, v245
	v_mad_i64_i32 v[66:67], s[34:35], v66, s63, v[134:135]
	v_mad_i64_i32 v[128:129], s[34:35], v128, s63, v[134:135]
	v_mad_i64_i32 v[88:89], s[34:35], v88, s63, v[134:135]
	v_lshl_add_u64 v[82:83], v[66:67], 0, v[204:205]
	v_lshl_add_u64 v[128:129], v[128:129], 0, v[204:205]
	v_lshl_add_u64 v[88:89], v[88:89], 0, v[204:205]
	v_mov_b32_e32 v148, v64
	v_mov_b32_e32 v149, v65
	v_mov_b32_e32 v64, 0
	v_mov_b32_e32 v70, 0
	v_mov_b32_e32 v71, 0
	v_mov_b32_e32 v72, 0
	v_mov_b32_e32 v73, 0
	v_mov_b32_e32 v78, 0
	v_mov_b32_e32 v79, 0
	v_mov_b32_e32 v80, 0
	v_mov_b32_e32 v81, 0
	v_mov_b32_e32 v66, 0
	v_mov_b32_e32 v67, 0
	v_mov_b32_e32 v68, 0
	v_mov_b32_e32 v69, 0
	v_mov_b32_e32 v74, 0
	v_mov_b32_e32 v75, 0
	v_mov_b32_e32 v76, 0
	v_mov_b32_e32 v77, 0
	v_mov_b32_e32 v154, v138
	v_mov_b32_e32 v155, v139
	v_mov_b32_e32 v198, v92
	v_mov_b32_e32 v199, v93
	s_and_saveexec_b64 s[34:35], s[20:21]
	s_cbranch_execz .LBB0_1953
	ds_read_b128 v[74:77], v241
	ds_read_b128 v[66:69], v240
	ds_read_b128 v[78:81], v239
	ds_read_b128 v[70:73], v238
.LBB0_1953:
	s_or_b64 exec, exec, s[34:35]
	s_waitcnt lgkmcnt(0)
	v_mov_b32_dpp v70, v44 row_shr:1 row_mask:0xf bank_mask:0xf
	v_mov_b32_dpp v71, v45 row_shr:1 row_mask:0xf bank_mask:0xf
	s_waitcnt vmcnt(0)
; #define LAS __attribute__((address_space(3)))
; __device__ __forceinline__ float sigmoidf_(float x) { return __builtin_amdgcn_rcpf(1.0f + __expf(-x)); }
;     __device__ __forceinline__ void operator()(AccRef acc, const Unit& u, int wr, int wc, int fr, int fq) const {
;     ...
;                 f32x4 h2v = (f32x4){0.f, 0.f, 0.f, 0.f}, h3v = h2v, h2g = h2v, h3g = h2v;
;                 const int pb = ai * 2 + wr - 1;
;                 if (pb >= 0 && fr == 0) { const LAS float* xp = xch + (pb * 2) * 256 + clb + 4 * n;
;                     h2v = *(const LAS f32x4*)(xp); h3v = *(const LAS f32x4*)(xp + 256); h2g = *(const LAS f32x4*)(xp + 128); h3g = *(const LAS f32x4*)(xp + 256 + 128); }
;                 float o[4][4];
; #pragma unroll
;                 for (int j = 0; j < 4; ++j) {
;                     const float v0 = acc[ai][0][0][n][j], v1 = acc[ai][0][1][n][j], v2 = acc[ai][0][2][n][j], v3 = acc[ai][0][3][n][j];
;                     const float g0 = acc[ai][1][0][n][j], g1 = acc[ai][1][1][n][j], g2 = acc[ai][1][2][n][j], g3 = acc[ai][1][3][n][j];
;                     const float pv3 = dpp_upd<0x111>(h3v[j], v3), pv2 = dpp_upd<0x111>(h2v[j], v2), pg3 = dpp_upd<0x111>(h3g[j], g3), pg2 = dpp_upd<0x111>(h2g[j], g2);
;                     const float hv0 = bvv[j] + w2v[j] * v0 + w1v[j] * pv3 + w0v[j] * pv2, hv1 = bvv[j] + w2v[j] * v1 + w1v[j] * v0 + w0v[j] * pv3;
;                     const float hv2 = bvv[j] + w2v[j] * v2 + w1v[j] * v1 + w0v[j] * v0, hv3 = bvv[j] + w2v[j] * v3 + w1v[j] * v2 + w0v[j] * v1;
;                     const float hg0 = bvg[j] + w2g[j] * g0 + w1g[j] * pg3 + w0g[j] * pg2, hg1 = bvg[j] + w2g[j] * g1 + w1g[j] * g0 + w0g[j] * pg3;
;                     const float hg2 = bvg[j] + w2g[j] * g2 + w1g[j] * g1 + w0g[j] * g0, hg3 = bvg[j] + w2g[j] * g3 + w1g[j] * g2 + w0g[j] * g1;
;                     o[0][j] = hg0 * sigmoidf_(hg0) * hv0; o[1][j] = hg1 * sigmoidf_(hg1) * hv1; o[2][j] = hg2 * sigmoidf_(hg2) * hv2; o[3][j] = hg3 * sigmoidf_(hg3) * hv3; }
; #pragma unroll
;                 for (int m = 0; m < 4; ++m) { u32x2 w; w.x = cvt_pk_bf16(o[m][0], o[m][1]); w.y = cvt_pk_bf16(o[m][2], o[m][3]);
;                     *(u32x2*)(Aout + (size_t)(row0 + ai * 128 + m) * FH + hc0 + 4 * n) = w; } } }
	v_pk_fma_f32 v[84:85], v[56:57], v[120:121], v[124:125]
	v_mov_b32_dpp v78, v32 row_shr:1 row_mask:0xf bank_mask:0xf
	v_mov_b32_dpp v79, v33 row_shr:1 row_mask:0xf bank_mask:0xf
	v_pk_fma_f32 v[84:85], v[116:117], v[70:71], v[84:85]
	v_mov_b32_dpp v66, v52 row_shr:1 row_mask:0xf bank_mask:0xf
	v_pk_fma_f32 v[78:79], v[112:113], v[78:79], v[84:85]
	v_mov_b32_dpp v67, v53 row_shr:1 row_mask:0xf bank_mask:0xf
	v_exp_f32_e32 v84, v78
	v_exp_f32_e32 v85, v79
	v_pk_fma_f32 v[86:87], v[60:61], v[104:105], v[108:109]
	v_pk_add_f32 v[84:85], v[84:85], 1.0 op_sel_hi:[1,0]
	v_rcp_f32_e32 v84, v84
	v_rcp_f32_e32 v85, v85
	v_mov_b32_dpp v74, v40 row_shr:1 row_mask:0xf bank_mask:0xf
	v_mov_b32_dpp v75, v41 row_shr:1 row_mask:0xf bank_mask:0xf
	v_pk_fma_f32 v[86:87], v[100:101], v[66:67], v[86:87]
	v_pk_mul_f32 v[78:79], v[78:79], v[84:85]
	v_pk_fma_f32 v[74:75], v[96:97], v[74:75], v[86:87]
	v_mov_b32_dpp v72, v46 row_shr:1 row_mask:0xf bank_mask:0xf
	v_mov_b32_dpp v73, v47 row_shr:1 row_mask:0xf bank_mask:0xf
	v_pk_mul_f32 v[74:75], v[74:75], v[78:79]
	v_pk_fma_f32 v[78:79], v[58:59], v[122:123], v[126:127]
	v_mov_b32_dpp v80, v34 row_shr:1 row_mask:0xf bank_mask:0xf
	v_mov_b32_dpp v81, v35 row_shr:1 row_mask:0xf bank_mask:0xf
	v_pk_fma_f32 v[78:79], v[118:119], v[72:73], v[78:79]
	v_mov_b32_dpp v68, v54 row_shr:1 row_mask:0xf bank_mask:0xf
	v_pk_fma_f32 v[78:79], v[114:115], v[80:81], v[78:79]
	v_mov_b32_dpp v69, v55 row_shr:1 row_mask:0xf bank_mask:0xf
	v_exp_f32_e32 v80, v78
	v_exp_f32_e32 v81, v79
	v_pk_fma_f32 v[84:85], v[62:63], v[106:107], v[110:111]
	v_pk_add_f32 v[80:81], v[80:81], 1.0 op_sel_hi:[1,0]
	v_rcp_f32_e32 v80, v80
	v_rcp_f32_e32 v81, v81
	v_mov_b32_dpp v76, v42 row_shr:1 row_mask:0xf bank_mask:0xf
	v_mov_b32_dpp v77, v43 row_shr:1 row_mask:0xf bank_mask:0xf
	v_pk_fma_f32 v[84:85], v[102:103], v[68:69], v[84:85]
	v_pk_mul_f32 v[78:79], v[78:79], v[80:81]
	v_pk_fma_f32 v[76:77], v[98:99], v[76:77], v[84:85]
	v_cvt_pk_bf16_f32 v74, v74, v75
	v_pk_mul_f32 v[76:77], v[76:77], v[78:79]
	v_pk_fma_f32 v[44:45], v[44:45], v[120:121], v[124:125]
	v_cvt_pk_bf16_f32 v75, v76, v77
	v_pk_fma_f32 v[76:77], v[36:37], v[120:121], v[124:125]
	v_mov_b32_e32 v90, v246
	v_mov_b32_e32 v91, v247
	v_mov_b32_e32 v92, v74
	v_mov_b32_e32 v93, v75
	global_store_dwordx4 v[202:203], v[90:93], off
	v_pk_fma_f32 v[76:77], v[56:57], v[116:117], v[76:77]
	v_pk_fma_f32 v[52:53], v[52:53], v[104:105], v[108:109]
	v_pk_fma_f32 v[70:71], v[112:113], v[70:71], v[76:77]
	s_nop 0
	v_exp_f32_e32 v74, v70
	v_exp_f32_e32 v75, v71
	s_nop 0
	v_pk_add_f32 v[74:75], v[74:75], 1.0 op_sel_hi:[1,0]
	v_rcp_f32_e32 v74, v74
	v_rcp_f32_e32 v75, v75
	v_pk_fma_f32 v[76:77], v[48:49], v[104:105], v[108:109]
	v_pk_mul_f32 v[70:71], v[70:71], v[74:75]
	v_pk_fma_f32 v[76:77], v[60:61], v[100:101], v[76:77]
	v_pk_fma_f32 v[74:75], v[50:51], v[106:107], v[110:111]
	v_pk_fma_f32 v[66:67], v[96:97], v[66:67], v[76:77]
	v_pk_fma_f32 v[74:75], v[62:63], v[102:103], v[74:75]
	v_pk_mul_f32 v[66:67], v[66:67], v[70:71]
	v_pk_fma_f32 v[70:71], v[38:39], v[122:123], v[126:127]
	v_pk_fma_f32 v[68:69], v[98:99], v[68:69], v[74:75]
	v_pk_fma_f32 v[70:71], v[58:59], v[118:119], v[70:71]
	v_cvt_pk_bf16_f32 v66, v66, v67
	v_pk_fma_f32 v[70:71], v[114:115], v[72:73], v[70:71]
	s_nop 0
	v_exp_f32_e32 v72, v70
	v_exp_f32_e32 v73, v71
	s_nop 0
	v_pk_add_f32 v[72:73], v[72:73], 1.0 op_sel_hi:[1,0]
	v_rcp_f32_e32 v72, v72
	v_rcp_f32_e32 v73, v73
	s_nop 0
	v_pk_mul_f32 v[70:71], v[70:71], v[72:73]
	s_nop 0
	v_pk_mul_f32 v[68:69], v[68:69], v[70:71]
	s_nop 0
	v_cvt_pk_bf16_f32 v67, v68, v69
	v_pk_fma_f32 v[68:69], v[32:33], v[120:121], v[124:125]
	v_mov_b32_e32 v134, v248
	v_mov_b32_e32 v135, v249
	v_mov_b32_e32 v136, v66
	v_mov_b32_e32 v137, v67
	global_store_dwordx4 v[196:197], v[134:137], off
	v_pk_fma_f32 v[68:69], v[36:37], v[116:117], v[68:69]
	v_pk_fma_f32 v[32:33], v[32:33], v[116:117], v[44:45]
	v_pk_fma_f32 v[56:57], v[56:57], v[112:113], v[68:69]
	v_pk_fma_f32 v[32:33], v[36:37], v[112:113], v[32:33]
	v_exp_f32_e32 v66, v56
	v_exp_f32_e32 v67, v57
	s_nop 0
	v_pk_add_f32 v[66:67], v[66:67], 1.0 op_sel_hi:[1,0]
	v_rcp_f32_e32 v66, v66
	v_rcp_f32_e32 v67, v67
	v_pk_fma_f32 v[68:69], v[40:41], v[104:105], v[108:109]
	v_exp_f32_e32 v44, v32
	v_pk_fma_f32 v[68:69], v[48:49], v[100:101], v[68:69]
	v_pk_mul_f32 v[56:57], v[56:57], v[66:67]
	v_pk_fma_f32 v[60:61], v[60:61], v[96:97], v[68:69]
	v_pk_fma_f32 v[36:37], v[46:47], v[122:123], v[126:127]
	v_pk_mul_f32 v[56:57], v[60:61], v[56:57]
	v_pk_fma_f32 v[60:61], v[34:35], v[122:123], v[126:127]
	v_pk_fma_f32 v[34:35], v[34:35], v[118:119], v[36:37]
	v_pk_fma_f32 v[60:61], v[38:39], v[118:119], v[60:61]
	v_pk_fma_f32 v[34:35], v[38:39], v[114:115], v[34:35]
	v_pk_fma_f32 v[58:59], v[58:59], v[114:115], v[60:61]
	v_exp_f32_e32 v60, v58
	v_exp_f32_e32 v45, v33
	v_exp_f32_e32 v36, v34
	v_exp_f32_e32 v37, v35
	v_exp_f32_e32 v61, v59
	v_cvt_pk_bf16_f32 v56, v56, v57
	v_pk_add_f32 v[44:45], v[44:45], 1.0 op_sel_hi:[1,0]
	v_pk_add_f32 v[36:37], v[36:37], 1.0 op_sel_hi:[1,0]
	v_pk_add_f32 v[60:61], v[60:61], 1.0 op_sel_hi:[1,0]
	v_rcp_f32_e32 v44, v44
	v_rcp_f32_e32 v45, v45
	v_rcp_f32_e32 v36, v36
	v_rcp_f32_e32 v37, v37
	v_rcp_f32_e32 v60, v60
	v_rcp_f32_e32 v61, v61
	v_pk_fma_f32 v[46:47], v[54:55], v[106:107], v[110:111]
	v_pk_fma_f32 v[66:67], v[42:43], v[106:107], v[110:111]
	v_pk_fma_f32 v[40:41], v[40:41], v[100:101], v[52:53]
	v_pk_fma_f32 v[38:39], v[42:43], v[102:103], v[46:47]
	v_pk_fma_f32 v[66:67], v[50:51], v[102:103], v[66:67]
	v_pk_fma_f32 v[40:41], v[48:49], v[96:97], v[40:41]
	v_pk_mul_f32 v[32:33], v[32:33], v[44:45]
	v_pk_fma_f32 v[38:39], v[50:51], v[98:99], v[38:39]
	v_pk_mul_f32 v[34:35], v[34:35], v[36:37]
	v_pk_fma_f32 v[62:63], v[62:63], v[98:99], v[66:67]
	v_pk_mul_f32 v[58:59], v[58:59], v[60:61]
	v_pk_mul_f32 v[32:33], v[40:41], v[32:33]
	v_pk_mul_f32 v[34:35], v[38:39], v[34:35]
	v_pk_mul_f32 v[58:59], v[62:63], v[58:59]
	v_cvt_pk_bf16_f32 v32, v32, v33
	v_cvt_pk_bf16_f32 v33, v34, v35
	v_cvt_pk_bf16_f32 v57, v58, v59
	v_mov_b32_e32 v158, v250
	v_mov_b32_e32 v159, v251
	v_mov_b32_e32 v160, v32
	v_mov_b32_e32 v161, v33
	global_store_dwordx4 v[140:141], v[158:161], off
	v_mov_b32_e32 v65, 0
	v_mov_b32_e32 v66, 0
	v_mov_b32_e32 v67, 0
	v_mov_b32_e32 v40, 0
	v_mov_b32_e32 v41, 0
	v_mov_b32_e32 v42, 0
	v_mov_b32_e32 v43, 0
	v_mov_b32_e32 v32, 0
	v_mov_b32_e32 v33, 0
	v_mov_b32_e32 v34, 0
	v_mov_b32_e32 v35, 0
	v_mov_b32_e32 v36, 0
	v_mov_b32_e32 v37, 0
	v_mov_b32_e32 v38, 0
	v_mov_b32_e32 v39, 0
	v_mov_b32_e32 v162, v253
	v_mov_b32_e32 v163, v254
	v_mov_b32_e32 v164, v56
	v_mov_b32_e32 v165, v57
	global_store_dwordx4 v[152:153], v[162:165], off
	s_and_saveexec_b64 s[34:35], s[22:23]
	s_cbranch_execz .LBB0_1936
	ds_read_b128 v[36:39], v236 offset:2064
	ds_read_b128 v[40:43], v236 offset:2576
	ds_read_b128 v[32:35], v236 offset:3088
	ds_read_b128 v[64:67], v236 offset:3600
	s_branch .LBB0_1936
